# projection GEMM tile prologues (K=384/512, 5 instances in the head-group loop): the 16 loads of K-tiles 1 and 2 hoisted above the K-tile-0 wait/ds_write block, waits made counted (23..16); plus counte
# speedup vs baseline: 1.0092x; 1.0034x over previous
; #define G_LOAD(S, kt_) do { G_LD1(S##a0, S##b0, 0, kt_); G_LD1(S##a1, S##b1, 1, kt_); G_LD1(S##a2, S##b2, 2, kt_); G_LD1(S##a3, S##b3, 3, kt_); } while (0)
; #define G_STORE(S, buf_) do { G_ST1(S##a0, S##b0, 0, buf_); G_ST1(S##a1, S##b1, 1, buf_); G_ST1(S##a2, S##b2, 2, buf_); G_ST1(S##a3, S##b3, 3, buf_); } while (0)
; template <class AL, class BL>
; DI void gemm_core(AL al, BL bl, int m0, int n0, int K, char* smem, f32x16 (&acc)[2][2]) {
;     ...
;   const int srow = tid >> 3, sch = tid & 7;
;     ...
;   G_LOAD(x, 0);
;   G_STORE(x, 0);
;   G_LOAD(x, 1);
;   G_LOAD(y, (nk > 2) ? 2 : 1);
;   __syncthreads();
;   for (int kt = 0; kt < nk; kt += 2) {
;     G_TILE(0, x, true, (kt + 3 < nk), kt + 3);
.LBB0_550:
	s_cmp_ge_i32 s73, s13
	s_mov_b64 s[0:1], -1
	s_cbranch_scc0 .LBB0_564
	s_cmp_ge_i32 s73, s26
	s_cbranch_scc0 .LBB0_561
	s_cmp_ge_i32 s73, s2
	s_cbranch_scc0 .LBB0_558
	s_cmp_ge_i32 s73, s27
	s_cbranch_scc0 .LBB0_555
	s_add_i32 s0, s55, s73
	s_add_i32 s1, s0, 0xfffffbc0
	s_mul_hi_u32 s0, s1, 0xf0f0f0f1
	v_mov_b32_e32 v34, v202
	s_lshr_b32 s0, s0, 8
	s_mul_i32 s30, s0, 0x110
	v_ashrrev_i32_e32 v35, 3, v34
	v_lshl_add_u32 v2, s0, 7, v35
	s_sub_i32 s1, s1, s30
	v_ashrrev_i32_e32 v3, 31, v2
	v_lshlrev_b64 v[2:3], 9, v[2:3]
	v_lshlrev_b32_e32 v0, 4, v34
	v_lshl_add_u32 v6, s1, 7, v35
	v_lshl_add_u64 v[2:3], s[96:97], 0, v[2:3]
	v_and_b32_e32 v0, 0x70, v0
	v_ashrrev_i32_e32 v7, 31, v6
	v_readlane_b32 s30, v226, 19
	s_waitcnt vmcnt(4)
	v_lshl_add_u64 v[146:147], v[2:3], 0, v[0:1]
	v_lshlrev_b64 v[6:7], 9, v[6:7]
	v_readlane_b32 s31, v226, 20
	v_add_co_u32_e32 v10, vcc, s33, v146
	s_nop 0
	v_lshl_add_u64 v[6:7], s[30:31], 0, v[6:7]
	s_waitcnt vmcnt(3)
	v_lshl_add_u64 v[148:149], v[6:7], 0, v[0:1]
	v_addc_co_u32_e32 v11, vcc, 0, v147, vcc
	v_add_co_u32_e32 v14, vcc, s33, v148
	global_load_dwordx4 v[2:5], v[146:147], off
	global_load_dwordx4 v[6:9], v[148:149], off
	v_addc_co_u32_e32 v15, vcc, 0, v149, vcc
	v_add_co_u32_e32 v18, vcc, s80, v146
	global_load_dwordx4 v[10:13], v[10:11], off
	s_nop 0
	v_addc_co_u32_e32 v19, vcc, 0, v147, vcc
	v_add_co_u32_e32 v22, vcc, s80, v148
	global_load_dwordx4 v[14:17], v[14:15], off
	s_nop 0
	v_addc_co_u32_e32 v23, vcc, 0, v149, vcc
	v_add_co_u32_e32 v26, vcc, s81, v146
	global_load_dwordx4 v[18:21], v[18:19], off
	s_nop 0
	v_addc_co_u32_e32 v27, vcc, 0, v147, vcc
	global_load_dwordx4 v[22:25], v[22:23], off
	v_add_co_u32_e32 v30, vcc, s81, v148
	global_load_dwordx4 v[26:29], v[26:27], off
	s_nop 0
	v_addc_co_u32_e32 v31, vcc, 0, v149, vcc
	global_load_dwordx4 v[30:33], v[30:31], off
	v_mad_u64_u32 v[130:131], s[30:31], v35, s82, v[0:1]
	v_lshl_add_u64 v[138:139], v[146:147], 0, s[18:19]
	v_lshl_add_u64 v[144:145], v[148:149], 0, s[18:19]
	v_lshl_add_u64 v[136:137], v[146:147], 0, s[88:89]
	v_lshl_add_u64 v[142:143], v[148:149], 0, s[88:89]
	v_lshl_add_u64 v[134:135], v[146:147], 0, s[90:91]
	v_lshl_add_u64 v[140:141], v[148:149], 0, s[90:91]
	v_add_u32_e32 v0, 0x9000, v130
	global_load_dwordx4 v[122:125], v[146:147], off offset:128
	global_load_dwordx4 v[126:129], v[148:149], off offset:128
	global_load_dwordx4 v[114:117], v[138:139], off offset:128
	global_load_dwordx4 v[118:121], v[144:145], off offset:128
	global_load_dwordx4 v[106:109], v[136:137], off offset:128
	global_load_dwordx4 v[110:113], v[142:143], off offset:128
	global_load_dwordx4 v[98:101], v[134:135], off offset:128
	global_load_dwordx4 v[102:105], v[140:141], off offset:128
	global_load_dwordx4 v[90:93], v[146:147], off offset:256
	global_load_dwordx4 v[94:97], v[148:149], off offset:256
	global_load_dwordx4 v[82:85], v[138:139], off offset:256
	global_load_dwordx4 v[86:89], v[144:145], off offset:256
	global_load_dwordx4 v[74:77], v[136:137], off offset:256
	global_load_dwordx4 v[78:81], v[142:143], off offset:256
	global_load_dwordx4 v[66:69], v[134:135], off offset:256
	global_load_dwordx4 v[70:73], v[140:141], off offset:256
	s_waitcnt vmcnt(23)
	ds_write_b128 v130, v[2:5]
	s_waitcnt vmcnt(22)
	ds_write_b128 v130, v[6:9] offset:36864
	s_waitcnt vmcnt(21)
	ds_write_b128 v130, v[10:13] offset:4608
	s_waitcnt vmcnt(20)
	ds_write_b128 v130, v[14:17] offset:41472
	s_waitcnt vmcnt(19)
	ds_write_b128 v130, v[18:21] offset:9216
	s_waitcnt vmcnt(18)
	ds_write_b128 v130, v[22:25] offset:46080
	s_waitcnt vmcnt(17)
	ds_write_b128 v130, v[26:29] offset:13824
	s_waitcnt vmcnt(16)
	ds_write_b128 v130, v[30:33] offset:50688
	v_lshrrev_b32_e32 v2, 1, v34
	v_and_b32_e32 v3, 31, v34
	v_and_or_b32 v3, v2, s83, v3
	v_and_b32_e32 v2, 16, v2
	v_mad_u64_u32 v[132:133], s[30:31], v3, s82, v[2:3]
	v_and_b32_e32 v3, 0x5f, v34
	v_mul_u32_u24_e32 v3, 0x48, v3
	s_waitcnt lgkmcnt(0)
	s_barrier
	v_lshl_add_u32 v131, v3, 1, v2
	ds_read_b128 v[2:5], v132 offset:4608
	ds_read_b128 v[6:9], v131 offset:41472
	ds_read_b128 v[10:13], v132
	ds_read_b128 v[150:153], v132 offset:32
	ds_read_b128 v[154:157], v132 offset:4640
	ds_read_b128 v[14:17], v131 offset:36864
	ds_read_b128 v[158:161], v131 offset:36896
	ds_read_b128 v[162:165], v131 offset:41504
	s_waitcnt lgkmcnt(2)
	v_mfma_f32_32x32x16_bf16 v[50:65], v[10:13], v[14:17], 0
	s_waitcnt vmcnt(15)
	ds_write_b128 v130, v[122:125] offset:18432
	s_waitcnt vmcnt(14)
	ds_write_b128 v130, v[126:129] offset:55296
	global_load_dwordx4 v[122:125], v[146:147], off offset:384
	global_load_dwordx4 v[126:129], v[148:149], off offset:384
	v_mfma_f32_32x32x16_bf16 v[34:49], v[10:13], v[6:9], 0
	v_mfma_f32_32x32x16_bf16 v[18:33], v[2:5], v[14:17], 0
	v_mfma_f32_32x32x16_bf16 v[2:17], v[2:5], v[6:9], 0
	s_waitcnt lgkmcnt(3)
	v_mfma_f32_32x32x16_bf16 v[50:65], v[150:153], v[158:161], v[50:65]
	s_waitcnt lgkmcnt(2)
	v_mfma_f32_32x32x16_bf16 v[34:49], v[150:153], v[162:165], v[34:49]
	global_load_dwordx4 v[146:149], v[138:139], off offset:384
	global_load_dwordx4 v[150:153], v[144:145], off offset:384
	v_mfma_f32_32x32x16_bf16 v[18:33], v[154:157], v[158:161], v[18:33]
	ds_read_b128 v[158:161], v132 offset:64
	ds_read_b128 v[166:169], v132 offset:4672
	ds_read_b128 v[170:173], v131 offset:36928
	ds_read_b128 v[174:177], v131 offset:41536
	s_waitcnt vmcnt(17)
	ds_write_b128 v130, v[114:117] offset:23040
	s_waitcnt vmcnt(16)
	ds_write_b128 v130, v[118:121] offset:59904
	v_mfma_f32_32x32x16_bf16 v[2:17], v[154:157], v[162:165], v[2:17]
	global_load_dwordx4 v[114:117], v[136:137], off offset:384
	global_load_dwordx4 v[118:121], v[142:143], off offset:384
	s_waitcnt lgkmcnt(3)
	v_mfma_f32_32x32x16_bf16 v[50:65], v[158:161], v[170:173], v[50:65]
	s_waitcnt lgkmcnt(2)
	v_mfma_f32_32x32x16_bf16 v[34:49], v[158:161], v[174:177], v[34:49]
	ds_read_b128 v[136:139], v132 offset:96
	ds_read_b128 v[142:145], v132 offset:4704
	ds_read_b128 v[154:157], v131 offset:36960
	ds_read_b128 v[158:161], v131 offset:41568
	s_waitcnt vmcnt(17)
	ds_write_b128 v130, v[106:109] offset:27648
	s_waitcnt vmcnt(16)
	ds_write_b128 v130, v[110:113] offset:64512
	v_mfma_f32_32x32x16_bf16 v[18:33], v[166:169], v[170:173], v[18:33]
	v_mfma_f32_32x32x16_bf16 v[2:17], v[166:169], v[174:177], v[2:17]
	global_load_dwordx4 v[106:109], v[134:135], off offset:384
	global_load_dwordx4 v[110:113], v[140:141], off offset:384
	s_waitcnt lgkmcnt(3)
	v_mfma_f32_32x32x16_bf16 v[50:65], v[136:139], v[154:157], v[50:65]
	s_waitcnt vmcnt(17)
	ds_write_b128 v130, v[98:101] offset:32256
	s_waitcnt vmcnt(16)
	ds_write_b128 v0, v[102:105] offset:32256
	s_waitcnt lgkmcnt(4)
	v_mfma_f32_32x32x16_bf16 v[34:49], v[136:139], v[158:161], v[34:49]
	v_mfma_f32_32x32x16_bf16 v[18:33], v[142:145], v[154:157], v[18:33]
	v_mfma_f32_32x32x16_bf16 v[2:17], v[142:145], v[158:161], v[2:17]
	s_waitcnt lgkmcnt(0)
	s_barrier
; #define G_LOAD(S, kt_) do { G_LD1(S##a0, S##b0, 0, kt_); G_LD1(S##a1, S##b1, 1, kt_); G_LD1(S##a2, S##b2, 2, kt_); G_LD1(S##a3, S##b3, 3, kt_); } while (0)
; #define G_STORE(S, buf_) do { G_ST1(S##a0, S##b0, 0, buf_); G_ST1(S##a1, S##b1, 1, buf_); G_ST1(S##a2, S##b2, 2, buf_); G_ST1(S##a3, S##b3, 3, buf_); } while (0)
; template <class AL, class BL>
; DI void gemm_core(AL al, BL bl, int m0, int n0, int K, char* smem, f32x16 (&acc)[2][2]) {
;     ...
;   G_LOAD(x, 0);
;   G_STORE(x, 0);
;   G_LOAD(x, 1);
;   G_LOAD(y, (nk > 2) ? 2 : 1);
;   __syncthreads();
;   for (int kt = 0; kt < nk; kt += 2) {
;     G_TILE(0, x, true, (kt + 3 < nk), kt + 3);
;     __syncthreads();
;     G_TILE(1, y, (kt + 2 < nk), (kt + 4 < nk), kt + 4);
;     __syncthreads();
	ds_read_b128 v[98:101], v132 offset:18432
	ds_read_b128 v[102:105], v131 offset:55296
	ds_read_b128 v[134:137], v131 offset:59904
	s_waitcnt lgkmcnt(1)
	v_mfma_f32_32x32x16_bf16 v[50:65], v[98:101], v[102:105], v[50:65]
	s_waitcnt lgkmcnt(0)
	v_mfma_f32_32x32x16_bf16 v[34:49], v[98:101], v[134:137], v[34:49]
	ds_read_b128 v[98:101], v132 offset:23040
	s_waitcnt lgkmcnt(0)
	v_mfma_f32_32x32x16_bf16 v[18:33], v[98:101], v[102:105], v[18:33]
	ds_read_b128 v[102:105], v132 offset:18464
	ds_read_b128 v[138:141], v131 offset:55328
	ds_read_b128 v[142:145], v131 offset:59936
	ds_read_b128 v[154:157], v132 offset:23072
	s_waitcnt vmcnt(15)
	ds_write_b128 v130, v[90:93]
	s_waitcnt vmcnt(14)
	ds_write_b128 v130, v[94:97] offset:36864
	v_mfma_f32_32x32x16_bf16 v[2:17], v[98:101], v[134:137], v[2:17]
	s_waitcnt lgkmcnt(4)
	v_mfma_f32_32x32x16_bf16 v[50:65], v[102:105], v[138:141], v[50:65]
	s_waitcnt lgkmcnt(3)
	v_mfma_f32_32x32x16_bf16 v[34:49], v[102:105], v[142:145], v[34:49]
	ds_read_b128 v[90:93], v132 offset:18496
	ds_read_b128 v[94:97], v132 offset:23104
	ds_read_b128 v[98:101], v131 offset:55360
	ds_read_b128 v[102:105], v131 offset:59968
	s_waitcnt vmcnt(13)
	ds_write_b128 v130, v[82:85] offset:4608
	s_waitcnt vmcnt(12)
	ds_write_b128 v130, v[86:89] offset:41472
	s_waitcnt lgkmcnt(8)
	v_mfma_f32_32x32x16_bf16 v[18:33], v[154:157], v[138:141], v[18:33]
	v_mfma_f32_32x32x16_bf16 v[2:17], v[154:157], v[142:145], v[2:17]
	s_waitcnt lgkmcnt(3)
	v_mfma_f32_32x32x16_bf16 v[50:65], v[90:93], v[98:101], v[50:65]
	s_waitcnt lgkmcnt(2)
	v_mfma_f32_32x32x16_bf16 v[34:49], v[90:93], v[102:105], v[34:49]
	v_mfma_f32_32x32x16_bf16 v[18:33], v[94:97], v[98:101], v[18:33]
	ds_read_b128 v[82:85], v132 offset:18528
	ds_read_b128 v[86:89], v132 offset:23136
	ds_read_b128 v[90:93], v131 offset:55392
	ds_read_b128 v[98:101], v131 offset:60000
	s_waitcnt vmcnt(11)
	ds_write_b128 v130, v[74:77] offset:9216
	s_waitcnt vmcnt(10)
	ds_write_b128 v130, v[78:81] offset:46080
	v_mfma_f32_32x32x16_bf16 v[2:17], v[94:97], v[102:105], v[2:17]
	s_waitcnt lgkmcnt(3)
	v_mfma_f32_32x32x16_bf16 v[50:65], v[82:85], v[90:93], v[50:65]
	s_waitcnt vmcnt(9)
	ds_write_b128 v130, v[66:69] offset:13824
	s_waitcnt vmcnt(8)
	ds_write_b128 v130, v[70:73] offset:50688
	s_waitcnt lgkmcnt(4)
	v_mfma_f32_32x32x16_bf16 v[34:49], v[82:85], v[98:101], v[34:49]
	v_mfma_f32_32x32x16_bf16 v[18:33], v[86:89], v[90:93], v[18:33]
	v_mfma_f32_32x32x16_bf16 v[2:17], v[86:89], v[98:101], v[2:17]
	s_waitcnt lgkmcnt(0)
	s_barrier
	ds_read_b128 v[66:69], v132
	ds_read_b128 v[70:73], v131 offset:36864
	ds_read_b128 v[74:77], v131 offset:41472
	s_waitcnt lgkmcnt(1)
	v_mfma_f32_32x32x16_bf16 v[50:65], v[66:69], v[70:73], v[50:65]
	s_waitcnt lgkmcnt(0)
	v_mfma_f32_32x32x16_bf16 v[34:49], v[66:69], v[74:77], v[34:49]
	ds_read_b128 v[66:69], v132 offset:4608
	s_waitcnt lgkmcnt(0)
	v_mfma_f32_32x32x16_bf16 v[18:33], v[66:69], v[70:73], v[18:33]
	ds_read_b128 v[70:73], v132 offset:32
	ds_read_b128 v[78:81], v131 offset:36896
	ds_read_b128 v[82:85], v131 offset:41504
	ds_read_b128 v[86:89], v132 offset:4640
	s_waitcnt vmcnt(7)
	ds_write_b128 v130, v[122:125] offset:18432
	s_waitcnt vmcnt(6)
	ds_write_b128 v130, v[126:129] offset:55296
	v_mfma_f32_32x32x16_bf16 v[2:17], v[66:69], v[74:77], v[2:17]
	s_waitcnt lgkmcnt(4)
	v_mfma_f32_32x32x16_bf16 v[50:65], v[70:73], v[78:81], v[50:65]
	s_waitcnt lgkmcnt(3)
	v_mfma_f32_32x32x16_bf16 v[34:49], v[70:73], v[82:85], v[34:49]
	s_waitcnt lgkmcnt(2)
	v_mfma_f32_32x32x16_bf16 v[18:33], v[86:89], v[78:81], v[18:33]
	ds_read_b128 v[66:69], v132 offset:64
	ds_read_b128 v[70:73], v132 offset:4672
	ds_read_b128 v[74:77], v131 offset:36928
	ds_read_b128 v[78:81], v131 offset:41536
	s_waitcnt vmcnt(5)
	ds_write_b128 v130, v[146:149] offset:23040
	s_waitcnt vmcnt(4)
	ds_write_b128 v130, v[150:153] offset:59904
	v_mfma_f32_32x32x16_bf16 v[2:17], v[86:89], v[82:85], v[2:17]
	s_waitcnt lgkmcnt(3)
	v_mfma_f32_32x32x16_bf16 v[50:65], v[66:69], v[74:77], v[50:65]
	s_waitcnt lgkmcnt(2)
	v_mfma_f32_32x32x16_bf16 v[34:49], v[66:69], v[78:81], v[34:49]
	v_mfma_f32_32x32x16_bf16 v[18:33], v[70:73], v[74:77], v[18:33]
	ds_read_b128 v[66:69], v132 offset:96
	ds_read_b128 v[74:77], v132 offset:4704
	ds_read_b128 v[82:85], v131 offset:36960
	ds_read_b128 v[86:89], v131 offset:41568
	s_waitcnt vmcnt(3)
	ds_write_b128 v130, v[114:117] offset:27648
	s_waitcnt vmcnt(2)
	ds_write_b128 v130, v[118:121] offset:64512
	v_mfma_f32_32x32x16_bf16 v[2:17], v[70:73], v[78:81], v[2:17]
	s_waitcnt lgkmcnt(3)
	v_mfma_f32_32x32x16_bf16 v[50:65], v[66:69], v[82:85], v[50:65]
	s_waitcnt vmcnt(1)
	ds_write_b128 v130, v[106:109] offset:32256
	s_waitcnt vmcnt(0)
	ds_write_b128 v0, v[110:113] offset:32256
	s_waitcnt lgkmcnt(4)
	v_mfma_f32_32x32x16_bf16 v[34:49], v[66:69], v[86:89], v[34:49]
	v_mfma_f32_32x32x16_bf16 v[18:33], v[74:77], v[82:85], v[18:33]
	v_mfma_f32_32x32x16_bf16 v[2:17], v[74:77], v[86:89], v[2:17]
	s_waitcnt lgkmcnt(0)
	s_barrier
; DI u16 f2bf(float x) { return (u16)(pack2(x, 0.f) & 0xffffu); }
; DI int opaque_tid() { int t = threadIdx.x; asm volatile("" : "+v"(t)); return t; }
; DI int crow(int i, int h) { return (i & 3) + 8 * (i >> 2) + 4 * h; }
; template <class F>
; DI void epi_bf16_vtile(const f32x16 (&acc)[2][2], u16* dst0  , char* smem, F f) {
;   const int tid = opaque_tid(), lane = tid & 63, w = tid >> 6, wm = w >> 1, wn = w & 1, h = lane >> 5;
;   u16* T = (u16*)smem;
; #pragma unroll
;   for (int mt = 0; mt < 2; mt++)
; #pragma unroll
;     for (int nt = 0; nt < 2; nt++)
; #pragma unroll
;       for (int i = 0; i < 16; i++) {
;         const int ml = wm * 64 + mt * 32 + crow(i, h), nl = wn * 64 + nt * 32 + (lane & 31);
;         T[ml * 136 + nl] = f2bf(f(acc[mt][nt][i]));
;       }
;   __syncthreads();
; #pragma unroll
;   for (int j = 0; j < 8; j++) {
;     const int idx = tid + 256 * j, row = idx >> 4, ch = idx & 15;
;     *(uint4*)(dst0 + ((long)(ch >> 3) * 128 + row) * 64 + (ch & 7) * 8) = *(const uint4*)(T + row * 136 + ch * 8);
;   }
;   __syncthreads();
; }
	ds_read_b128 v[66:69], v132 offset:18432
	ds_read_b128 v[70:73], v131 offset:55296
	ds_read_b128 v[74:77], v131 offset:59904
	s_waitcnt lgkmcnt(1)
	v_mfma_f32_32x32x16_bf16 v[50:65], v[66:69], v[70:73], v[50:65]
	s_waitcnt lgkmcnt(0)
	v_mfma_f32_32x32x16_bf16 v[34:49], v[66:69], v[74:77], v[34:49]
	ds_read_b128 v[66:69], v132 offset:23040
	s_waitcnt lgkmcnt(0)
	v_mfma_f32_32x32x16_bf16 v[18:33], v[66:69], v[70:73], v[18:33]
	ds_read_b128 v[70:73], v132 offset:18464
	ds_read_b128 v[78:81], v131 offset:55328
	ds_read_b128 v[82:85], v131 offset:59936
	ds_read_b128 v[86:89], v132 offset:23072
	v_mfma_f32_32x32x16_bf16 v[2:17], v[66:69], v[74:77], v[2:17]
	s_waitcnt lgkmcnt(2)
	v_mfma_f32_32x32x16_bf16 v[50:65], v[70:73], v[78:81], v[50:65]
	s_waitcnt lgkmcnt(1)
	v_mfma_f32_32x32x16_bf16 v[34:49], v[70:73], v[82:85], v[34:49]
	s_waitcnt lgkmcnt(0)
	v_mfma_f32_32x32x16_bf16 v[18:33], v[86:89], v[78:81], v[18:33]
	ds_read_b128 v[66:69], v132 offset:18496
	ds_read_b128 v[70:73], v132 offset:23104
	ds_read_b128 v[74:77], v131 offset:55360
	ds_read_b128 v[78:81], v131 offset:59968
	v_mfma_f32_32x32x16_bf16 v[2:17], v[86:89], v[82:85], v[2:17]
	s_waitcnt lgkmcnt(1)
	v_mfma_f32_32x32x16_bf16 v[50:65], v[66:69], v[74:77], v[50:65]
	s_waitcnt lgkmcnt(0)
	v_mfma_f32_32x32x16_bf16 v[34:49], v[66:69], v[78:81], v[34:49]
	v_mfma_f32_32x32x16_bf16 v[18:33], v[70:73], v[74:77], v[18:33]
	ds_read_b128 v[66:69], v132 offset:18528
	ds_read_b128 v[74:77], v132 offset:23136
	ds_read_b128 v[82:85], v131 offset:55392
	ds_read_b128 v[86:89], v131 offset:60000
	v_mfma_f32_32x32x16_bf16 v[2:17], v[70:73], v[78:81], v[2:17]
	s_waitcnt lgkmcnt(1)
	v_mfma_f32_32x32x16_bf16 v[50:65], v[66:69], v[82:85], v[50:65]
	s_waitcnt lgkmcnt(0)
	v_mfma_f32_32x32x16_bf16 v[34:49], v[66:69], v[86:89], v[34:49]
	v_mfma_f32_32x32x16_bf16 v[18:33], v[74:77], v[82:85], v[18:33]
	v_mfma_f32_32x32x16_bf16 v[2:17], v[74:77], v[86:89], v[2:17]
	s_mul_hi_u32 s30, s0, 0x220
	s_mulk_i32 s0, 0x220
	s_lshl_b32 s1, s1, 1
	v_mov_b32_e32 v66, v202
	s_barrier
	s_add_u32 s0, s0, s1
	s_addc_u32 s1, s30, 0
	v_lshrrev_b32_e32 v0, 1, v66
	v_and_b32_e32 v0, 0xfffffc0, v0
	v_lshrrev_b32_e32 v67, 3, v66
	s_lshl_b64 s[0:1], s[0:1], 14
	v_and_or_b32 v0, v67, 4, v0
	s_add_u32 s0, s60, s0
	v_and_b32_e32 v67, 0x5f, v66
	v_mul_lo_u32 v0, v0, s51
	v_lshl_add_u32 v0, v67, 1, v0
	v_cvt_pk_bf16_f32 v2, v2, s0
	v_cvt_pk_bf16_f32 v50, v50, s0
	v_cvt_pk_bf16_f32 v34, v34, s0
	v_cvt_pk_bf16_f32 v18, v18, s0
	ds_write_b16 v0, v2 offset:8768
	v_cvt_pk_bf16_f32 v2, v3, s0
	ds_write_b16 v0, v50
	v_cvt_pk_bf16_f32 v50, v51, s0
	ds_write_b16 v0, v34 offset:64
	v_cvt_pk_bf16_f32 v34, v35, s0
	ds_write_b16 v0, v18 offset:8704
	v_cvt_pk_bf16_f32 v18, v19, s0
	ds_write_b16 v0, v2 offset:9040
	v_cvt_pk_bf16_f32 v2, v4, s0
	ds_write_b16 v0, v50 offset:272
	v_cvt_pk_bf16_f32 v50, v52, s0
	ds_write_b16 v0, v34 offset:336
	v_cvt_pk_bf16_f32 v34, v36, s0
	ds_write_b16 v0, v18 offset:8976
	v_cvt_pk_bf16_f32 v18, v20, s0
	ds_write_b16 v0, v2 offset:9312
	v_cvt_pk_bf16_f32 v2, v5, s0
	ds_write_b16 v0, v50 offset:544
	v_cvt_pk_bf16_f32 v50, v53, s0
	ds_write_b16 v0, v34 offset:608
	v_cvt_pk_bf16_f32 v34, v37, s0
	ds_write_b16 v0, v18 offset:9248
	v_cvt_pk_bf16_f32 v18, v21, s0
	ds_write_b16 v0, v2 offset:9584
	v_cvt_pk_bf16_f32 v2, v6, s0
	ds_write_b16 v0, v50 offset:816
	v_cvt_pk_bf16_f32 v50, v54, s0
	ds_write_b16 v0, v34 offset:880
	v_cvt_pk_bf16_f32 v34, v38, s0
	ds_write_b16 v0, v18 offset:9520
	v_cvt_pk_bf16_f32 v18, v22, s0
	ds_write_b16 v0, v2 offset:10944
	v_cvt_pk_bf16_f32 v2, v7, s0
	ds_write_b16 v0, v50 offset:2176
	v_cvt_pk_bf16_f32 v50, v55, s0
	ds_write_b16 v0, v34 offset:2240
	v_cvt_pk_bf16_f32 v34, v39, s0
	ds_write_b16 v0, v18 offset:10880
	v_cvt_pk_bf16_f32 v18, v23, s0
	ds_write_b16 v0, v2 offset:11216
	v_cvt_pk_bf16_f32 v2, v8, s0
	ds_write_b16 v0, v50 offset:2448
	v_cvt_pk_bf16_f32 v50, v56, s0
	ds_write_b16 v0, v34 offset:2512
	v_cvt_pk_bf16_f32 v34, v40, s0
	ds_write_b16 v0, v18 offset:11152
	v_cvt_pk_bf16_f32 v18, v24, s0
	ds_write_b16 v0, v2 offset:11488
	v_cvt_pk_bf16_f32 v2, v9, s0
	ds_write_b16 v0, v50 offset:2720
	v_cvt_pk_bf16_f32 v50, v57, s0
	ds_write_b16 v0, v34 offset:2784
	v_cvt_pk_bf16_f32 v34, v41, s0
	ds_write_b16 v0, v18 offset:11424
	v_cvt_pk_bf16_f32 v18, v25, s0
	ds_write_b16 v0, v2 offset:11760
	v_cvt_pk_bf16_f32 v2, v10, s0
	ds_write_b16 v0, v50 offset:2992
	v_cvt_pk_bf16_f32 v50, v58, s0
	ds_write_b16 v0, v34 offset:3056
	v_cvt_pk_bf16_f32 v34, v42, s0
	ds_write_b16 v0, v18 offset:11696
	v_cvt_pk_bf16_f32 v18, v26, s0
	ds_write_b16 v0, v2 offset:13120
	v_cvt_pk_bf16_f32 v2, v11, s0
	ds_write_b16 v0, v50 offset:4352
	v_cvt_pk_bf16_f32 v50, v59, s0
	ds_write_b16 v0, v34 offset:4416
	v_cvt_pk_bf16_f32 v34, v43, s0
	ds_write_b16 v0, v18 offset:13056
	v_cvt_pk_bf16_f32 v18, v27, s0
	ds_write_b16 v0, v2 offset:13392
	v_cvt_pk_bf16_f32 v2, v12, s0
	ds_write_b16 v0, v50 offset:4624
	v_cvt_pk_bf16_f32 v50, v60, s0
	ds_write_b16 v0, v34 offset:4688
	v_cvt_pk_bf16_f32 v34, v44, s0
	ds_write_b16 v0, v18 offset:13328
	v_cvt_pk_bf16_f32 v18, v28, s0
	ds_write_b16 v0, v2 offset:13664
	v_cvt_pk_bf16_f32 v2, v13, s0
	ds_write_b16 v0, v50 offset:4896
	v_cvt_pk_bf16_f32 v50, v61, s0
	ds_write_b16 v0, v34 offset:4960
	v_cvt_pk_bf16_f32 v34, v45, s0
	ds_write_b16 v0, v18 offset:13600
	v_cvt_pk_bf16_f32 v18, v29, s0
	ds_write_b16 v0, v2 offset:13936
	v_cvt_pk_bf16_f32 v2, v14, s0
	ds_write_b16 v0, v50 offset:5168
	v_cvt_pk_bf16_f32 v50, v62, s0
	ds_write_b16 v0, v34 offset:5232
	v_cvt_pk_bf16_f32 v34, v46, s0
	ds_write_b16 v0, v18 offset:13872
	v_cvt_pk_bf16_f32 v18, v30, s0
	ds_write_b16 v0, v2 offset:15296
	v_cvt_pk_bf16_f32 v2, v15, s0
	ds_write_b16 v0, v50 offset:6528
	v_cvt_pk_bf16_f32 v50, v63, s0
	ds_write_b16 v0, v34 offset:6592
	v_cvt_pk_bf16_f32 v34, v47, s0
	ds_write_b16 v0, v18 offset:15232
	v_cvt_pk_bf16_f32 v18, v31, s0
	ds_write_b16 v0, v2 offset:15568
	v_cvt_pk_bf16_f32 v2, v16, s0
	ds_write_b16 v0, v50 offset:6800
	v_cvt_pk_bf16_f32 v50, v64, s0
	ds_write_b16 v0, v34 offset:6864
	v_cvt_pk_bf16_f32 v34, v48, s0
	ds_write_b16 v0, v18 offset:15504
	v_cvt_pk_bf16_f32 v18, v32, s0
	ds_write_b16 v0, v2 offset:15840
	v_cvt_pk_bf16_f32 v2, v17, s0
	ds_write_b16 v0, v50 offset:7072
	v_cvt_pk_bf16_f32 v50, v65, s0
	ds_write_b16 v0, v34 offset:7136
	v_cvt_pk_bf16_f32 v34, v49, s0
	ds_write_b16 v0, v18 offset:15776
	v_cvt_pk_bf16_f32 v18, v33, s0
	ds_write_b16 v0, v2 offset:16112
	v_lshlrev_b32_e32 v2, 4, v66
	s_addc_u32 s1, s61, s1
	ds_write_b16 v0, v50 offset:7344
	ds_write_b16 v0, v34 offset:7408
	ds_write_b16 v0, v18 offset:16048
	v_and_b32_e32 v10, 0xf0, v2
	v_and_b32_e32 v0, 0x80, v2
	v_and_b32_e32 v2, 0x70, v2
	v_mov_b32_e32 v3, v1
	v_lshl_add_u64 v[12:13], s[0:1], 0, v[2:3]
	v_ashrrev_i32_e32 v2, 4, v66
	v_ashrrev_i32_e32 v3, 31, v2
	v_mad_u64_u32 v[4:5], s[0:1], v2, s51, v[10:11]
	v_lshl_add_u64 v[2:3], v[0:1], 0, v[2:3]
	v_lshlrev_b64 v[2:3], 7, v[2:3]
	s_waitcnt lgkmcnt(0)
	s_barrier
; #define G_LOAD(S, kt_) do { G_LD1(S##a0, S##b0, 0, kt_); G_LD1(S##a1, S##b1, 1, kt_); G_LD1(S##a2, S##b2, 2, kt_); G_LD1(S##a3, S##b3, 3, kt_); } while (0)
; #define G_STORE(S, buf_) do { G_ST1(S##a0, S##b0, 0, buf_); G_ST1(S##a1, S##b1, 1, buf_); G_ST1(S##a2, S##b2, 2, buf_); G_ST1(S##a3, S##b3, 3, buf_); } while (0)
; template <class AL, class BL>
; DI void gemm_core(AL al, BL bl, int m0, int n0, int K, char* smem, f32x16 (&acc)[2][2]) {
;     ...
;   const int srow = tid >> 3, sch = tid & 7;
;     ...
;   G_LOAD(x, 0);
;   G_STORE(x, 0);
;   G_LOAD(x, 1);
;   G_LOAD(y, (nk > 2) ? 2 : 1);
;   __syncthreads();
; __global__ void __launch_bounds__(256, 2) fwd_megakernel(Params p) {
;     ...
;         } else if (t < e4) {
;           const int tt = t - e3, tm = tt % (NSKV / 128), tn = tt / (NSKV / 128);
;           gemm_core([=](int m, int k) { return lats + (long)m * 256 + k; },
;                     [=](int n, int k) { return wukTg + (long)n * 256 + k; }, tm * 128, tn * 128, 256, smem, acc);
;           epi_bf16_tile(acc, tm * 128, tn * 128, kns + ((long)tn * NSKV + tm * 128) * 128, 128, smem, [=](int m, int n, float v) { return v; });
	v_lshl_add_u64 v[14:15], v[12:13], 0, v[2:3]
	ds_read_b128 v[2:5], v4
	v_add_u32_e32 v6, 0x100, v66
	v_ashrrev_i32_e32 v16, 4, v6
	v_mad_u64_u32 v[6:7], s[0:1], v16, s51, v[10:11]
	ds_read_b128 v[6:9], v6
	v_ashrrev_i32_e32 v17, 31, v16
	s_waitcnt lgkmcnt(1)
	global_store_dwordx4 v[14:15], v[2:5], off
	s_nop 1
	v_lshl_add_u64 v[2:3], v[16:17], 0, v[0:1]
	v_lshlrev_b64 v[2:3], 7, v[2:3]
	v_lshl_add_u64 v[2:3], v[12:13], 0, v[2:3]
	s_waitcnt lgkmcnt(0)
	global_store_dwordx4 v[2:3], v[6:9], off
	v_add_u32_e32 v2, 0x200, v66
	v_ashrrev_i32_e32 v2, 4, v2
	v_ashrrev_i32_e32 v3, 31, v2
	v_mad_u64_u32 v[4:5], s[0:1], v2, s51, v[10:11]
	v_lshl_add_u64 v[2:3], v[2:3], 0, v[0:1]
	v_lshlrev_b64 v[2:3], 7, v[2:3]
	v_lshl_add_u64 v[14:15], v[12:13], 0, v[2:3]
	ds_read_b128 v[2:5], v4
	v_add_u32_e32 v6, 0x300, v66
	v_ashrrev_i32_e32 v16, 4, v6
	v_mad_u64_u32 v[6:7], s[0:1], v16, s51, v[10:11]
	ds_read_b128 v[6:9], v6
	v_ashrrev_i32_e32 v17, 31, v16
	s_waitcnt lgkmcnt(1)
	global_store_dwordx4 v[14:15], v[2:5], off
	s_nop 1
	v_lshl_add_u64 v[2:3], v[16:17], 0, v[0:1]
	v_lshlrev_b64 v[2:3], 7, v[2:3]
	v_lshl_add_u64 v[2:3], v[12:13], 0, v[2:3]
	s_waitcnt lgkmcnt(0)
	global_store_dwordx4 v[2:3], v[6:9], off
	v_add_u32_e32 v2, 0x400, v66
	v_ashrrev_i32_e32 v2, 4, v2
	v_ashrrev_i32_e32 v3, 31, v2
	v_mad_u64_u32 v[4:5], s[0:1], v2, s51, v[10:11]
	v_lshl_add_u64 v[2:3], v[2:3], 0, v[0:1]
	v_lshlrev_b64 v[2:3], 7, v[2:3]
	v_lshl_add_u64 v[14:15], v[12:13], 0, v[2:3]
	ds_read_b128 v[2:5], v4
	v_add_u32_e32 v6, 0x500, v66
	v_ashrrev_i32_e32 v16, 4, v6
	v_mad_u64_u32 v[6:7], s[0:1], v16, s51, v[10:11]
	ds_read_b128 v[6:9], v6
	v_ashrrev_i32_e32 v17, 31, v16
	s_waitcnt lgkmcnt(1)
	global_store_dwordx4 v[14:15], v[2:5], off
	s_nop 1
	v_lshl_add_u64 v[2:3], v[16:17], 0, v[0:1]
	v_lshlrev_b64 v[2:3], 7, v[2:3]
	v_lshl_add_u64 v[2:3], v[12:13], 0, v[2:3]
	s_waitcnt lgkmcnt(0)
	global_store_dwordx4 v[2:3], v[6:9], off
	v_add_u32_e32 v2, 0x600, v66
	v_ashrrev_i32_e32 v2, 4, v2
	v_ashrrev_i32_e32 v3, 31, v2
	v_mad_u64_u32 v[4:5], s[0:1], v2, s51, v[10:11]
	v_lshl_add_u64 v[2:3], v[2:3], 0, v[0:1]
	v_lshlrev_b64 v[2:3], 7, v[2:3]
	v_lshl_add_u64 v[14:15], v[12:13], 0, v[2:3]
	ds_read_b128 v[2:5], v4
	v_add_u32_e32 v6, 0x700, v66
	v_ashrrev_i32_e32 v16, 4, v6
	v_mad_u64_u32 v[6:7], s[0:1], v16, s51, v[10:11]
	ds_read_b128 v[6:9], v6
	v_ashrrev_i32_e32 v17, 31, v16
	s_waitcnt lgkmcnt(1)
	global_store_dwordx4 v[14:15], v[2:5], off
	s_mov_b64 s[0:1], 0
	s_nop 0
	v_lshl_add_u64 v[2:3], v[16:17], 0, v[0:1]
	v_lshlrev_b64 v[2:3], 7, v[2:3]
	v_lshl_add_u64 v[2:3], v[12:13], 0, v[2:3]
	s_waitcnt lgkmcnt(0)
	global_store_dwordx4 v[2:3], v[6:9], off
	s_barrier
.LBB0_555:
	s_andn2_b64 vcc, exec, s[0:1]
	s_cbranch_vccnz .LBB0_557
	s_add_i32 s1, s55, s73
	s_mul_hi_i32 s0, s1, 0x78787879
	s_lshr_b32 s30, s0, 31
	s_ashr_i32 s0, s0, 7
	s_add_i32 s0, s0, s30
	s_mul_i32 s30, s0, 0x110
	s_sub_i32 s1, s1, s30
	v_mov_b32_e32 v34, v202
	s_lshl_b32 s1, s1, 7
	v_readlane_b32 s30, v226, 19
	v_ashrrev_i32_e32 v35, 3, v34
	v_add_u32_e32 v2, s1, v35
	v_ashrrev_i32_e32 v3, 31, v2
	v_lshlrev_b64 v[2:3], 9, v[2:3]
	v_readlane_b32 s31, v226, 20
	v_lshlrev_b32_e32 v0, 4, v34
	v_lshl_add_u32 v6, s0, 7, v35
	v_lshl_add_u64 v[2:3], s[30:31], 0, v[2:3]
	v_and_b32_e32 v0, 0x70, v0
	v_ashrrev_i32_e32 v7, 31, v6
	s_waitcnt vmcnt(4)
	v_lshl_add_u64 v[146:147], v[2:3], 0, v[0:1]
	v_lshlrev_b64 v[6:7], 9, v[6:7]
	v_lshl_add_u64 v[6:7], s[14:15], 0, v[6:7]
	v_add_co_u32_e32 v10, vcc, s33, v146
	s_waitcnt vmcnt(3)
	v_lshl_add_u64 v[148:149], v[6:7], 0, v[0:1]
	v_addc_co_u32_e32 v11, vcc, 0, v147, vcc
	v_add_co_u32_e32 v14, vcc, s33, v148
	global_load_dwordx4 v[2:5], v[146:147], off
	global_load_dwordx4 v[6:9], v[148:149], off
	v_addc_co_u32_e32 v15, vcc, 0, v149, vcc
	v_add_co_u32_e32 v18, vcc, s80, v146
	global_load_dwordx4 v[10:13], v[10:11], off
	s_nop 0
	v_addc_co_u32_e32 v19, vcc, 0, v147, vcc
	v_add_co_u32_e32 v22, vcc, s80, v148
	global_load_dwordx4 v[14:17], v[14:15], off
	s_nop 0
	v_addc_co_u32_e32 v23, vcc, 0, v149, vcc
	v_add_co_u32_e32 v26, vcc, s81, v146
	global_load_dwordx4 v[18:21], v[18:19], off
	s_nop 0
	v_addc_co_u32_e32 v27, vcc, 0, v147, vcc
	global_load_dwordx4 v[22:25], v[22:23], off
	v_add_co_u32_e32 v30, vcc, s81, v148
	global_load_dwordx4 v[26:29], v[26:27], off
	s_nop 0
	v_addc_co_u32_e32 v31, vcc, 0, v149, vcc
	global_load_dwordx4 v[30:33], v[30:31], off
	v_mad_u64_u32 v[130:131], s[30:31], v35, s82, v[0:1]
	v_lshl_add_u64 v[140:141], v[146:147], 0, s[18:19]
	v_lshl_add_u64 v[144:145], v[148:149], 0, s[18:19]
	v_lshl_add_u64 v[136:137], v[146:147], 0, s[88:89]
	v_lshl_add_u64 v[142:143], v[148:149], 0, s[88:89]
	v_lshl_add_u64 v[134:135], v[146:147], 0, s[90:91]
	v_lshl_add_u64 v[138:139], v[148:149], 0, s[90:91]
	v_add_u32_e32 v0, 0x9000, v130
	global_load_dwordx4 v[122:125], v[146:147], off offset:128
	global_load_dwordx4 v[126:129], v[148:149], off offset:128
	global_load_dwordx4 v[114:117], v[140:141], off offset:128
	global_load_dwordx4 v[118:121], v[144:145], off offset:128
	global_load_dwordx4 v[106:109], v[136:137], off offset:128
	global_load_dwordx4 v[110:113], v[142:143], off offset:128
	global_load_dwordx4 v[98:101], v[134:135], off offset:128
	global_load_dwordx4 v[102:105], v[138:139], off offset:128
	global_load_dwordx4 v[90:93], v[146:147], off offset:256
	global_load_dwordx4 v[94:97], v[148:149], off offset:256
	global_load_dwordx4 v[82:85], v[140:141], off offset:256
	global_load_dwordx4 v[86:89], v[144:145], off offset:256
	global_load_dwordx4 v[74:77], v[136:137], off offset:256
	global_load_dwordx4 v[78:81], v[142:143], off offset:256
	global_load_dwordx4 v[66:69], v[134:135], off offset:256
	global_load_dwordx4 v[70:73], v[138:139], off offset:256
	s_waitcnt vmcnt(23)
	ds_write_b128 v130, v[2:5]
	s_waitcnt vmcnt(22)
	ds_write_b128 v130, v[6:9] offset:36864
	s_waitcnt vmcnt(21)
	ds_write_b128 v130, v[10:13] offset:4608
	s_waitcnt vmcnt(20)
	ds_write_b128 v130, v[14:17] offset:41472
	s_waitcnt vmcnt(19)
	ds_write_b128 v130, v[18:21] offset:9216
	s_waitcnt vmcnt(18)
	ds_write_b128 v130, v[22:25] offset:46080
	s_waitcnt vmcnt(17)
	ds_write_b128 v130, v[26:29] offset:13824
	s_waitcnt vmcnt(16)
	ds_write_b128 v130, v[30:33] offset:50688
	v_lshrrev_b32_e32 v2, 1, v34
	v_and_b32_e32 v3, 31, v34
	v_and_or_b32 v3, v2, s83, v3
	v_and_b32_e32 v2, 16, v2
	v_mad_u64_u32 v[132:133], s[30:31], v3, s82, v[2:3]
	v_and_b32_e32 v3, 0x5f, v34
	v_mul_u32_u24_e32 v3, 0x48, v3
	s_waitcnt lgkmcnt(0)
	s_barrier
; #define G_LOAD(S, kt_) do { G_LD1(S##a0, S##b0, 0, kt_); G_LD1(S##a1, S##b1, 1, kt_); G_LD1(S##a2, S##b2, 2, kt_); G_LD1(S##a3, S##b3, 3, kt_); } while (0)
; #define G_STORE(S, buf_) do { G_ST1(S##a0, S##b0, 0, buf_); G_ST1(S##a1, S##b1, 1, buf_); G_ST1(S##a2, S##b2, 2, buf_); G_ST1(S##a3, S##b3, 3, buf_); } while (0)
; template <class AL, class BL>
; DI void gemm_core(AL al, BL bl, int m0, int n0, int K, char* smem, f32x16 (&acc)[2][2]) {
;     ...
;   G_LOAD(x, 0);
;   G_STORE(x, 0);
;   G_LOAD(x, 1);
;   G_LOAD(y, (nk > 2) ? 2 : 1);
;   __syncthreads();
;   for (int kt = 0; kt < nk; kt += 2) {
;     G_TILE(0, x, true, (kt + 3 < nk), kt + 3);
;     __syncthreads();
;     G_TILE(1, y, (kt + 2 < nk), (kt + 4 < nk), kt + 4);
;     __syncthreads();
	v_lshl_add_u32 v131, v3, 1, v2
	ds_read_b128 v[2:5], v132 offset:4608
	ds_read_b128 v[6:9], v131 offset:41472
	ds_read_b128 v[10:13], v132
	ds_read_b128 v[150:153], v132 offset:32
	ds_read_b128 v[154:157], v132 offset:4640
	ds_read_b128 v[14:17], v131 offset:36864
	ds_read_b128 v[158:161], v131 offset:36896
	ds_read_b128 v[162:165], v131 offset:41504
	s_waitcnt lgkmcnt(2)
	v_mfma_f32_32x32x16_bf16 v[50:65], v[10:13], v[14:17], 0
	s_waitcnt vmcnt(15)
	ds_write_b128 v130, v[122:125] offset:18432
	s_waitcnt vmcnt(14)
	ds_write_b128 v130, v[126:129] offset:55296
	global_load_dwordx4 v[122:125], v[146:147], off offset:384
	global_load_dwordx4 v[126:129], v[148:149], off offset:384
	v_mfma_f32_32x32x16_bf16 v[34:49], v[10:13], v[6:9], 0
	v_mfma_f32_32x32x16_bf16 v[18:33], v[2:5], v[14:17], 0
	v_mfma_f32_32x32x16_bf16 v[2:17], v[2:5], v[6:9], 0
	s_waitcnt lgkmcnt(3)
	v_mfma_f32_32x32x16_bf16 v[50:65], v[150:153], v[158:161], v[50:65]
	s_waitcnt lgkmcnt(2)
	v_mfma_f32_32x32x16_bf16 v[34:49], v[150:153], v[162:165], v[34:49]
	global_load_dwordx4 v[146:149], v[140:141], off offset:384
	global_load_dwordx4 v[150:153], v[144:145], off offset:384
	v_mfma_f32_32x32x16_bf16 v[18:33], v[154:157], v[158:161], v[18:33]
	ds_read_b128 v[158:161], v132 offset:64
	ds_read_b128 v[166:169], v132 offset:4672
	ds_read_b128 v[170:173], v131 offset:36928
	ds_read_b128 v[174:177], v131 offset:41536
	s_waitcnt vmcnt(17)
	ds_write_b128 v130, v[114:117] offset:23040
	s_waitcnt vmcnt(16)
	ds_write_b128 v130, v[118:121] offset:59904
	v_mfma_f32_32x32x16_bf16 v[2:17], v[154:157], v[162:165], v[2:17]
	global_load_dwordx4 v[114:117], v[136:137], off offset:384
	global_load_dwordx4 v[118:121], v[142:143], off offset:384
	s_waitcnt lgkmcnt(3)
	v_mfma_f32_32x32x16_bf16 v[50:65], v[158:161], v[170:173], v[50:65]
	s_waitcnt lgkmcnt(2)
	v_mfma_f32_32x32x16_bf16 v[34:49], v[158:161], v[174:177], v[34:49]
	ds_read_b128 v[140:143], v132 offset:96
	ds_read_b128 v[154:157], v132 offset:4704
	ds_read_b128 v[158:161], v131 offset:36960
	ds_read_b128 v[162:165], v131 offset:41568
	s_waitcnt vmcnt(17)
	ds_write_b128 v130, v[106:109] offset:27648
	s_waitcnt vmcnt(16)
	ds_write_b128 v130, v[110:113] offset:64512
	v_mfma_f32_32x32x16_bf16 v[18:33], v[166:169], v[170:173], v[18:33]
	v_mfma_f32_32x32x16_bf16 v[2:17], v[166:169], v[174:177], v[2:17]
	global_load_dwordx4 v[106:109], v[134:135], off offset:384
	global_load_dwordx4 v[110:113], v[138:139], off offset:384
	s_waitcnt lgkmcnt(3)
	v_mfma_f32_32x32x16_bf16 v[50:65], v[140:143], v[158:161], v[50:65]
	s_waitcnt vmcnt(17)
	ds_write_b128 v130, v[98:101] offset:32256
	s_waitcnt vmcnt(16)
	ds_write_b128 v0, v[102:105] offset:32256
	s_waitcnt lgkmcnt(4)
	v_mfma_f32_32x32x16_bf16 v[34:49], v[140:143], v[162:165], v[34:49]
	v_mfma_f32_32x32x16_bf16 v[18:33], v[154:157], v[158:161], v[18:33]
	v_mfma_f32_32x32x16_bf16 v[2:17], v[154:157], v[162:165], v[2:17]
	s_waitcnt lgkmcnt(0)
	s_barrier
	ds_read_b128 v[98:101], v132 offset:18432
	ds_read_b128 v[102:105], v131 offset:55296
	ds_read_b128 v[134:137], v131 offset:59904
	s_waitcnt lgkmcnt(1)
	v_mfma_f32_32x32x16_bf16 v[50:65], v[98:101], v[102:105], v[50:65]
	s_waitcnt lgkmcnt(0)
	v_mfma_f32_32x32x16_bf16 v[34:49], v[98:101], v[134:137], v[34:49]
	ds_read_b128 v[98:101], v132 offset:23040
	s_waitcnt lgkmcnt(0)
	v_mfma_f32_32x32x16_bf16 v[18:33], v[98:101], v[102:105], v[18:33]
	ds_read_b128 v[102:105], v132 offset:18464
	ds_read_b128 v[138:141], v131 offset:55328
	ds_read_b128 v[142:145], v131 offset:59936
	ds_read_b128 v[154:157], v132 offset:23072
	s_waitcnt vmcnt(15)
	ds_write_b128 v130, v[90:93]
	s_waitcnt vmcnt(14)
	ds_write_b128 v130, v[94:97] offset:36864
	v_mfma_f32_32x32x16_bf16 v[2:17], v[98:101], v[134:137], v[2:17]
	s_waitcnt lgkmcnt(4)
	v_mfma_f32_32x32x16_bf16 v[50:65], v[102:105], v[138:141], v[50:65]
	s_waitcnt lgkmcnt(3)
	v_mfma_f32_32x32x16_bf16 v[34:49], v[102:105], v[142:145], v[34:49]
	ds_read_b128 v[90:93], v132 offset:18496
	ds_read_b128 v[94:97], v132 offset:23104
	ds_read_b128 v[98:101], v131 offset:55360
	ds_read_b128 v[102:105], v131 offset:59968
	s_waitcnt vmcnt(13)
	ds_write_b128 v130, v[82:85] offset:4608
	s_waitcnt vmcnt(12)
	ds_write_b128 v130, v[86:89] offset:41472
	s_waitcnt lgkmcnt(8)
	v_mfma_f32_32x32x16_bf16 v[18:33], v[154:157], v[138:141], v[18:33]
	v_mfma_f32_32x32x16_bf16 v[2:17], v[154:157], v[142:145], v[2:17]
	s_waitcnt lgkmcnt(3)
	v_mfma_f32_32x32x16_bf16 v[50:65], v[90:93], v[98:101], v[50:65]
	s_waitcnt lgkmcnt(2)
	v_mfma_f32_32x32x16_bf16 v[34:49], v[90:93], v[102:105], v[34:49]
	v_mfma_f32_32x32x16_bf16 v[18:33], v[94:97], v[98:101], v[18:33]
	ds_read_b128 v[82:85], v132 offset:18528
	ds_read_b128 v[86:89], v132 offset:23136
	ds_read_b128 v[90:93], v131 offset:55392
	ds_read_b128 v[98:101], v131 offset:60000
	s_waitcnt vmcnt(11)
	ds_write_b128 v130, v[74:77] offset:9216
	s_waitcnt vmcnt(10)
	ds_write_b128 v130, v[78:81] offset:46080
	v_mfma_f32_32x32x16_bf16 v[2:17], v[94:97], v[102:105], v[2:17]
	s_waitcnt lgkmcnt(3)
	v_mfma_f32_32x32x16_bf16 v[50:65], v[82:85], v[90:93], v[50:65]
	s_waitcnt vmcnt(9)
	ds_write_b128 v130, v[66:69] offset:13824
	s_waitcnt vmcnt(8)
	ds_write_b128 v130, v[70:73] offset:50688
	s_waitcnt lgkmcnt(4)
	v_mfma_f32_32x32x16_bf16 v[34:49], v[82:85], v[98:101], v[34:49]
	v_mfma_f32_32x32x16_bf16 v[18:33], v[86:89], v[90:93], v[18:33]
	v_mfma_f32_32x32x16_bf16 v[2:17], v[86:89], v[98:101], v[2:17]
	s_waitcnt lgkmcnt(0)
	s_barrier
; #define G_LOAD(S, kt_) do { G_LD1(S##a0, S##b0, 0, kt_); G_LD1(S##a1, S##b1, 1, kt_); G_LD1(S##a2, S##b2, 2, kt_); G_LD1(S##a3, S##b3, 3, kt_); } while (0)
; #define G_STORE(S, buf_) do { G_ST1(S##a0, S##b0, 0, buf_); G_ST1(S##a1, S##b1, 1, buf_); G_ST1(S##a2, S##b2, 2, buf_); G_ST1(S##a3, S##b3, 3, buf_); } while (0)
; template <class AL, class BL>
; DI void gemm_core(AL al, BL bl, int m0, int n0, int K, char* smem, f32x16 (&acc)[2][2]) {
;     ...
;   G_LOAD(x, 0);
;   G_STORE(x, 0);
;   G_LOAD(x, 1);
;   G_LOAD(y, (nk > 2) ? 2 : 1);
;   __syncthreads();
;   for (int kt = 0; kt < nk; kt += 2) {
;     G_TILE(0, x, true, (kt + 3 < nk), kt + 3);
;     __syncthreads();
;     G_TILE(1, y, (kt + 2 < nk), (kt + 4 < nk), kt + 4);
;     __syncthreads();
;   }
	ds_read_b128 v[66:69], v132
	ds_read_b128 v[70:73], v131 offset:36864
	ds_read_b128 v[74:77], v131 offset:41472
	s_waitcnt lgkmcnt(1)
	v_mfma_f32_32x32x16_bf16 v[50:65], v[66:69], v[70:73], v[50:65]
	s_waitcnt lgkmcnt(0)
	v_mfma_f32_32x32x16_bf16 v[34:49], v[66:69], v[74:77], v[34:49]
	ds_read_b128 v[66:69], v132 offset:4608
	s_waitcnt lgkmcnt(0)
	v_mfma_f32_32x32x16_bf16 v[18:33], v[66:69], v[70:73], v[18:33]
	ds_read_b128 v[70:73], v132 offset:32
	ds_read_b128 v[78:81], v131 offset:36896
	ds_read_b128 v[82:85], v131 offset:41504
	ds_read_b128 v[86:89], v132 offset:4640
	s_waitcnt vmcnt(7)
	ds_write_b128 v130, v[122:125] offset:18432
	s_waitcnt vmcnt(6)
	ds_write_b128 v130, v[126:129] offset:55296
	v_mfma_f32_32x32x16_bf16 v[2:17], v[66:69], v[74:77], v[2:17]
	s_waitcnt lgkmcnt(4)
	v_mfma_f32_32x32x16_bf16 v[50:65], v[70:73], v[78:81], v[50:65]
	s_waitcnt lgkmcnt(3)
	v_mfma_f32_32x32x16_bf16 v[34:49], v[70:73], v[82:85], v[34:49]
	s_waitcnt lgkmcnt(2)
	v_mfma_f32_32x32x16_bf16 v[18:33], v[86:89], v[78:81], v[18:33]
	ds_read_b128 v[66:69], v132 offset:64
	ds_read_b128 v[70:73], v132 offset:4672
	ds_read_b128 v[74:77], v131 offset:36928
	ds_read_b128 v[78:81], v131 offset:41536
	s_waitcnt vmcnt(5)
	ds_write_b128 v130, v[146:149] offset:23040
	s_waitcnt vmcnt(4)
	ds_write_b128 v130, v[150:153] offset:59904
	v_mfma_f32_32x32x16_bf16 v[2:17], v[86:89], v[82:85], v[2:17]
	s_waitcnt lgkmcnt(3)
	v_mfma_f32_32x32x16_bf16 v[50:65], v[66:69], v[74:77], v[50:65]
	s_waitcnt lgkmcnt(2)
	v_mfma_f32_32x32x16_bf16 v[34:49], v[66:69], v[78:81], v[34:49]
	v_mfma_f32_32x32x16_bf16 v[18:33], v[70:73], v[74:77], v[18:33]
	ds_read_b128 v[66:69], v132 offset:96
	ds_read_b128 v[74:77], v132 offset:4704
	ds_read_b128 v[82:85], v131 offset:36960
	ds_read_b128 v[86:89], v131 offset:41568
	s_waitcnt vmcnt(3)
	ds_write_b128 v130, v[114:117] offset:27648
	s_waitcnt vmcnt(2)
	ds_write_b128 v130, v[118:121] offset:64512
	v_mfma_f32_32x32x16_bf16 v[2:17], v[70:73], v[78:81], v[2:17]
	s_waitcnt lgkmcnt(3)
	v_mfma_f32_32x32x16_bf16 v[50:65], v[66:69], v[82:85], v[50:65]
	s_waitcnt vmcnt(1)
	ds_write_b128 v130, v[106:109] offset:32256
	s_waitcnt vmcnt(0)
	ds_write_b128 v0, v[110:113] offset:32256
	s_waitcnt lgkmcnt(4)
	v_mfma_f32_32x32x16_bf16 v[34:49], v[66:69], v[86:89], v[34:49]
	v_mfma_f32_32x32x16_bf16 v[18:33], v[74:77], v[82:85], v[18:33]
	v_mfma_f32_32x32x16_bf16 v[2:17], v[74:77], v[86:89], v[2:17]
	s_waitcnt lgkmcnt(0)
	s_barrier
	ds_read_b128 v[66:69], v132 offset:18432
	ds_read_b128 v[70:73], v131 offset:55296
	ds_read_b128 v[74:77], v131 offset:59904
	s_waitcnt lgkmcnt(1)
	v_mfma_f32_32x32x16_bf16 v[50:65], v[66:69], v[70:73], v[50:65]
	s_waitcnt lgkmcnt(0)
	v_mfma_f32_32x32x16_bf16 v[34:49], v[66:69], v[74:77], v[34:49]
	ds_read_b128 v[66:69], v132 offset:23040
	s_waitcnt lgkmcnt(0)
	v_mfma_f32_32x32x16_bf16 v[18:33], v[66:69], v[70:73], v[18:33]
	ds_read_b128 v[70:73], v132 offset:18464
	ds_read_b128 v[78:81], v131 offset:55328
	ds_read_b128 v[82:85], v131 offset:59936
	ds_read_b128 v[86:89], v132 offset:23072
	v_mfma_f32_32x32x16_bf16 v[2:17], v[66:69], v[74:77], v[2:17]
	s_waitcnt lgkmcnt(2)
	v_mfma_f32_32x32x16_bf16 v[50:65], v[70:73], v[78:81], v[50:65]
	s_waitcnt lgkmcnt(1)
	v_mfma_f32_32x32x16_bf16 v[34:49], v[70:73], v[82:85], v[34:49]
	s_waitcnt lgkmcnt(0)
	v_mfma_f32_32x32x16_bf16 v[18:33], v[86:89], v[78:81], v[18:33]
	ds_read_b128 v[66:69], v132 offset:18496
	ds_read_b128 v[70:73], v132 offset:23104
	ds_read_b128 v[74:77], v131 offset:55360
	ds_read_b128 v[78:81], v131 offset:59968
	v_mfma_f32_32x32x16_bf16 v[2:17], v[86:89], v[82:85], v[2:17]
	s_waitcnt lgkmcnt(1)
	v_mfma_f32_32x32x16_bf16 v[50:65], v[66:69], v[74:77], v[50:65]
	s_waitcnt lgkmcnt(0)
	v_mfma_f32_32x32x16_bf16 v[34:49], v[66:69], v[78:81], v[34:49]
	v_mfma_f32_32x32x16_bf16 v[18:33], v[70:73], v[74:77], v[18:33]
	ds_read_b128 v[66:69], v132 offset:18528
	ds_read_b128 v[74:77], v132 offset:23136
	ds_read_b128 v[82:85], v131 offset:55392
	ds_read_b128 v[86:89], v131 offset:60000
	v_mfma_f32_32x32x16_bf16 v[2:17], v[70:73], v[78:81], v[2:17]
	s_waitcnt lgkmcnt(1)
	v_mfma_f32_32x32x16_bf16 v[50:65], v[66:69], v[82:85], v[50:65]
	s_waitcnt lgkmcnt(0)
	v_mfma_f32_32x32x16_bf16 v[34:49], v[66:69], v[86:89], v[34:49]
	v_mfma_f32_32x32x16_bf16 v[18:33], v[74:77], v[82:85], v[18:33]
	v_mfma_f32_32x32x16_bf16 v[2:17], v[74:77], v[86:89], v[2:17]
	s_mul_hi_i32 s30, s0, 0x8800
	s_mul_i32 s0, s0, 0x8800
	s_ashr_i32 s31, s1, 31
	v_mov_b32_e32 v66, v202
	s_barrier
; DI u16 f2bf(float x) { return (u16)(pack2(x, 0.f) & 0xffffu); }
; DI int opaque_tid() { int t = threadIdx.x; asm volatile("" : "+v"(t)); return t; }
; DI int crow(int i, int h) { return (i & 3) + 8 * (i >> 2) + 4 * h; }
; template <class F>
; DI void epi_bf16_tile(const f32x16 (&acc)[2][2], int m0, int n0, u16* dst0, long ld, char* smem, F f) {
;   const int tid = opaque_tid(), lane = tid & 63, w = tid >> 6, wm = w >> 1, wn = w & 1, h = lane >> 5;
;   u16* T = (u16*)smem;
; #pragma unroll
;   for (int mt = 0; mt < 2; mt++)
; #pragma unroll
;     for (int nt = 0; nt < 2; nt++)
; #pragma unroll
;       for (int i = 0; i < 16; i++) {
;         const int ml = wm * 64 + mt * 32 + crow(i, h), nl = wn * 64 + nt * 32 + (lane & 31);
;         T[ml * 136 + nl] = f2bf(f(m0 + ml, n0 + nl, acc[mt][nt][i]));
;       }
;   __syncthreads();
; __global__ void __launch_bounds__(256, 2) fwd_megakernel(Params p) {
;     ...
;           epi_bf16_tile(acc, tm * 128, tn * 128, kns + ((long)tn * NSKV + tm * 128) * 128, 128, smem, [=](int m, int n, float v) { return v; });
	s_add_u32 s0, s0, s1
	s_addc_u32 s1, s30, s31
	v_lshrrev_b32_e32 v0, 1, v66
	v_and_b32_e32 v0, 0xfffffc0, v0
	v_lshrrev_b32_e32 v67, 3, v66
	s_lshl_b64 s[0:1], s[0:1], 8
	v_and_or_b32 v0, v67, 4, v0
	s_add_u32 s0, s58, s0
	v_and_b32_e32 v67, 0x5f, v66
	v_mul_lo_u32 v0, v0, s51
	v_cvt_pk_bf16_f32 v50, v50, s0
	v_lshl_add_u32 v0, v67, 1, v0
	v_cvt_pk_bf16_f32 v34, v34, s0
	v_cvt_pk_bf16_f32 v18, v18, s0
	v_cvt_pk_bf16_f32 v2, v2, s0
	ds_write_b16 v0, v50
	v_cvt_pk_bf16_f32 v50, v51, s0
	ds_write_b16 v0, v34 offset:64
	v_cvt_pk_bf16_f32 v34, v35, s0
	ds_write_b16 v0, v18 offset:8704
	v_cvt_pk_bf16_f32 v18, v19, s0
	ds_write_b16 v0, v2 offset:8768
	v_cvt_pk_bf16_f32 v2, v3, s0
	ds_write_b16 v0, v50 offset:272
	v_cvt_pk_bf16_f32 v50, v52, s0
	ds_write_b16 v0, v34 offset:336
	v_cvt_pk_bf16_f32 v34, v36, s0
	ds_write_b16 v0, v18 offset:8976
	v_cvt_pk_bf16_f32 v18, v20, s0
	ds_write_b16 v0, v2 offset:9040
	v_cvt_pk_bf16_f32 v2, v4, s0
	ds_write_b16 v0, v50 offset:544
	v_cvt_pk_bf16_f32 v50, v53, s0
	ds_write_b16 v0, v34 offset:608
	v_cvt_pk_bf16_f32 v34, v37, s0
	ds_write_b16 v0, v18 offset:9248
	v_cvt_pk_bf16_f32 v18, v21, s0
	ds_write_b16 v0, v2 offset:9312
	v_cvt_pk_bf16_f32 v2, v5, s0
	ds_write_b16 v0, v50 offset:816
	v_cvt_pk_bf16_f32 v50, v54, s0
	ds_write_b16 v0, v34 offset:880
	v_cvt_pk_bf16_f32 v34, v38, s0
	ds_write_b16 v0, v18 offset:9520
	v_cvt_pk_bf16_f32 v18, v22, s0
	ds_write_b16 v0, v2 offset:9584
	v_cvt_pk_bf16_f32 v2, v6, s0
	ds_write_b16 v0, v50 offset:2176
	v_cvt_pk_bf16_f32 v50, v55, s0
	ds_write_b16 v0, v34 offset:2240
	v_cvt_pk_bf16_f32 v34, v39, s0
	ds_write_b16 v0, v18 offset:10880
	v_cvt_pk_bf16_f32 v18, v23, s0
	ds_write_b16 v0, v2 offset:10944
	v_cvt_pk_bf16_f32 v2, v7, s0
	ds_write_b16 v0, v50 offset:2448
	v_cvt_pk_bf16_f32 v50, v56, s0
	ds_write_b16 v0, v34 offset:2512
	v_cvt_pk_bf16_f32 v34, v40, s0
	ds_write_b16 v0, v18 offset:11152
	v_cvt_pk_bf16_f32 v18, v24, s0
	ds_write_b16 v0, v2 offset:11216
	v_cvt_pk_bf16_f32 v2, v8, s0
	ds_write_b16 v0, v50 offset:2720
	v_cvt_pk_bf16_f32 v50, v57, s0
	ds_write_b16 v0, v34 offset:2784
	v_cvt_pk_bf16_f32 v34, v41, s0
	ds_write_b16 v0, v18 offset:11424
	v_cvt_pk_bf16_f32 v18, v25, s0
	ds_write_b16 v0, v2 offset:11488
	v_cvt_pk_bf16_f32 v2, v9, s0
	ds_write_b16 v0, v50 offset:2992
	v_cvt_pk_bf16_f32 v50, v58, s0
	ds_write_b16 v0, v34 offset:3056
	v_cvt_pk_bf16_f32 v34, v42, s0
	ds_write_b16 v0, v18 offset:11696
	v_cvt_pk_bf16_f32 v18, v26, s0
	ds_write_b16 v0, v2 offset:11760
	v_cvt_pk_bf16_f32 v2, v10, s0
	ds_write_b16 v0, v50 offset:4352
	v_cvt_pk_bf16_f32 v50, v59, s0
	ds_write_b16 v0, v34 offset:4416
	v_cvt_pk_bf16_f32 v34, v43, s0
	ds_write_b16 v0, v18 offset:13056
	v_cvt_pk_bf16_f32 v18, v27, s0
	ds_write_b16 v0, v2 offset:13120
	v_cvt_pk_bf16_f32 v2, v11, s0
	ds_write_b16 v0, v50 offset:4624
	v_cvt_pk_bf16_f32 v50, v60, s0
	ds_write_b16 v0, v34 offset:4688
	v_cvt_pk_bf16_f32 v34, v44, s0
	ds_write_b16 v0, v18 offset:13328
	v_cvt_pk_bf16_f32 v18, v28, s0
	ds_write_b16 v0, v2 offset:13392
	v_cvt_pk_bf16_f32 v2, v12, s0
	ds_write_b16 v0, v50 offset:4896
	v_cvt_pk_bf16_f32 v50, v61, s0
	ds_write_b16 v0, v34 offset:4960
	v_cvt_pk_bf16_f32 v34, v45, s0
	ds_write_b16 v0, v18 offset:13600
	v_cvt_pk_bf16_f32 v18, v29, s0
	ds_write_b16 v0, v2 offset:13664
	v_cvt_pk_bf16_f32 v2, v13, s0
	ds_write_b16 v0, v50 offset:5168
	v_cvt_pk_bf16_f32 v50, v62, s0
	ds_write_b16 v0, v34 offset:5232
	v_cvt_pk_bf16_f32 v34, v46, s0
	ds_write_b16 v0, v18 offset:13872
	v_cvt_pk_bf16_f32 v18, v30, s0
	ds_write_b16 v0, v2 offset:13936
	v_cvt_pk_bf16_f32 v2, v14, s0
	ds_write_b16 v0, v50 offset:6528
	v_cvt_pk_bf16_f32 v50, v63, s0
	ds_write_b16 v0, v34 offset:6592
	v_cvt_pk_bf16_f32 v34, v47, s0
	ds_write_b16 v0, v18 offset:15232
	v_cvt_pk_bf16_f32 v18, v31, s0
	ds_write_b16 v0, v2 offset:15296
	v_cvt_pk_bf16_f32 v2, v15, s0
	ds_write_b16 v0, v50 offset:6800
	v_cvt_pk_bf16_f32 v50, v64, s0
	ds_write_b16 v0, v34 offset:6864
	v_cvt_pk_bf16_f32 v34, v48, s0
	ds_write_b16 v0, v18 offset:15504
	v_cvt_pk_bf16_f32 v18, v32, s0
	ds_write_b16 v0, v2 offset:15568
	v_cvt_pk_bf16_f32 v2, v16, s0
	ds_write_b16 v0, v50 offset:7072
	v_cvt_pk_bf16_f32 v50, v65, s0
	ds_write_b16 v0, v34 offset:7136
	v_cvt_pk_bf16_f32 v34, v49, s0
	ds_write_b16 v0, v18 offset:15776
	v_cvt_pk_bf16_f32 v18, v33, s0
	ds_write_b16 v0, v2 offset:15840
	v_cvt_pk_bf16_f32 v2, v17, s0
	ds_write_b16 v0, v50 offset:7344
	ds_write_b16 v0, v34 offset:7408
	ds_write_b16 v0, v18 offset:16048
	ds_write_b16 v0, v2 offset:16112
	v_lshlrev_b32_e32 v0, 4, v66
	v_ashrrev_i32_e32 v2, 4, v66
	s_addc_u32 s1, s59, s1
	v_and_b32_e32 v0, 0xf0, v0
	v_ashrrev_i32_e32 v3, 31, v2
	v_lshl_add_u64 v[10:11], s[0:1], 0, v[0:1]
	v_mad_u64_u32 v[4:5], s[0:1], v2, s51, v[0:1]
	v_lshlrev_b64 v[2:3], 8, v[2:3]
	v_add_u32_e32 v6, 0x100, v66
	s_waitcnt lgkmcnt(0)
	s_barrier
; template <class F>
; DI void epi_bf16_tile(const f32x16 (&acc)[2][2], int m0, int n0, u16* dst0, long ld, char* smem, F f) {
;     ...
; #pragma unroll
;   for (int j = 0; j < 8; j++) {
;     const int idx = tid + 256 * j, row = idx >> 4, ch = idx & 15;
;     *(uint4*)(dst0 + (long)row * ld + ch * 8) = *(const uint4*)(T + row * 136 + ch * 8);
;   }
;   __syncthreads();
	v_lshl_add_u64 v[12:13], v[10:11], 0, v[2:3]
	ds_read_b128 v[2:5], v4
	v_ashrrev_i32_e32 v14, 4, v6
	v_mad_u64_u32 v[6:7], s[0:1], v14, s51, v[0:1]
	ds_read_b128 v[6:9], v6
	v_ashrrev_i32_e32 v15, 31, v14
	s_waitcnt lgkmcnt(1)
	global_store_dwordx4 v[12:13], v[2:5], off
	s_nop 1
	v_lshlrev_b64 v[2:3], 8, v[14:15]
	v_lshl_add_u64 v[2:3], v[10:11], 0, v[2:3]
	s_waitcnt lgkmcnt(0)
	global_store_dwordx4 v[2:3], v[6:9], off
	v_add_u32_e32 v2, 0x200, v66
	v_ashrrev_i32_e32 v2, 4, v2
	v_ashrrev_i32_e32 v3, 31, v2
	v_mad_u64_u32 v[4:5], s[0:1], v2, s51, v[0:1]
	v_lshlrev_b64 v[2:3], 8, v[2:3]
	v_add_u32_e32 v6, 0x300, v66
	v_lshl_add_u64 v[12:13], v[10:11], 0, v[2:3]
	ds_read_b128 v[2:5], v4
	v_ashrrev_i32_e32 v14, 4, v6
	v_mad_u64_u32 v[6:7], s[0:1], v14, s51, v[0:1]
	ds_read_b128 v[6:9], v6
	v_ashrrev_i32_e32 v15, 31, v14
	s_waitcnt lgkmcnt(1)
	global_store_dwordx4 v[12:13], v[2:5], off
	s_nop 1
	v_lshlrev_b64 v[2:3], 8, v[14:15]
	v_lshl_add_u64 v[2:3], v[10:11], 0, v[2:3]
	s_waitcnt lgkmcnt(0)
	global_store_dwordx4 v[2:3], v[6:9], off
	v_add_u32_e32 v2, 0x400, v66
	v_ashrrev_i32_e32 v2, 4, v2
	v_ashrrev_i32_e32 v3, 31, v2
	v_mad_u64_u32 v[4:5], s[0:1], v2, s51, v[0:1]
	v_lshlrev_b64 v[2:3], 8, v[2:3]
	v_add_u32_e32 v6, 0x500, v66
	v_lshl_add_u64 v[12:13], v[10:11], 0, v[2:3]
	ds_read_b128 v[2:5], v4
	v_ashrrev_i32_e32 v14, 4, v6
	v_mad_u64_u32 v[6:7], s[0:1], v14, s51, v[0:1]
	ds_read_b128 v[6:9], v6
	v_ashrrev_i32_e32 v15, 31, v14
	s_waitcnt lgkmcnt(1)
	global_store_dwordx4 v[12:13], v[2:5], off
	s_nop 1
	v_lshlrev_b64 v[2:3], 8, v[14:15]
	v_lshl_add_u64 v[2:3], v[10:11], 0, v[2:3]
	s_waitcnt lgkmcnt(0)
	global_store_dwordx4 v[2:3], v[6:9], off
	v_add_u32_e32 v2, 0x600, v66
	v_ashrrev_i32_e32 v2, 4, v2
	v_ashrrev_i32_e32 v3, 31, v2
	v_mad_u64_u32 v[4:5], s[0:1], v2, s51, v[0:1]
	v_lshlrev_b64 v[2:3], 8, v[2:3]
	v_add_u32_e32 v6, 0x700, v66
	v_lshl_add_u64 v[12:13], v[10:11], 0, v[2:3]
	ds_read_b128 v[2:5], v4
	v_ashrrev_i32_e32 v14, 4, v6
	v_mad_u64_u32 v[6:7], s[0:1], v14, s51, v[0:1]
	ds_read_b128 v[6:9], v6
	v_ashrrev_i32_e32 v15, 31, v14
	s_waitcnt lgkmcnt(1)
	global_store_dwordx4 v[12:13], v[2:5], off
	s_nop 1
	v_lshlrev_b64 v[2:3], 8, v[14:15]
	v_lshl_add_u64 v[2:3], v[10:11], 0, v[2:3]
	s_waitcnt lgkmcnt(0)
	global_store_dwordx4 v[2:3], v[6:9], off
	s_barrier

; #define G_LOAD(S, kt_) do { G_LD1(S##a0, S##b0, 0, kt_); G_LD1(S##a1, S##b1, 1, kt_); G_LD1(S##a2, S##b2, 2, kt_); G_LD1(S##a3, S##b3, 3, kt_); } while (0)
; #define G_STORE(S, buf_) do { G_ST1(S##a0, S##b0, 0, buf_); G_ST1(S##a1, S##b1, 1, buf_); G_ST1(S##a2, S##b2, 2, buf_); G_ST1(S##a3, S##b3, 3, buf_); } while (0)
; template <class AL, class BL>
; DI void gemm_core(AL al, BL bl, int m0, int n0, int K, char* smem, f32x16 (&acc)[2][2]) {
;     ...
;   const int srow = tid >> 3, sch = tid & 7;
;     ...
;   G_LOAD(x, 0);
;   G_STORE(x, 0);
;   G_LOAD(x, 1);
;   G_LOAD(y, (nk > 2) ? 2 : 1);
;   __syncthreads();
; __global__ void __launch_bounds__(256, 2) fwd_megakernel(Params p) {
;     ...
;         } else if (t < e3) {
;           const int tt = t - e2, tn = tt % (NP / 128), tm = tt / (NP / 128);
;           gemm_core([=](int m, int k) { return wuvT + (long)m * 256 + k; },
;                     [=](int n, int k) { return latall + (long)n * 256 + k; }, tm * 128, tn * 128, 256, smem, acc);
;           epi_bf16_vtile(acc, vtp + ((long)tm * (NP / 64) + 2 * tn) * 8192, smem, [=](float v) { return v; });
.LBB0_558:
	s_andn2_b64 vcc, exec, s[0:1]
	s_cbranch_vccnz .LBB0_560
	s_add_i32 s1, s56, s73
	s_ashr_i32 s0, s1, 31
	s_lshr_b32 s0, s0, 25
	s_add_i32 s30, s1, s0
	v_mov_b32_e32 v34, v202
	s_and_b32 s31, s30, 0xffffff80
	s_ashr_i32 s0, s30, 7
	v_ashrrev_i32_e32 v35, 3, v34
	v_add_u32_e32 v2, s31, v35
	s_sub_i32 s30, s1, s31
	v_ashrrev_i32_e32 v3, 31, v2
	v_readlane_b32 s52, v226, 21
	v_lshlrev_b64 v[2:3], 9, v[2:3]
	v_readlane_b32 s53, v226, 22
	v_lshlrev_b32_e32 v0, 4, v34
	v_lshl_add_u32 v6, s30, 7, v35
	v_lshl_add_u64 v[2:3], s[52:53], 0, v[2:3]
	v_and_b32_e32 v0, 0x70, v0
	v_ashrrev_i32_e32 v7, 31, v6
	s_waitcnt vmcnt(4)
	v_lshl_add_u64 v[146:147], v[2:3], 0, v[0:1]
	v_lshlrev_b64 v[6:7], 9, v[6:7]
	v_lshl_add_u64 v[6:7], s[24:25], 0, v[6:7]
	v_add_co_u32_e32 v10, vcc, s33, v146
	s_waitcnt vmcnt(3)
	v_lshl_add_u64 v[148:149], v[6:7], 0, v[0:1]
	v_addc_co_u32_e32 v11, vcc, 0, v147, vcc
	v_add_co_u32_e32 v14, vcc, s33, v148
	global_load_dwordx4 v[2:5], v[146:147], off
	global_load_dwordx4 v[6:9], v[148:149], off
	v_addc_co_u32_e32 v15, vcc, 0, v149, vcc
	v_add_co_u32_e32 v18, vcc, s80, v146
	global_load_dwordx4 v[10:13], v[10:11], off
	s_nop 0
	v_addc_co_u32_e32 v19, vcc, 0, v147, vcc
	v_add_co_u32_e32 v22, vcc, s80, v148
	global_load_dwordx4 v[14:17], v[14:15], off
	s_nop 0
	v_addc_co_u32_e32 v23, vcc, 0, v149, vcc
	v_add_co_u32_e32 v26, vcc, s81, v146
	global_load_dwordx4 v[18:21], v[18:19], off
	s_nop 0
	v_addc_co_u32_e32 v27, vcc, 0, v147, vcc
	global_load_dwordx4 v[22:25], v[22:23], off
	v_add_co_u32_e32 v30, vcc, s81, v148
	global_load_dwordx4 v[26:29], v[26:27], off
	s_nop 0
	v_addc_co_u32_e32 v31, vcc, 0, v149, vcc
	global_load_dwordx4 v[30:33], v[30:31], off
	v_mad_u64_u32 v[130:131], s[52:53], v35, s82, v[0:1]
	v_lshl_add_u64 v[138:139], v[146:147], 0, s[18:19]
	v_lshl_add_u64 v[144:145], v[148:149], 0, s[18:19]
	v_lshl_add_u64 v[136:137], v[146:147], 0, s[88:89]
	v_lshl_add_u64 v[142:143], v[148:149], 0, s[88:89]
	v_lshl_add_u64 v[134:135], v[146:147], 0, s[90:91]
	v_lshl_add_u64 v[140:141], v[148:149], 0, s[90:91]
	v_add_u32_e32 v0, 0x9000, v130
	global_load_dwordx4 v[122:125], v[146:147], off offset:128
	global_load_dwordx4 v[126:129], v[148:149], off offset:128
	global_load_dwordx4 v[114:117], v[138:139], off offset:128
	global_load_dwordx4 v[118:121], v[144:145], off offset:128
	global_load_dwordx4 v[106:109], v[136:137], off offset:128
	global_load_dwordx4 v[110:113], v[142:143], off offset:128
	global_load_dwordx4 v[98:101], v[134:135], off offset:128
	global_load_dwordx4 v[102:105], v[140:141], off offset:128
	global_load_dwordx4 v[90:93], v[146:147], off offset:256
	global_load_dwordx4 v[94:97], v[148:149], off offset:256
	global_load_dwordx4 v[82:85], v[138:139], off offset:256
	global_load_dwordx4 v[86:89], v[144:145], off offset:256
	global_load_dwordx4 v[74:77], v[136:137], off offset:256
	global_load_dwordx4 v[78:81], v[142:143], off offset:256
	global_load_dwordx4 v[66:69], v[134:135], off offset:256
	global_load_dwordx4 v[70:73], v[140:141], off offset:256
	s_waitcnt vmcnt(23)
	ds_write_b128 v130, v[2:5]
	s_waitcnt vmcnt(22)
	ds_write_b128 v130, v[6:9] offset:36864
	s_waitcnt vmcnt(21)
	ds_write_b128 v130, v[10:13] offset:4608
	s_waitcnt vmcnt(20)
	ds_write_b128 v130, v[14:17] offset:41472
	s_waitcnt vmcnt(19)
	ds_write_b128 v130, v[18:21] offset:9216
	s_waitcnt vmcnt(18)
	ds_write_b128 v130, v[22:25] offset:46080
	s_waitcnt vmcnt(17)
	ds_write_b128 v130, v[26:29] offset:13824
	s_waitcnt vmcnt(16)
	ds_write_b128 v130, v[30:33] offset:50688
	v_lshrrev_b32_e32 v2, 1, v34
	v_and_b32_e32 v3, 31, v34
	v_and_or_b32 v3, v2, s83, v3
	v_and_b32_e32 v2, 16, v2
	v_mad_u64_u32 v[132:133], s[52:53], v3, s82, v[2:3]
	v_and_b32_e32 v3, 0x5f, v34
	v_mul_u32_u24_e32 v3, 0x48, v3
	s_waitcnt lgkmcnt(0)
	s_barrier
	v_lshl_add_u32 v131, v3, 1, v2
	ds_read_b128 v[2:5], v132 offset:4608
	ds_read_b128 v[6:9], v131 offset:41472
	ds_read_b128 v[10:13], v132
	ds_read_b128 v[150:153], v132 offset:32
	ds_read_b128 v[154:157], v132 offset:4640
	ds_read_b128 v[14:17], v131 offset:36864
	ds_read_b128 v[158:161], v131 offset:36896
	ds_read_b128 v[162:165], v131 offset:41504
	s_waitcnt lgkmcnt(2)
	v_mfma_f32_32x32x16_bf16 v[50:65], v[10:13], v[14:17], 0
	s_waitcnt vmcnt(15)
	ds_write_b128 v130, v[122:125] offset:18432
	s_waitcnt vmcnt(14)
	ds_write_b128 v130, v[126:129] offset:55296
	global_load_dwordx4 v[122:125], v[146:147], off offset:384
	global_load_dwordx4 v[126:129], v[148:149], off offset:384
	v_mfma_f32_32x32x16_bf16 v[34:49], v[10:13], v[6:9], 0
	v_mfma_f32_32x32x16_bf16 v[18:33], v[2:5], v[14:17], 0
	v_mfma_f32_32x32x16_bf16 v[2:17], v[2:5], v[6:9], 0
	s_waitcnt lgkmcnt(3)
	v_mfma_f32_32x32x16_bf16 v[50:65], v[150:153], v[158:161], v[50:65]
	s_waitcnt lgkmcnt(2)
	v_mfma_f32_32x32x16_bf16 v[34:49], v[150:153], v[162:165], v[34:49]
	global_load_dwordx4 v[146:149], v[138:139], off offset:384
	global_load_dwordx4 v[150:153], v[144:145], off offset:384
	v_mfma_f32_32x32x16_bf16 v[18:33], v[154:157], v[158:161], v[18:33]
	ds_read_b128 v[158:161], v132 offset:64
	ds_read_b128 v[166:169], v132 offset:4672
	ds_read_b128 v[170:173], v131 offset:36928
	ds_read_b128 v[174:177], v131 offset:41536
	s_waitcnt vmcnt(17)
	ds_write_b128 v130, v[114:117] offset:23040
	s_waitcnt vmcnt(16)
	ds_write_b128 v130, v[118:121] offset:59904
	v_mfma_f32_32x32x16_bf16 v[2:17], v[154:157], v[162:165], v[2:17]
	global_load_dwordx4 v[114:117], v[136:137], off offset:384
	global_load_dwordx4 v[118:121], v[142:143], off offset:384
	s_waitcnt lgkmcnt(3)
	v_mfma_f32_32x32x16_bf16 v[50:65], v[158:161], v[170:173], v[50:65]
	s_waitcnt lgkmcnt(2)
	v_mfma_f32_32x32x16_bf16 v[34:49], v[158:161], v[174:177], v[34:49]
	ds_read_b128 v[136:139], v132 offset:96
	ds_read_b128 v[142:145], v132 offset:4704
	ds_read_b128 v[154:157], v131 offset:36960
	ds_read_b128 v[158:161], v131 offset:41568
	s_waitcnt vmcnt(17)
	ds_write_b128 v130, v[106:109] offset:27648
	s_waitcnt vmcnt(16)
	ds_write_b128 v130, v[110:113] offset:64512
	v_mfma_f32_32x32x16_bf16 v[18:33], v[166:169], v[170:173], v[18:33]
	v_mfma_f32_32x32x16_bf16 v[2:17], v[166:169], v[174:177], v[2:17]
	global_load_dwordx4 v[106:109], v[134:135], off offset:384
	global_load_dwordx4 v[110:113], v[140:141], off offset:384
	s_waitcnt lgkmcnt(3)
	v_mfma_f32_32x32x16_bf16 v[50:65], v[136:139], v[154:157], v[50:65]
	s_waitcnt vmcnt(17)
	ds_write_b128 v130, v[98:101] offset:32256
	s_waitcnt vmcnt(16)
	ds_write_b128 v0, v[102:105] offset:32256
	s_waitcnt lgkmcnt(4)
	v_mfma_f32_32x32x16_bf16 v[34:49], v[136:139], v[158:161], v[34:49]
	v_mfma_f32_32x32x16_bf16 v[18:33], v[142:145], v[154:157], v[18:33]
	v_mfma_f32_32x32x16_bf16 v[2:17], v[142:145], v[158:161], v[2:17]
	s_waitcnt lgkmcnt(0)
	s_barrier
; #define G_LOAD(S, kt_) do { G_LD1(S##a0, S##b0, 0, kt_); G_LD1(S##a1, S##b1, 1, kt_); G_LD1(S##a2, S##b2, 2, kt_); G_LD1(S##a3, S##b3, 3, kt_); } while (0)
; #define G_STORE(S, buf_) do { G_ST1(S##a0, S##b0, 0, buf_); G_ST1(S##a1, S##b1, 1, buf_); G_ST1(S##a2, S##b2, 2, buf_); G_ST1(S##a3, S##b3, 3, buf_); } while (0)
; template <class AL, class BL>
; DI void gemm_core(AL al, BL bl, int m0, int n0, int K, char* smem, f32x16 (&acc)[2][2]) {
;     ...
;   G_LOAD(x, 0);
;   G_STORE(x, 0);
;   G_LOAD(x, 1);
;   G_LOAD(y, (nk > 2) ? 2 : 1);
;   __syncthreads();
;   for (int kt = 0; kt < nk; kt += 2) {
;     G_TILE(0, x, true, (kt + 3 < nk), kt + 3);
;     __syncthreads();
;     G_TILE(1, y, (kt + 2 < nk), (kt + 4 < nk), kt + 4);
;     __syncthreads();
	ds_read_b128 v[98:101], v132 offset:18432
	ds_read_b128 v[102:105], v131 offset:55296
	ds_read_b128 v[134:137], v131 offset:59904
	s_waitcnt lgkmcnt(1)
	v_mfma_f32_32x32x16_bf16 v[50:65], v[98:101], v[102:105], v[50:65]
	s_waitcnt lgkmcnt(0)
	v_mfma_f32_32x32x16_bf16 v[34:49], v[98:101], v[134:137], v[34:49]
	ds_read_b128 v[98:101], v132 offset:23040
	s_waitcnt lgkmcnt(0)
	v_mfma_f32_32x32x16_bf16 v[18:33], v[98:101], v[102:105], v[18:33]
	ds_read_b128 v[102:105], v132 offset:18464
	ds_read_b128 v[138:141], v131 offset:55328
	ds_read_b128 v[142:145], v131 offset:59936
	ds_read_b128 v[154:157], v132 offset:23072
	s_waitcnt vmcnt(15)
	ds_write_b128 v130, v[90:93]
	s_waitcnt vmcnt(14)
	ds_write_b128 v130, v[94:97] offset:36864
	v_mfma_f32_32x32x16_bf16 v[2:17], v[98:101], v[134:137], v[2:17]
	s_waitcnt lgkmcnt(4)
	v_mfma_f32_32x32x16_bf16 v[50:65], v[102:105], v[138:141], v[50:65]
	s_waitcnt lgkmcnt(3)
	v_mfma_f32_32x32x16_bf16 v[34:49], v[102:105], v[142:145], v[34:49]
	ds_read_b128 v[90:93], v132 offset:18496
	ds_read_b128 v[94:97], v132 offset:23104
	ds_read_b128 v[98:101], v131 offset:55360
	ds_read_b128 v[102:105], v131 offset:59968
	s_waitcnt vmcnt(13)
	ds_write_b128 v130, v[82:85] offset:4608
	s_waitcnt vmcnt(12)
	ds_write_b128 v130, v[86:89] offset:41472
	s_waitcnt lgkmcnt(8)
	v_mfma_f32_32x32x16_bf16 v[18:33], v[154:157], v[138:141], v[18:33]
	v_mfma_f32_32x32x16_bf16 v[2:17], v[154:157], v[142:145], v[2:17]
	s_waitcnt lgkmcnt(3)
	v_mfma_f32_32x32x16_bf16 v[50:65], v[90:93], v[98:101], v[50:65]
	s_waitcnt lgkmcnt(2)
	v_mfma_f32_32x32x16_bf16 v[34:49], v[90:93], v[102:105], v[34:49]
	v_mfma_f32_32x32x16_bf16 v[18:33], v[94:97], v[98:101], v[18:33]
	ds_read_b128 v[82:85], v132 offset:18528
	ds_read_b128 v[86:89], v132 offset:23136
	ds_read_b128 v[90:93], v131 offset:55392
	ds_read_b128 v[98:101], v131 offset:60000
	s_waitcnt vmcnt(11)
	ds_write_b128 v130, v[74:77] offset:9216
	s_waitcnt vmcnt(10)
	ds_write_b128 v130, v[78:81] offset:46080
	v_mfma_f32_32x32x16_bf16 v[2:17], v[94:97], v[102:105], v[2:17]
	s_waitcnt lgkmcnt(3)
	v_mfma_f32_32x32x16_bf16 v[50:65], v[82:85], v[90:93], v[50:65]
	s_waitcnt vmcnt(9)
	ds_write_b128 v130, v[66:69] offset:13824
	s_waitcnt vmcnt(8)
	ds_write_b128 v130, v[70:73] offset:50688
	s_waitcnt lgkmcnt(4)
	v_mfma_f32_32x32x16_bf16 v[34:49], v[82:85], v[98:101], v[34:49]
	v_mfma_f32_32x32x16_bf16 v[18:33], v[86:89], v[90:93], v[18:33]
	v_mfma_f32_32x32x16_bf16 v[2:17], v[86:89], v[98:101], v[2:17]
	s_waitcnt lgkmcnt(0)
	s_barrier
	ds_read_b128 v[66:69], v132
	ds_read_b128 v[70:73], v131 offset:36864
	ds_read_b128 v[74:77], v131 offset:41472
	s_waitcnt lgkmcnt(1)
	v_mfma_f32_32x32x16_bf16 v[50:65], v[66:69], v[70:73], v[50:65]
	s_waitcnt lgkmcnt(0)
	v_mfma_f32_32x32x16_bf16 v[34:49], v[66:69], v[74:77], v[34:49]
	ds_read_b128 v[66:69], v132 offset:4608
	s_waitcnt lgkmcnt(0)
	v_mfma_f32_32x32x16_bf16 v[18:33], v[66:69], v[70:73], v[18:33]
	ds_read_b128 v[70:73], v132 offset:32
	ds_read_b128 v[78:81], v131 offset:36896
	ds_read_b128 v[82:85], v131 offset:41504
	ds_read_b128 v[86:89], v132 offset:4640
	s_waitcnt vmcnt(7)
	ds_write_b128 v130, v[122:125] offset:18432
	s_waitcnt vmcnt(6)
	ds_write_b128 v130, v[126:129] offset:55296
	v_mfma_f32_32x32x16_bf16 v[2:17], v[66:69], v[74:77], v[2:17]
	s_waitcnt lgkmcnt(4)
	v_mfma_f32_32x32x16_bf16 v[50:65], v[70:73], v[78:81], v[50:65]
	s_waitcnt lgkmcnt(3)
	v_mfma_f32_32x32x16_bf16 v[34:49], v[70:73], v[82:85], v[34:49]
	s_waitcnt lgkmcnt(2)
	v_mfma_f32_32x32x16_bf16 v[18:33], v[86:89], v[78:81], v[18:33]
	ds_read_b128 v[66:69], v132 offset:64
	ds_read_b128 v[70:73], v132 offset:4672
	ds_read_b128 v[74:77], v131 offset:36928
	ds_read_b128 v[78:81], v131 offset:41536
	s_waitcnt vmcnt(5)
	ds_write_b128 v130, v[146:149] offset:23040
	s_waitcnt vmcnt(4)
	ds_write_b128 v130, v[150:153] offset:59904
	v_mfma_f32_32x32x16_bf16 v[2:17], v[86:89], v[82:85], v[2:17]
	s_waitcnt lgkmcnt(3)
	v_mfma_f32_32x32x16_bf16 v[50:65], v[66:69], v[74:77], v[50:65]
	s_waitcnt lgkmcnt(2)
	v_mfma_f32_32x32x16_bf16 v[34:49], v[66:69], v[78:81], v[34:49]
	v_mfma_f32_32x32x16_bf16 v[18:33], v[70:73], v[74:77], v[18:33]
	ds_read_b128 v[66:69], v132 offset:96
	ds_read_b128 v[74:77], v132 offset:4704
	ds_read_b128 v[82:85], v131 offset:36960
	ds_read_b128 v[86:89], v131 offset:41568
	s_waitcnt vmcnt(3)
	ds_write_b128 v130, v[114:117] offset:27648
	s_waitcnt vmcnt(2)
	ds_write_b128 v130, v[118:121] offset:64512
	v_mfma_f32_32x32x16_bf16 v[2:17], v[70:73], v[78:81], v[2:17]
	s_waitcnt lgkmcnt(3)
	v_mfma_f32_32x32x16_bf16 v[50:65], v[66:69], v[82:85], v[50:65]
	s_waitcnt vmcnt(1)
	ds_write_b128 v130, v[106:109] offset:32256
	s_waitcnt vmcnt(0)
	ds_write_b128 v0, v[110:113] offset:32256
	s_waitcnt lgkmcnt(4)
	v_mfma_f32_32x32x16_bf16 v[34:49], v[66:69], v[86:89], v[34:49]
	v_mfma_f32_32x32x16_bf16 v[18:33], v[74:77], v[82:85], v[18:33]
	v_mfma_f32_32x32x16_bf16 v[2:17], v[74:77], v[86:89], v[2:17]
	s_waitcnt lgkmcnt(0)
	s_barrier
; DI u16 f2bf(float x) { return (u16)(pack2(x, 0.f) & 0xffffu); }
; DI int opaque_tid() { int t = threadIdx.x; asm volatile("" : "+v"(t)); return t; }
; DI int crow(int i, int h) { return (i & 3) + 8 * (i >> 2) + 4 * h; }
; #define G_LOAD(S, kt_) do { G_LD1(S##a0, S##b0, 0, kt_); G_LD1(S##a1, S##b1, 1, kt_); G_LD1(S##a2, S##b2, 2, kt_); G_LD1(S##a3, S##b3, 3, kt_); } while (0)
; #define G_STORE(S, buf_) do { G_ST1(S##a0, S##b0, 0, buf_); G_ST1(S##a1, S##b1, 1, buf_); G_ST1(S##a2, S##b2, 2, buf_); G_ST1(S##a3, S##b3, 3, buf_); } while (0)
; template <class AL, class BL>
; DI void gemm_core(AL al, BL bl, int m0, int n0, int K, char* smem, f32x16 (&acc)[2][2]) {
;     ...
;   G_LOAD(x, 0);
;   G_STORE(x, 0);
;   G_LOAD(x, 1);
;   G_LOAD(y, (nk > 2) ? 2 : 1);
;   __syncthreads();
;   for (int kt = 0; kt < nk; kt += 2) {
;     G_TILE(0, x, true, (kt + 3 < nk), kt + 3);
;     __syncthreads();
;     G_TILE(1, y, (kt + 2 < nk), (kt + 4 < nk), kt + 4);
;     __syncthreads();
;   }
; template <class F>
; DI void epi_bf16_vtile(const f32x16 (&acc)[2][2], u16* dst0  , char* smem, F f) {
;   const int tid = opaque_tid(), lane = tid & 63, w = tid >> 6, wm = w >> 1, wn = w & 1, h = lane >> 5;
;   u16* T = (u16*)smem;
; #pragma unroll
;   for (int mt = 0; mt < 2; mt++)
; #pragma unroll
;     for (int nt = 0; nt < 2; nt++)
; #pragma unroll
;       for (int i = 0; i < 16; i++) {
;         const int ml = wm * 64 + mt * 32 + crow(i, h), nl = wn * 64 + nt * 32 + (lane & 31);
;         T[ml * 136 + nl] = f2bf(f(acc[mt][nt][i]));
;       }
;   __syncthreads();
	ds_read_b128 v[66:69], v132 offset:18432
	ds_read_b128 v[70:73], v131 offset:55296
	ds_read_b128 v[74:77], v131 offset:59904
	s_waitcnt lgkmcnt(1)
	v_mfma_f32_32x32x16_bf16 v[50:65], v[66:69], v[70:73], v[50:65]
	s_waitcnt lgkmcnt(0)
	v_mfma_f32_32x32x16_bf16 v[34:49], v[66:69], v[74:77], v[34:49]
	ds_read_b128 v[66:69], v132 offset:23040
	s_waitcnt lgkmcnt(0)
	v_mfma_f32_32x32x16_bf16 v[18:33], v[66:69], v[70:73], v[18:33]
	ds_read_b128 v[70:73], v132 offset:18464
	ds_read_b128 v[78:81], v131 offset:55328
	ds_read_b128 v[82:85], v131 offset:59936
	ds_read_b128 v[86:89], v132 offset:23072
	v_mfma_f32_32x32x16_bf16 v[2:17], v[66:69], v[74:77], v[2:17]
	s_waitcnt lgkmcnt(2)
	v_mfma_f32_32x32x16_bf16 v[50:65], v[70:73], v[78:81], v[50:65]
	s_waitcnt lgkmcnt(1)
	v_mfma_f32_32x32x16_bf16 v[34:49], v[70:73], v[82:85], v[34:49]
	s_waitcnt lgkmcnt(0)
	v_mfma_f32_32x32x16_bf16 v[18:33], v[86:89], v[78:81], v[18:33]
	ds_read_b128 v[66:69], v132 offset:18496
	ds_read_b128 v[70:73], v132 offset:23104
	ds_read_b128 v[74:77], v131 offset:55360
	ds_read_b128 v[78:81], v131 offset:59968
	v_mfma_f32_32x32x16_bf16 v[2:17], v[86:89], v[82:85], v[2:17]
	s_waitcnt lgkmcnt(1)
	v_mfma_f32_32x32x16_bf16 v[50:65], v[66:69], v[74:77], v[50:65]
	s_waitcnt lgkmcnt(0)
	v_mfma_f32_32x32x16_bf16 v[34:49], v[66:69], v[78:81], v[34:49]
	v_mfma_f32_32x32x16_bf16 v[18:33], v[70:73], v[74:77], v[18:33]
	ds_read_b128 v[66:69], v132 offset:18528
	ds_read_b128 v[74:77], v132 offset:23136
	ds_read_b128 v[82:85], v131 offset:55392
	ds_read_b128 v[86:89], v131 offset:60000
	v_mfma_f32_32x32x16_bf16 v[2:17], v[70:73], v[78:81], v[2:17]
	s_waitcnt lgkmcnt(1)
	v_mfma_f32_32x32x16_bf16 v[50:65], v[66:69], v[82:85], v[50:65]
	s_waitcnt lgkmcnt(0)
	v_mfma_f32_32x32x16_bf16 v[34:49], v[66:69], v[86:89], v[34:49]
	v_mfma_f32_32x32x16_bf16 v[18:33], v[74:77], v[82:85], v[18:33]
	v_mfma_f32_32x32x16_bf16 v[2:17], v[74:77], v[86:89], v[2:17]
	s_ashr_i32 s1, s0, 31
	s_lshl_b32 s30, s30, 1
	v_mov_b32_e32 v66, v202
	s_barrier
	s_ashr_i32 s31, s30, 31
	s_lshl_b64 s[0:1], s[0:1], 22
	s_add_u32 s52, s42, s0
	v_lshrrev_b32_e32 v0, 1, v66
	v_and_b32_e32 v0, 0xfffffc0, v0
	v_lshrrev_b32_e32 v67, 3, v66
	s_addc_u32 s53, s43, s1
	s_lshl_b64 s[0:1], s[30:31], 14
	v_and_or_b32 v0, v67, 4, v0
	s_add_u32 s0, s52, s0
	v_and_b32_e32 v67, 0x5f, v66
	v_mul_lo_u32 v0, v0, s51
	v_lshl_add_u32 v0, v67, 1, v0
	v_cvt_pk_bf16_f32 v2, v2, s0
	v_cvt_pk_bf16_f32 v50, v50, s0
	v_cvt_pk_bf16_f32 v34, v34, s0
	v_cvt_pk_bf16_f32 v18, v18, s0
	ds_write_b16 v0, v2 offset:8768
	v_cvt_pk_bf16_f32 v2, v3, s0
	ds_write_b16 v0, v50
	v_cvt_pk_bf16_f32 v50, v51, s0
	ds_write_b16 v0, v34 offset:64
	v_cvt_pk_bf16_f32 v34, v35, s0
	ds_write_b16 v0, v18 offset:8704
	v_cvt_pk_bf16_f32 v18, v19, s0
	ds_write_b16 v0, v2 offset:9040
	v_cvt_pk_bf16_f32 v2, v4, s0
	ds_write_b16 v0, v50 offset:272
	v_cvt_pk_bf16_f32 v50, v52, s0
	ds_write_b16 v0, v34 offset:336
	v_cvt_pk_bf16_f32 v34, v36, s0
	ds_write_b16 v0, v18 offset:8976
	v_cvt_pk_bf16_f32 v18, v20, s0
	ds_write_b16 v0, v2 offset:9312
	v_cvt_pk_bf16_f32 v2, v5, s0
	ds_write_b16 v0, v50 offset:544
	v_cvt_pk_bf16_f32 v50, v53, s0
	ds_write_b16 v0, v34 offset:608
	v_cvt_pk_bf16_f32 v34, v37, s0
	ds_write_b16 v0, v18 offset:9248
	v_cvt_pk_bf16_f32 v18, v21, s0
	ds_write_b16 v0, v2 offset:9584
	v_cvt_pk_bf16_f32 v2, v6, s0
	ds_write_b16 v0, v50 offset:816
	v_cvt_pk_bf16_f32 v50, v54, s0
	ds_write_b16 v0, v34 offset:880
	v_cvt_pk_bf16_f32 v34, v38, s0
	ds_write_b16 v0, v18 offset:9520
	v_cvt_pk_bf16_f32 v18, v22, s0
	ds_write_b16 v0, v2 offset:10944
	v_cvt_pk_bf16_f32 v2, v7, s0
	ds_write_b16 v0, v50 offset:2176
	v_cvt_pk_bf16_f32 v50, v55, s0
	ds_write_b16 v0, v34 offset:2240
	v_cvt_pk_bf16_f32 v34, v39, s0
	ds_write_b16 v0, v18 offset:10880
	v_cvt_pk_bf16_f32 v18, v23, s0
	ds_write_b16 v0, v2 offset:11216
	v_cvt_pk_bf16_f32 v2, v8, s0
	ds_write_b16 v0, v50 offset:2448
	v_cvt_pk_bf16_f32 v50, v56, s0
	ds_write_b16 v0, v34 offset:2512
	v_cvt_pk_bf16_f32 v34, v40, s0
	ds_write_b16 v0, v18 offset:11152
	v_cvt_pk_bf16_f32 v18, v24, s0
	ds_write_b16 v0, v2 offset:11488
	v_cvt_pk_bf16_f32 v2, v9, s0
	ds_write_b16 v0, v50 offset:2720
	v_cvt_pk_bf16_f32 v50, v57, s0
	ds_write_b16 v0, v34 offset:2784
	v_cvt_pk_bf16_f32 v34, v41, s0
	ds_write_b16 v0, v18 offset:11424
	v_cvt_pk_bf16_f32 v18, v25, s0
	ds_write_b16 v0, v2 offset:11760
	v_cvt_pk_bf16_f32 v2, v10, s0
	ds_write_b16 v0, v50 offset:2992
	v_cvt_pk_bf16_f32 v50, v58, s0
	ds_write_b16 v0, v34 offset:3056
	v_cvt_pk_bf16_f32 v34, v42, s0
	ds_write_b16 v0, v18 offset:11696
	v_cvt_pk_bf16_f32 v18, v26, s0
	ds_write_b16 v0, v2 offset:13120
	v_cvt_pk_bf16_f32 v2, v11, s0
	ds_write_b16 v0, v50 offset:4352
	v_cvt_pk_bf16_f32 v50, v59, s0
	ds_write_b16 v0, v34 offset:4416
	v_cvt_pk_bf16_f32 v34, v43, s0
	ds_write_b16 v0, v18 offset:13056
	v_cvt_pk_bf16_f32 v18, v27, s0
	ds_write_b16 v0, v2 offset:13392
	v_cvt_pk_bf16_f32 v2, v12, s0
	ds_write_b16 v0, v50 offset:4624
	v_cvt_pk_bf16_f32 v50, v60, s0
	ds_write_b16 v0, v34 offset:4688
	v_cvt_pk_bf16_f32 v34, v44, s0
	ds_write_b16 v0, v18 offset:13328
	v_cvt_pk_bf16_f32 v18, v28, s0
	ds_write_b16 v0, v2 offset:13664
	v_cvt_pk_bf16_f32 v2, v13, s0
	ds_write_b16 v0, v50 offset:4896
	v_cvt_pk_bf16_f32 v50, v61, s0
	ds_write_b16 v0, v34 offset:4960
	v_cvt_pk_bf16_f32 v34, v45, s0
	ds_write_b16 v0, v18 offset:13600
	v_cvt_pk_bf16_f32 v18, v29, s0
	ds_write_b16 v0, v2 offset:13936
	v_cvt_pk_bf16_f32 v2, v14, s0
	ds_write_b16 v0, v50 offset:5168
	v_cvt_pk_bf16_f32 v50, v62, s0
	ds_write_b16 v0, v34 offset:5232
	v_cvt_pk_bf16_f32 v34, v46, s0
	ds_write_b16 v0, v18 offset:13872
	v_cvt_pk_bf16_f32 v18, v30, s0
	ds_write_b16 v0, v2 offset:15296
	v_cvt_pk_bf16_f32 v2, v15, s0
	ds_write_b16 v0, v50 offset:6528
	v_cvt_pk_bf16_f32 v50, v63, s0
	ds_write_b16 v0, v34 offset:6592
	v_cvt_pk_bf16_f32 v34, v47, s0
	ds_write_b16 v0, v18 offset:15232
	v_cvt_pk_bf16_f32 v18, v31, s0
	ds_write_b16 v0, v2 offset:15568
	v_cvt_pk_bf16_f32 v2, v16, s0
	ds_write_b16 v0, v50 offset:6800
	v_cvt_pk_bf16_f32 v50, v64, s0
	ds_write_b16 v0, v34 offset:6864
	v_cvt_pk_bf16_f32 v34, v48, s0
	ds_write_b16 v0, v18 offset:15504
	v_cvt_pk_bf16_f32 v18, v32, s0
	ds_write_b16 v0, v2 offset:15840
	v_cvt_pk_bf16_f32 v2, v17, s0
	ds_write_b16 v0, v50 offset:7072
	v_cvt_pk_bf16_f32 v50, v65, s0
	ds_write_b16 v0, v34 offset:7136
	v_cvt_pk_bf16_f32 v34, v49, s0
	ds_write_b16 v0, v18 offset:15776
	v_cvt_pk_bf16_f32 v18, v33, s0
	ds_write_b16 v0, v2 offset:16112
	v_lshlrev_b32_e32 v2, 4, v66
	s_addc_u32 s1, s53, s1
	ds_write_b16 v0, v50 offset:7344
	ds_write_b16 v0, v34 offset:7408
	ds_write_b16 v0, v18 offset:16048
	v_and_b32_e32 v10, 0xf0, v2
	v_and_b32_e32 v0, 0x80, v2
	v_and_b32_e32 v2, 0x70, v2
	v_mov_b32_e32 v3, v1
	v_lshl_add_u64 v[12:13], s[0:1], 0, v[2:3]
	v_ashrrev_i32_e32 v2, 4, v66
	v_ashrrev_i32_e32 v3, 31, v2
	v_mad_u64_u32 v[4:5], s[0:1], v2, s51, v[10:11]
	v_lshl_add_u64 v[2:3], v[0:1], 0, v[2:3]
	v_lshlrev_b64 v[2:3], 7, v[2:3]
	s_waitcnt lgkmcnt(0)
	s_barrier
; template <class F>
; DI void epi_bf16_vtile(const f32x16 (&acc)[2][2], u16* dst0  , char* smem, F f) {
;     ...
; #pragma unroll
;   for (int j = 0; j < 8; j++) {
;     const int idx = tid + 256 * j, row = idx >> 4, ch = idx & 15;
;     *(uint4*)(dst0 + ((long)(ch >> 3) * 128 + row) * 64 + (ch & 7) * 8) = *(const uint4*)(T + row * 136 + ch * 8);
;   }
;   __syncthreads();
	v_lshl_add_u64 v[14:15], v[12:13], 0, v[2:3]
	ds_read_b128 v[2:5], v4
	v_add_u32_e32 v6, 0x100, v66
	v_ashrrev_i32_e32 v16, 4, v6
	v_mad_u64_u32 v[6:7], s[0:1], v16, s51, v[10:11]
	ds_read_b128 v[6:9], v6
	v_ashrrev_i32_e32 v17, 31, v16
	s_waitcnt lgkmcnt(1)
	global_store_dwordx4 v[14:15], v[2:5], off
	s_nop 1
	v_lshl_add_u64 v[2:3], v[16:17], 0, v[0:1]
	v_lshlrev_b64 v[2:3], 7, v[2:3]
	v_lshl_add_u64 v[2:3], v[12:13], 0, v[2:3]
	s_waitcnt lgkmcnt(0)
	global_store_dwordx4 v[2:3], v[6:9], off
	v_add_u32_e32 v2, 0x200, v66
	v_ashrrev_i32_e32 v2, 4, v2
	v_ashrrev_i32_e32 v3, 31, v2
	v_mad_u64_u32 v[4:5], s[0:1], v2, s51, v[10:11]
	v_lshl_add_u64 v[2:3], v[2:3], 0, v[0:1]
	v_lshlrev_b64 v[2:3], 7, v[2:3]
	v_lshl_add_u64 v[14:15], v[12:13], 0, v[2:3]
	ds_read_b128 v[2:5], v4
	v_add_u32_e32 v6, 0x300, v66
	v_ashrrev_i32_e32 v16, 4, v6
	v_mad_u64_u32 v[6:7], s[0:1], v16, s51, v[10:11]
	ds_read_b128 v[6:9], v6
	v_ashrrev_i32_e32 v17, 31, v16
	s_waitcnt lgkmcnt(1)
	global_store_dwordx4 v[14:15], v[2:5], off
	s_nop 1
	v_lshl_add_u64 v[2:3], v[16:17], 0, v[0:1]
	v_lshlrev_b64 v[2:3], 7, v[2:3]
	v_lshl_add_u64 v[2:3], v[12:13], 0, v[2:3]
	s_waitcnt lgkmcnt(0)
	global_store_dwordx4 v[2:3], v[6:9], off
	v_add_u32_e32 v2, 0x400, v66
	v_ashrrev_i32_e32 v2, 4, v2
	v_ashrrev_i32_e32 v3, 31, v2
	v_mad_u64_u32 v[4:5], s[0:1], v2, s51, v[10:11]
	v_lshl_add_u64 v[2:3], v[2:3], 0, v[0:1]
	v_lshlrev_b64 v[2:3], 7, v[2:3]
	v_lshl_add_u64 v[14:15], v[12:13], 0, v[2:3]
	ds_read_b128 v[2:5], v4
	v_add_u32_e32 v6, 0x500, v66
	v_ashrrev_i32_e32 v16, 4, v6
	v_mad_u64_u32 v[6:7], s[0:1], v16, s51, v[10:11]
	ds_read_b128 v[6:9], v6
	v_ashrrev_i32_e32 v17, 31, v16
	s_waitcnt lgkmcnt(1)
	global_store_dwordx4 v[14:15], v[2:5], off
	s_nop 1
	v_lshl_add_u64 v[2:3], v[16:17], 0, v[0:1]
	v_lshlrev_b64 v[2:3], 7, v[2:3]
	v_lshl_add_u64 v[2:3], v[12:13], 0, v[2:3]
	s_waitcnt lgkmcnt(0)
	global_store_dwordx4 v[2:3], v[6:9], off
	v_add_u32_e32 v2, 0x600, v66
	v_ashrrev_i32_e32 v2, 4, v2
	v_ashrrev_i32_e32 v3, 31, v2
	v_mad_u64_u32 v[4:5], s[0:1], v2, s51, v[10:11]
	v_lshl_add_u64 v[2:3], v[2:3], 0, v[0:1]
	v_lshlrev_b64 v[2:3], 7, v[2:3]
	v_lshl_add_u64 v[14:15], v[12:13], 0, v[2:3]
	ds_read_b128 v[2:5], v4
	v_add_u32_e32 v6, 0x700, v66
	v_ashrrev_i32_e32 v16, 4, v6
	v_mad_u64_u32 v[6:7], s[0:1], v16, s51, v[10:11]
	ds_read_b128 v[6:9], v6
	v_ashrrev_i32_e32 v17, 31, v16
	s_waitcnt lgkmcnt(1)
	global_store_dwordx4 v[14:15], v[2:5], off
	s_nop 1
	v_lshl_add_u64 v[2:3], v[16:17], 0, v[0:1]
	v_lshlrev_b64 v[2:3], 7, v[2:3]
	v_lshl_add_u64 v[2:3], v[12:13], 0, v[2:3]
	s_waitcnt lgkmcnt(0)
	global_store_dwordx4 v[2:3], v[6:9], off
	s_barrier

; #define G_LOAD(S, kt_) do { G_LD1(S##a0, S##b0, 0, kt_); G_LD1(S##a1, S##b1, 1, kt_); G_LD1(S##a2, S##b2, 2, kt_); G_LD1(S##a3, S##b3, 3, kt_); } while (0)
; #define G_STORE(S, buf_) do { G_ST1(S##a0, S##b0, 0, buf_); G_ST1(S##a1, S##b1, 1, buf_); G_ST1(S##a2, S##b2, 2, buf_); G_ST1(S##a3, S##b3, 3, buf_); } while (0)
; template <class AL, class BL>
; DI void gemm_core(AL al, BL bl, int m0, int n0, int K, char* smem, f32x16 (&acc)[2][2]) {
;     ...
;   const int srow = tid >> 3, sch = tid & 7;
;     ...
;   G_LOAD(x, 0);
;   G_STORE(x, 0);
;   G_LOAD(x, 1);
;   G_LOAD(y, (nk > 2) ? 2 : 1);
;   __syncthreads();
; __global__ void __launch_bounds__(256, 2) fwd_megakernel(Params p) {
;     ...
;         } else if (t < e2) {
;           const int tt = t - e1, tm = tt % (NP / 128), tn = tt / (NP / 128);
;           gemm_core([=](int m, int k) { return latall + (long)m * 256 + k; },
;                     [=](int n, int k) { return wukT + (long)n * 256 + k; }, tm * 128, tn * 128, 256, smem, acc);
;           epi_bf16_tile(acc, tm * 128, tn * 128, knp + ((long)tn * NP + tm * 128) * 128, 128, smem, [=](int m, int n, float v) { return v; });
.LBB0_561:
	s_andn2_b64 vcc, exec, s[0:1]
	s_cbranch_vccnz .LBB0_563
	s_add_i32 s1, s57, s73
	s_ashr_i32 s0, s1, 31
	s_lshr_b32 s0, s0, 25
	s_add_i32 s30, s1, s0
	s_ashr_i32 s0, s30, 7
	s_and_b32 s30, s30, 0xffffff80
	s_sub_i32 s1, s1, s30
	v_mov_b32_e32 v34, v202
	s_lshl_b32 s52, s1, 7
	s_nop 0
	v_ashrrev_i32_e32 v35, 3, v34
	v_add_u32_e32 v2, s52, v35
	v_ashrrev_i32_e32 v3, 31, v2
	v_lshlrev_b64 v[2:3], 9, v[2:3]
	v_lshlrev_b32_e32 v0, 4, v34
	v_add_u32_e32 v6, s30, v35
	v_lshl_add_u64 v[2:3], s[24:25], 0, v[2:3]
	v_and_b32_e32 v0, 0x70, v0
	v_ashrrev_i32_e32 v7, 31, v6
	s_waitcnt vmcnt(4)
	v_lshl_add_u64 v[146:147], v[2:3], 0, v[0:1]
	v_lshlrev_b64 v[6:7], 9, v[6:7]
	v_lshl_add_u64 v[6:7], s[28:29], 0, v[6:7]
	v_add_co_u32_e32 v10, vcc, s33, v146
	s_waitcnt vmcnt(3)
	v_lshl_add_u64 v[148:149], v[6:7], 0, v[0:1]
	v_addc_co_u32_e32 v11, vcc, 0, v147, vcc
	v_add_co_u32_e32 v14, vcc, s33, v148
	global_load_dwordx4 v[2:5], v[146:147], off
	global_load_dwordx4 v[6:9], v[148:149], off
	v_addc_co_u32_e32 v15, vcc, 0, v149, vcc
	v_add_co_u32_e32 v18, vcc, s80, v146
	global_load_dwordx4 v[10:13], v[10:11], off
	s_nop 0
	v_addc_co_u32_e32 v19, vcc, 0, v147, vcc
	v_add_co_u32_e32 v22, vcc, s80, v148
	global_load_dwordx4 v[14:17], v[14:15], off
	s_nop 0
	v_addc_co_u32_e32 v23, vcc, 0, v149, vcc
	v_add_co_u32_e32 v26, vcc, s81, v146
	global_load_dwordx4 v[18:21], v[18:19], off
	s_nop 0
	v_addc_co_u32_e32 v27, vcc, 0, v147, vcc
	global_load_dwordx4 v[22:25], v[22:23], off
	v_add_co_u32_e32 v30, vcc, s81, v148
	global_load_dwordx4 v[26:29], v[26:27], off
	s_nop 0
	v_addc_co_u32_e32 v31, vcc, 0, v149, vcc
	global_load_dwordx4 v[30:33], v[30:31], off
	v_mad_u64_u32 v[130:131], s[30:31], v35, s82, v[0:1]
	v_lshl_add_u64 v[140:141], v[146:147], 0, s[18:19]
	v_lshl_add_u64 v[144:145], v[148:149], 0, s[18:19]
	v_lshl_add_u64 v[136:137], v[146:147], 0, s[88:89]
	v_lshl_add_u64 v[142:143], v[148:149], 0, s[88:89]
	v_lshl_add_u64 v[134:135], v[146:147], 0, s[90:91]
	v_lshl_add_u64 v[138:139], v[148:149], 0, s[90:91]
	v_add_u32_e32 v0, 0x9000, v130
	global_load_dwordx4 v[122:125], v[146:147], off offset:128
	global_load_dwordx4 v[126:129], v[148:149], off offset:128
	global_load_dwordx4 v[114:117], v[140:141], off offset:128
	global_load_dwordx4 v[118:121], v[144:145], off offset:128
	global_load_dwordx4 v[106:109], v[136:137], off offset:128
	global_load_dwordx4 v[110:113], v[142:143], off offset:128
	global_load_dwordx4 v[98:101], v[134:135], off offset:128
	global_load_dwordx4 v[102:105], v[138:139], off offset:128
	global_load_dwordx4 v[90:93], v[146:147], off offset:256
	global_load_dwordx4 v[94:97], v[148:149], off offset:256
	global_load_dwordx4 v[82:85], v[140:141], off offset:256
	global_load_dwordx4 v[86:89], v[144:145], off offset:256
	global_load_dwordx4 v[74:77], v[136:137], off offset:256
	global_load_dwordx4 v[78:81], v[142:143], off offset:256
	global_load_dwordx4 v[66:69], v[134:135], off offset:256
	global_load_dwordx4 v[70:73], v[138:139], off offset:256
	s_waitcnt vmcnt(23)
	ds_write_b128 v130, v[2:5]
	s_waitcnt vmcnt(22)
	ds_write_b128 v130, v[6:9] offset:36864
	s_waitcnt vmcnt(21)
	ds_write_b128 v130, v[10:13] offset:4608
	s_waitcnt vmcnt(20)
	ds_write_b128 v130, v[14:17] offset:41472
	s_waitcnt vmcnt(19)
	ds_write_b128 v130, v[18:21] offset:9216
	s_waitcnt vmcnt(18)
	ds_write_b128 v130, v[22:25] offset:46080
	s_waitcnt vmcnt(17)
	ds_write_b128 v130, v[26:29] offset:13824
	s_waitcnt vmcnt(16)
	ds_write_b128 v130, v[30:33] offset:50688
	v_lshrrev_b32_e32 v2, 1, v34
	v_and_b32_e32 v3, 31, v34
	v_and_or_b32 v3, v2, s83, v3
	v_and_b32_e32 v2, 16, v2
	v_mad_u64_u32 v[132:133], s[30:31], v3, s82, v[2:3]
	v_and_b32_e32 v3, 0x5f, v34
	v_mul_u32_u24_e32 v3, 0x48, v3
	s_waitcnt lgkmcnt(0)
	s_barrier
	v_lshl_add_u32 v131, v3, 1, v2
	ds_read_b128 v[2:5], v132 offset:4608
	ds_read_b128 v[6:9], v131 offset:41472
	ds_read_b128 v[10:13], v132
	ds_read_b128 v[150:153], v132 offset:32
	ds_read_b128 v[154:157], v132 offset:4640
	ds_read_b128 v[14:17], v131 offset:36864
	ds_read_b128 v[158:161], v131 offset:36896
	ds_read_b128 v[162:165], v131 offset:41504
	s_waitcnt lgkmcnt(2)
	v_mfma_f32_32x32x16_bf16 v[50:65], v[10:13], v[14:17], 0
	s_waitcnt vmcnt(15)
	ds_write_b128 v130, v[122:125] offset:18432
	s_waitcnt vmcnt(14)
	ds_write_b128 v130, v[126:129] offset:55296
	global_load_dwordx4 v[122:125], v[146:147], off offset:384
	global_load_dwordx4 v[126:129], v[148:149], off offset:384
	v_mfma_f32_32x32x16_bf16 v[34:49], v[10:13], v[6:9], 0
	v_mfma_f32_32x32x16_bf16 v[18:33], v[2:5], v[14:17], 0
	v_mfma_f32_32x32x16_bf16 v[2:17], v[2:5], v[6:9], 0
	s_waitcnt lgkmcnt(3)
	v_mfma_f32_32x32x16_bf16 v[50:65], v[150:153], v[158:161], v[50:65]
	s_waitcnt lgkmcnt(2)
	v_mfma_f32_32x32x16_bf16 v[34:49], v[150:153], v[162:165], v[34:49]
	global_load_dwordx4 v[146:149], v[140:141], off offset:384
	global_load_dwordx4 v[150:153], v[144:145], off offset:384
	v_mfma_f32_32x32x16_bf16 v[18:33], v[154:157], v[158:161], v[18:33]
	ds_read_b128 v[158:161], v132 offset:64
	ds_read_b128 v[166:169], v132 offset:4672
	ds_read_b128 v[170:173], v131 offset:36928
	ds_read_b128 v[174:177], v131 offset:41536
	s_waitcnt vmcnt(17)
	ds_write_b128 v130, v[114:117] offset:23040
	s_waitcnt vmcnt(16)
	ds_write_b128 v130, v[118:121] offset:59904
	v_mfma_f32_32x32x16_bf16 v[2:17], v[154:157], v[162:165], v[2:17]
	global_load_dwordx4 v[114:117], v[136:137], off offset:384
	global_load_dwordx4 v[118:121], v[142:143], off offset:384
	s_waitcnt lgkmcnt(3)
	v_mfma_f32_32x32x16_bf16 v[50:65], v[158:161], v[170:173], v[50:65]
	s_waitcnt lgkmcnt(2)
	v_mfma_f32_32x32x16_bf16 v[34:49], v[158:161], v[174:177], v[34:49]
	ds_read_b128 v[140:143], v132 offset:96
	ds_read_b128 v[154:157], v132 offset:4704
	ds_read_b128 v[158:161], v131 offset:36960
	ds_read_b128 v[162:165], v131 offset:41568
	s_waitcnt vmcnt(17)
	ds_write_b128 v130, v[106:109] offset:27648
	s_waitcnt vmcnt(16)
	ds_write_b128 v130, v[110:113] offset:64512
	v_mfma_f32_32x32x16_bf16 v[18:33], v[166:169], v[170:173], v[18:33]
	v_mfma_f32_32x32x16_bf16 v[2:17], v[166:169], v[174:177], v[2:17]
	global_load_dwordx4 v[106:109], v[134:135], off offset:384
	global_load_dwordx4 v[110:113], v[138:139], off offset:384
	s_waitcnt lgkmcnt(3)
	v_mfma_f32_32x32x16_bf16 v[50:65], v[140:143], v[158:161], v[50:65]
	s_waitcnt vmcnt(17)
	ds_write_b128 v130, v[98:101] offset:32256
	s_waitcnt vmcnt(16)
	ds_write_b128 v0, v[102:105] offset:32256
	s_waitcnt lgkmcnt(4)
	v_mfma_f32_32x32x16_bf16 v[34:49], v[140:143], v[162:165], v[34:49]
	v_mfma_f32_32x32x16_bf16 v[18:33], v[154:157], v[158:161], v[18:33]
	v_mfma_f32_32x32x16_bf16 v[2:17], v[154:157], v[162:165], v[2:17]
	s_waitcnt lgkmcnt(0)
	s_barrier
; #define G_LOAD(S, kt_) do { G_LD1(S##a0, S##b0, 0, kt_); G_LD1(S##a1, S##b1, 1, kt_); G_LD1(S##a2, S##b2, 2, kt_); G_LD1(S##a3, S##b3, 3, kt_); } while (0)
; #define G_STORE(S, buf_) do { G_ST1(S##a0, S##b0, 0, buf_); G_ST1(S##a1, S##b1, 1, buf_); G_ST1(S##a2, S##b2, 2, buf_); G_ST1(S##a3, S##b3, 3, buf_); } while (0)
; template <class AL, class BL>
; DI void gemm_core(AL al, BL bl, int m0, int n0, int K, char* smem, f32x16 (&acc)[2][2]) {
;     ...
;   G_LOAD(x, 0);
;   G_STORE(x, 0);
;   G_LOAD(x, 1);
;   G_LOAD(y, (nk > 2) ? 2 : 1);
;   __syncthreads();
;   for (int kt = 0; kt < nk; kt += 2) {
;     G_TILE(0, x, true, (kt + 3 < nk), kt + 3);
;     __syncthreads();
;     G_TILE(1, y, (kt + 2 < nk), (kt + 4 < nk), kt + 4);
;     __syncthreads();
	ds_read_b128 v[98:101], v132 offset:18432
	ds_read_b128 v[102:105], v131 offset:55296
	ds_read_b128 v[134:137], v131 offset:59904
	s_waitcnt lgkmcnt(1)
	v_mfma_f32_32x32x16_bf16 v[50:65], v[98:101], v[102:105], v[50:65]
	s_waitcnt lgkmcnt(0)
	v_mfma_f32_32x32x16_bf16 v[34:49], v[98:101], v[134:137], v[34:49]
	ds_read_b128 v[98:101], v132 offset:23040
	s_waitcnt lgkmcnt(0)
	v_mfma_f32_32x32x16_bf16 v[18:33], v[98:101], v[102:105], v[18:33]
	ds_read_b128 v[102:105], v132 offset:18464
	ds_read_b128 v[138:141], v131 offset:55328
	ds_read_b128 v[142:145], v131 offset:59936
	ds_read_b128 v[154:157], v132 offset:23072
	s_waitcnt vmcnt(15)
	ds_write_b128 v130, v[90:93]
	s_waitcnt vmcnt(14)
	ds_write_b128 v130, v[94:97] offset:36864
	v_mfma_f32_32x32x16_bf16 v[2:17], v[98:101], v[134:137], v[2:17]
	s_waitcnt lgkmcnt(4)
	v_mfma_f32_32x32x16_bf16 v[50:65], v[102:105], v[138:141], v[50:65]
	s_waitcnt lgkmcnt(3)
	v_mfma_f32_32x32x16_bf16 v[34:49], v[102:105], v[142:145], v[34:49]
	ds_read_b128 v[90:93], v132 offset:18496
	ds_read_b128 v[94:97], v132 offset:23104
	ds_read_b128 v[98:101], v131 offset:55360
	ds_read_b128 v[102:105], v131 offset:59968
	s_waitcnt vmcnt(13)
	ds_write_b128 v130, v[82:85] offset:4608
	s_waitcnt vmcnt(12)
	ds_write_b128 v130, v[86:89] offset:41472
	s_waitcnt lgkmcnt(8)
	v_mfma_f32_32x32x16_bf16 v[18:33], v[154:157], v[138:141], v[18:33]
	v_mfma_f32_32x32x16_bf16 v[2:17], v[154:157], v[142:145], v[2:17]
	s_waitcnt lgkmcnt(3)
	v_mfma_f32_32x32x16_bf16 v[50:65], v[90:93], v[98:101], v[50:65]
	s_waitcnt lgkmcnt(2)
	v_mfma_f32_32x32x16_bf16 v[34:49], v[90:93], v[102:105], v[34:49]
	v_mfma_f32_32x32x16_bf16 v[18:33], v[94:97], v[98:101], v[18:33]
	ds_read_b128 v[82:85], v132 offset:18528
	ds_read_b128 v[86:89], v132 offset:23136
	ds_read_b128 v[90:93], v131 offset:55392
	ds_read_b128 v[98:101], v131 offset:60000
	s_waitcnt vmcnt(11)
	ds_write_b128 v130, v[74:77] offset:9216
	s_waitcnt vmcnt(10)
	ds_write_b128 v130, v[78:81] offset:46080
	v_mfma_f32_32x32x16_bf16 v[2:17], v[94:97], v[102:105], v[2:17]
	s_waitcnt lgkmcnt(3)
	v_mfma_f32_32x32x16_bf16 v[50:65], v[82:85], v[90:93], v[50:65]
	s_waitcnt vmcnt(9)
	ds_write_b128 v130, v[66:69] offset:13824
	s_waitcnt vmcnt(8)
	ds_write_b128 v130, v[70:73] offset:50688
	s_waitcnt lgkmcnt(4)
	v_mfma_f32_32x32x16_bf16 v[34:49], v[82:85], v[98:101], v[34:49]
	v_mfma_f32_32x32x16_bf16 v[18:33], v[86:89], v[90:93], v[18:33]
	v_mfma_f32_32x32x16_bf16 v[2:17], v[86:89], v[98:101], v[2:17]
	s_waitcnt lgkmcnt(0)
	s_barrier
	ds_read_b128 v[66:69], v132
	ds_read_b128 v[70:73], v131 offset:36864
	ds_read_b128 v[74:77], v131 offset:41472
	s_waitcnt lgkmcnt(1)
	v_mfma_f32_32x32x16_bf16 v[50:65], v[66:69], v[70:73], v[50:65]
	s_waitcnt lgkmcnt(0)
	v_mfma_f32_32x32x16_bf16 v[34:49], v[66:69], v[74:77], v[34:49]
	ds_read_b128 v[66:69], v132 offset:4608
	s_waitcnt lgkmcnt(0)
	v_mfma_f32_32x32x16_bf16 v[18:33], v[66:69], v[70:73], v[18:33]
	ds_read_b128 v[70:73], v132 offset:32
	ds_read_b128 v[78:81], v131 offset:36896
	ds_read_b128 v[82:85], v131 offset:41504
	ds_read_b128 v[86:89], v132 offset:4640
	s_waitcnt vmcnt(7)
	ds_write_b128 v130, v[122:125] offset:18432
	s_waitcnt vmcnt(6)
	ds_write_b128 v130, v[126:129] offset:55296
	v_mfma_f32_32x32x16_bf16 v[2:17], v[66:69], v[74:77], v[2:17]
	s_waitcnt lgkmcnt(4)
	v_mfma_f32_32x32x16_bf16 v[50:65], v[70:73], v[78:81], v[50:65]
	s_waitcnt lgkmcnt(3)
	v_mfma_f32_32x32x16_bf16 v[34:49], v[70:73], v[82:85], v[34:49]
	s_waitcnt lgkmcnt(2)
	v_mfma_f32_32x32x16_bf16 v[18:33], v[86:89], v[78:81], v[18:33]
	ds_read_b128 v[66:69], v132 offset:64
	ds_read_b128 v[70:73], v132 offset:4672
	ds_read_b128 v[74:77], v131 offset:36928
	ds_read_b128 v[78:81], v131 offset:41536
	s_waitcnt vmcnt(5)
	ds_write_b128 v130, v[146:149] offset:23040
	s_waitcnt vmcnt(4)
	ds_write_b128 v130, v[150:153] offset:59904
	v_mfma_f32_32x32x16_bf16 v[2:17], v[86:89], v[82:85], v[2:17]
	s_waitcnt lgkmcnt(3)
	v_mfma_f32_32x32x16_bf16 v[50:65], v[66:69], v[74:77], v[50:65]
	s_waitcnt lgkmcnt(2)
	v_mfma_f32_32x32x16_bf16 v[34:49], v[66:69], v[78:81], v[34:49]
	v_mfma_f32_32x32x16_bf16 v[18:33], v[70:73], v[74:77], v[18:33]
	ds_read_b128 v[66:69], v132 offset:96
	ds_read_b128 v[74:77], v132 offset:4704
	ds_read_b128 v[82:85], v131 offset:36960
	ds_read_b128 v[86:89], v131 offset:41568
	s_waitcnt vmcnt(3)
	ds_write_b128 v130, v[114:117] offset:27648
	s_waitcnt vmcnt(2)
	ds_write_b128 v130, v[118:121] offset:64512
	v_mfma_f32_32x32x16_bf16 v[2:17], v[70:73], v[78:81], v[2:17]
	s_waitcnt lgkmcnt(3)
	v_mfma_f32_32x32x16_bf16 v[50:65], v[66:69], v[82:85], v[50:65]
	s_waitcnt vmcnt(1)
	ds_write_b128 v130, v[106:109] offset:32256
	s_waitcnt vmcnt(0)
	ds_write_b128 v0, v[110:113] offset:32256
	s_waitcnt lgkmcnt(4)
	v_mfma_f32_32x32x16_bf16 v[34:49], v[66:69], v[86:89], v[34:49]
	v_mfma_f32_32x32x16_bf16 v[18:33], v[74:77], v[82:85], v[18:33]
	v_mfma_f32_32x32x16_bf16 v[2:17], v[74:77], v[86:89], v[2:17]
	s_waitcnt lgkmcnt(0)
	s_barrier
; DI u16 f2bf(float x) { return (u16)(pack2(x, 0.f) & 0xffffu); }
; DI int opaque_tid() { int t = threadIdx.x; asm volatile("" : "+v"(t)); return t; }
; DI int crow(int i, int h) { return (i & 3) + 8 * (i >> 2) + 4 * h; }
; #define G_LOAD(S, kt_) do { G_LD1(S##a0, S##b0, 0, kt_); G_LD1(S##a1, S##b1, 1, kt_); G_LD1(S##a2, S##b2, 2, kt_); G_LD1(S##a3, S##b3, 3, kt_); } while (0)
; #define G_STORE(S, buf_) do { G_ST1(S##a0, S##b0, 0, buf_); G_ST1(S##a1, S##b1, 1, buf_); G_ST1(S##a2, S##b2, 2, buf_); G_ST1(S##a3, S##b3, 3, buf_); } while (0)
; template <class AL, class BL>
; DI void gemm_core(AL al, BL bl, int m0, int n0, int K, char* smem, f32x16 (&acc)[2][2]) {
;     ...
;   G_LOAD(x, 0);
;   G_STORE(x, 0);
;   G_LOAD(x, 1);
;   G_LOAD(y, (nk > 2) ? 2 : 1);
;   __syncthreads();
;   for (int kt = 0; kt < nk; kt += 2) {
;     G_TILE(0, x, true, (kt + 3 < nk), kt + 3);
;     __syncthreads();
;     G_TILE(1, y, (kt + 2 < nk), (kt + 4 < nk), kt + 4);
;     __syncthreads();
;   }
; template <class F>
; DI void epi_bf16_tile(const f32x16 (&acc)[2][2], int m0, int n0, u16* dst0, long ld, char* smem, F f) {
;   const int tid = opaque_tid(), lane = tid & 63, w = tid >> 6, wm = w >> 1, wn = w & 1, h = lane >> 5;
;   u16* T = (u16*)smem;
; #pragma unroll
;   for (int mt = 0; mt < 2; mt++)
; #pragma unroll
;     for (int nt = 0; nt < 2; nt++)
; #pragma unroll
;       for (int i = 0; i < 16; i++) {
;         const int ml = wm * 64 + mt * 32 + crow(i, h), nl = wn * 64 + nt * 32 + (lane & 31);
;         T[ml * 136 + nl] = f2bf(f(m0 + ml, n0 + nl, acc[mt][nt][i]));
;       }
;   __syncthreads();
	ds_read_b128 v[66:69], v132 offset:18432
	ds_read_b128 v[70:73], v131 offset:55296
	ds_read_b128 v[74:77], v131 offset:59904
	s_waitcnt lgkmcnt(1)
	v_mfma_f32_32x32x16_bf16 v[50:65], v[66:69], v[70:73], v[50:65]
	s_waitcnt lgkmcnt(0)
	v_mfma_f32_32x32x16_bf16 v[34:49], v[66:69], v[74:77], v[34:49]
	ds_read_b128 v[66:69], v132 offset:23040
	s_waitcnt lgkmcnt(0)
	v_mfma_f32_32x32x16_bf16 v[18:33], v[66:69], v[70:73], v[18:33]
	ds_read_b128 v[70:73], v132 offset:18464
	ds_read_b128 v[78:81], v131 offset:55328
	ds_read_b128 v[82:85], v131 offset:59936
	ds_read_b128 v[86:89], v132 offset:23072
	v_mfma_f32_32x32x16_bf16 v[2:17], v[66:69], v[74:77], v[2:17]
	s_waitcnt lgkmcnt(2)
	v_mfma_f32_32x32x16_bf16 v[50:65], v[70:73], v[78:81], v[50:65]
	s_waitcnt lgkmcnt(1)
	v_mfma_f32_32x32x16_bf16 v[34:49], v[70:73], v[82:85], v[34:49]
	s_waitcnt lgkmcnt(0)
	v_mfma_f32_32x32x16_bf16 v[18:33], v[86:89], v[78:81], v[18:33]
	ds_read_b128 v[66:69], v132 offset:18496
	ds_read_b128 v[70:73], v132 offset:23104
	ds_read_b128 v[74:77], v131 offset:55360
	ds_read_b128 v[78:81], v131 offset:59968
	v_mfma_f32_32x32x16_bf16 v[2:17], v[86:89], v[82:85], v[2:17]
	s_waitcnt lgkmcnt(1)
	v_mfma_f32_32x32x16_bf16 v[50:65], v[66:69], v[74:77], v[50:65]
	s_waitcnt lgkmcnt(0)
	v_mfma_f32_32x32x16_bf16 v[34:49], v[66:69], v[78:81], v[34:49]
	v_mfma_f32_32x32x16_bf16 v[18:33], v[70:73], v[74:77], v[18:33]
	ds_read_b128 v[66:69], v132 offset:18528
	ds_read_b128 v[74:77], v132 offset:23136
	ds_read_b128 v[82:85], v131 offset:55392
	ds_read_b128 v[86:89], v131 offset:60000
	v_mfma_f32_32x32x16_bf16 v[2:17], v[70:73], v[78:81], v[2:17]
	s_waitcnt lgkmcnt(1)
	v_mfma_f32_32x32x16_bf16 v[50:65], v[66:69], v[82:85], v[50:65]
	s_waitcnt lgkmcnt(0)
	v_mfma_f32_32x32x16_bf16 v[34:49], v[66:69], v[86:89], v[34:49]
	v_mfma_f32_32x32x16_bf16 v[18:33], v[74:77], v[82:85], v[18:33]
	v_mfma_f32_32x32x16_bf16 v[2:17], v[74:77], v[86:89], v[2:17]
	s_ashr_i32 s1, s0, 31
	v_mov_b32_e32 v66, v202
	s_barrier
	s_ashr_i32 s53, s52, 31
	s_lshl_b64 s[0:1], s[0:1], 22
	s_add_u32 s30, s40, s0
	v_lshrrev_b32_e32 v0, 1, v66
	v_and_b32_e32 v0, 0xfffffc0, v0
	v_lshrrev_b32_e32 v67, 3, v66
	s_addc_u32 s31, s41, s1
	s_lshl_b64 s[0:1], s[52:53], 8
	v_and_or_b32 v0, v67, 4, v0
	s_add_u32 s0, s30, s0
	v_and_b32_e32 v67, 0x5f, v66
	v_mul_lo_u32 v0, v0, s51
	v_cvt_pk_bf16_f32 v50, v50, s0
	v_lshl_add_u32 v0, v67, 1, v0
	v_cvt_pk_bf16_f32 v34, v34, s0
	v_cvt_pk_bf16_f32 v18, v18, s0
	v_cvt_pk_bf16_f32 v2, v2, s0
	ds_write_b16 v0, v50
	v_cvt_pk_bf16_f32 v50, v51, s0
	ds_write_b16 v0, v34 offset:64
	v_cvt_pk_bf16_f32 v34, v35, s0
	ds_write_b16 v0, v18 offset:8704
	v_cvt_pk_bf16_f32 v18, v19, s0
	ds_write_b16 v0, v2 offset:8768
	v_cvt_pk_bf16_f32 v2, v3, s0
	ds_write_b16 v0, v50 offset:272
	v_cvt_pk_bf16_f32 v50, v52, s0
	ds_write_b16 v0, v34 offset:336
	v_cvt_pk_bf16_f32 v34, v36, s0
	ds_write_b16 v0, v18 offset:8976
	v_cvt_pk_bf16_f32 v18, v20, s0
	ds_write_b16 v0, v2 offset:9040
	v_cvt_pk_bf16_f32 v2, v4, s0
	ds_write_b16 v0, v50 offset:544
	v_cvt_pk_bf16_f32 v50, v53, s0
	ds_write_b16 v0, v34 offset:608
	v_cvt_pk_bf16_f32 v34, v37, s0
	ds_write_b16 v0, v18 offset:9248
	v_cvt_pk_bf16_f32 v18, v21, s0
	ds_write_b16 v0, v2 offset:9312
	v_cvt_pk_bf16_f32 v2, v5, s0
	ds_write_b16 v0, v50 offset:816
	v_cvt_pk_bf16_f32 v50, v54, s0
	ds_write_b16 v0, v34 offset:880
	v_cvt_pk_bf16_f32 v34, v38, s0
	ds_write_b16 v0, v18 offset:9520
	v_cvt_pk_bf16_f32 v18, v22, s0
	ds_write_b16 v0, v2 offset:9584
	v_cvt_pk_bf16_f32 v2, v6, s0
	ds_write_b16 v0, v50 offset:2176
	v_cvt_pk_bf16_f32 v50, v55, s0
	ds_write_b16 v0, v34 offset:2240
	v_cvt_pk_bf16_f32 v34, v39, s0
	ds_write_b16 v0, v18 offset:10880
	v_cvt_pk_bf16_f32 v18, v23, s0
	ds_write_b16 v0, v2 offset:10944
	v_cvt_pk_bf16_f32 v2, v7, s0
	ds_write_b16 v0, v50 offset:2448
	v_cvt_pk_bf16_f32 v50, v56, s0
	ds_write_b16 v0, v34 offset:2512
	v_cvt_pk_bf16_f32 v34, v40, s0
	ds_write_b16 v0, v18 offset:11152
	v_cvt_pk_bf16_f32 v18, v24, s0
	ds_write_b16 v0, v2 offset:11216
	v_cvt_pk_bf16_f32 v2, v8, s0
	ds_write_b16 v0, v50 offset:2720
	v_cvt_pk_bf16_f32 v50, v57, s0
	ds_write_b16 v0, v34 offset:2784
	v_cvt_pk_bf16_f32 v34, v41, s0
	ds_write_b16 v0, v18 offset:11424
	v_cvt_pk_bf16_f32 v18, v25, s0
	ds_write_b16 v0, v2 offset:11488
	v_cvt_pk_bf16_f32 v2, v9, s0
	ds_write_b16 v0, v50 offset:2992
	v_cvt_pk_bf16_f32 v50, v58, s0
	ds_write_b16 v0, v34 offset:3056
	v_cvt_pk_bf16_f32 v34, v42, s0
	ds_write_b16 v0, v18 offset:11696
	v_cvt_pk_bf16_f32 v18, v26, s0
	ds_write_b16 v0, v2 offset:11760
	v_cvt_pk_bf16_f32 v2, v10, s0
	ds_write_b16 v0, v50 offset:4352
	v_cvt_pk_bf16_f32 v50, v59, s0
	ds_write_b16 v0, v34 offset:4416
	v_cvt_pk_bf16_f32 v34, v43, s0
	ds_write_b16 v0, v18 offset:13056
	v_cvt_pk_bf16_f32 v18, v27, s0
	ds_write_b16 v0, v2 offset:13120
	v_cvt_pk_bf16_f32 v2, v11, s0
	ds_write_b16 v0, v50 offset:4624
	v_cvt_pk_bf16_f32 v50, v60, s0
	ds_write_b16 v0, v34 offset:4688
	v_cvt_pk_bf16_f32 v34, v44, s0
	ds_write_b16 v0, v18 offset:13328
	v_cvt_pk_bf16_f32 v18, v28, s0
	ds_write_b16 v0, v2 offset:13392
	v_cvt_pk_bf16_f32 v2, v12, s0
	ds_write_b16 v0, v50 offset:4896
	v_cvt_pk_bf16_f32 v50, v61, s0
	ds_write_b16 v0, v34 offset:4960
	v_cvt_pk_bf16_f32 v34, v45, s0
	ds_write_b16 v0, v18 offset:13600
	v_cvt_pk_bf16_f32 v18, v29, s0
	ds_write_b16 v0, v2 offset:13664
	v_cvt_pk_bf16_f32 v2, v13, s0
	ds_write_b16 v0, v50 offset:5168
	v_cvt_pk_bf16_f32 v50, v62, s0
	ds_write_b16 v0, v34 offset:5232
	v_cvt_pk_bf16_f32 v34, v46, s0
	ds_write_b16 v0, v18 offset:13872
	v_cvt_pk_bf16_f32 v18, v30, s0
	ds_write_b16 v0, v2 offset:13936
	v_cvt_pk_bf16_f32 v2, v14, s0
	ds_write_b16 v0, v50 offset:6528
	v_cvt_pk_bf16_f32 v50, v63, s0
	ds_write_b16 v0, v34 offset:6592
	v_cvt_pk_bf16_f32 v34, v47, s0
	ds_write_b16 v0, v18 offset:15232
	v_cvt_pk_bf16_f32 v18, v31, s0
	ds_write_b16 v0, v2 offset:15296
	v_cvt_pk_bf16_f32 v2, v15, s0
	ds_write_b16 v0, v50 offset:6800
	v_cvt_pk_bf16_f32 v50, v64, s0
	ds_write_b16 v0, v34 offset:6864
	v_cvt_pk_bf16_f32 v34, v48, s0
	ds_write_b16 v0, v18 offset:15504
	v_cvt_pk_bf16_f32 v18, v32, s0
	ds_write_b16 v0, v2 offset:15568
	v_cvt_pk_bf16_f32 v2, v16, s0
	ds_write_b16 v0, v50 offset:7072
	v_cvt_pk_bf16_f32 v50, v65, s0
	ds_write_b16 v0, v34 offset:7136
	v_cvt_pk_bf16_f32 v34, v49, s0
	ds_write_b16 v0, v18 offset:15776
	v_cvt_pk_bf16_f32 v18, v33, s0
	ds_write_b16 v0, v2 offset:15840
	v_cvt_pk_bf16_f32 v2, v17, s0
	ds_write_b16 v0, v50 offset:7344
	ds_write_b16 v0, v34 offset:7408
	ds_write_b16 v0, v18 offset:16048
	ds_write_b16 v0, v2 offset:16112
	v_lshlrev_b32_e32 v0, 4, v66
	v_ashrrev_i32_e32 v2, 4, v66
	s_addc_u32 s1, s31, s1
	v_and_b32_e32 v0, 0xf0, v0
	v_ashrrev_i32_e32 v3, 31, v2
	v_lshl_add_u64 v[10:11], s[0:1], 0, v[0:1]
	v_mad_u64_u32 v[4:5], s[0:1], v2, s51, v[0:1]
	v_lshlrev_b64 v[2:3], 8, v[2:3]
	v_add_u32_e32 v6, 0x100, v66
	s_waitcnt lgkmcnt(0)
	s_barrier
; template <class F>
; DI void epi_bf16_tile(const f32x16 (&acc)[2][2], int m0, int n0, u16* dst0, long ld, char* smem, F f) {
;     ...
; #pragma unroll
;   for (int j = 0; j < 8; j++) {
;     const int idx = tid + 256 * j, row = idx >> 4, ch = idx & 15;
;     *(uint4*)(dst0 + (long)row * ld + ch * 8) = *(const uint4*)(T + row * 136 + ch * 8);
;   }
;   __syncthreads();
	v_lshl_add_u64 v[12:13], v[10:11], 0, v[2:3]
	ds_read_b128 v[2:5], v4
	v_ashrrev_i32_e32 v14, 4, v6
	v_mad_u64_u32 v[6:7], s[0:1], v14, s51, v[0:1]
	ds_read_b128 v[6:9], v6
	v_ashrrev_i32_e32 v15, 31, v14
	s_waitcnt lgkmcnt(1)
	global_store_dwordx4 v[12:13], v[2:5], off
	s_nop 1
	v_lshlrev_b64 v[2:3], 8, v[14:15]
	v_lshl_add_u64 v[2:3], v[10:11], 0, v[2:3]
	s_waitcnt lgkmcnt(0)
	global_store_dwordx4 v[2:3], v[6:9], off
	v_add_u32_e32 v2, 0x200, v66
	v_ashrrev_i32_e32 v2, 4, v2
	v_ashrrev_i32_e32 v3, 31, v2
	v_mad_u64_u32 v[4:5], s[0:1], v2, s51, v[0:1]
	v_lshlrev_b64 v[2:3], 8, v[2:3]
	v_add_u32_e32 v6, 0x300, v66
	v_lshl_add_u64 v[12:13], v[10:11], 0, v[2:3]
	ds_read_b128 v[2:5], v4
	v_ashrrev_i32_e32 v14, 4, v6
	v_mad_u64_u32 v[6:7], s[0:1], v14, s51, v[0:1]
	ds_read_b128 v[6:9], v6
	v_ashrrev_i32_e32 v15, 31, v14
	s_waitcnt lgkmcnt(1)
	global_store_dwordx4 v[12:13], v[2:5], off
	s_nop 1
	v_lshlrev_b64 v[2:3], 8, v[14:15]
	v_lshl_add_u64 v[2:3], v[10:11], 0, v[2:3]
	s_waitcnt lgkmcnt(0)
	global_store_dwordx4 v[2:3], v[6:9], off
	v_add_u32_e32 v2, 0x400, v66
	v_ashrrev_i32_e32 v2, 4, v2
	v_ashrrev_i32_e32 v3, 31, v2
	v_mad_u64_u32 v[4:5], s[0:1], v2, s51, v[0:1]
	v_lshlrev_b64 v[2:3], 8, v[2:3]
	v_add_u32_e32 v6, 0x500, v66
	v_lshl_add_u64 v[12:13], v[10:11], 0, v[2:3]
	ds_read_b128 v[2:5], v4
	v_ashrrev_i32_e32 v14, 4, v6
	v_mad_u64_u32 v[6:7], s[0:1], v14, s51, v[0:1]
	ds_read_b128 v[6:9], v6
	v_ashrrev_i32_e32 v15, 31, v14
	s_waitcnt lgkmcnt(1)
	global_store_dwordx4 v[12:13], v[2:5], off
	s_nop 1
	v_lshlrev_b64 v[2:3], 8, v[14:15]
	v_lshl_add_u64 v[2:3], v[10:11], 0, v[2:3]
	s_waitcnt lgkmcnt(0)
	global_store_dwordx4 v[2:3], v[6:9], off
	v_add_u32_e32 v2, 0x600, v66
	v_ashrrev_i32_e32 v2, 4, v2
	v_ashrrev_i32_e32 v3, 31, v2
	v_mad_u64_u32 v[4:5], s[0:1], v2, s51, v[0:1]
	v_lshlrev_b64 v[2:3], 8, v[2:3]
	v_add_u32_e32 v6, 0x700, v66
	v_lshl_add_u64 v[12:13], v[10:11], 0, v[2:3]
	ds_read_b128 v[2:5], v4
	v_ashrrev_i32_e32 v14, 4, v6
	v_mad_u64_u32 v[6:7], s[0:1], v14, s51, v[0:1]
	ds_read_b128 v[6:9], v6
	v_ashrrev_i32_e32 v15, 31, v14
	s_waitcnt lgkmcnt(1)
	global_store_dwordx4 v[12:13], v[2:5], off
	s_nop 1
	v_lshlrev_b64 v[2:3], 8, v[14:15]
	v_lshl_add_u64 v[2:3], v[10:11], 0, v[2:3]
	s_waitcnt lgkmcnt(0)
	global_store_dwordx4 v[2:3], v[6:9], off
	s_barrier

; #define G_LOAD(S, kt_) do { G_LD1(S##a0, S##b0, 0, kt_); G_LD1(S##a1, S##b1, 1, kt_); G_LD1(S##a2, S##b2, 2, kt_); G_LD1(S##a3, S##b3, 3, kt_); } while (0)
; #define G_STORE(S, buf_) do { G_ST1(S##a0, S##b0, 0, buf_); G_ST1(S##a1, S##b1, 1, buf_); G_ST1(S##a2, S##b2, 2, buf_); G_ST1(S##a3, S##b3, 3, buf_); } while (0)
; template <class AL, class BL>
; DI void gemm_core(AL al, BL bl, int m0, int n0, int K, char* smem, f32x16 (&acc)[2][2]) {
;     ...
;   const int srow = tid >> 3, sch = tid & 7;
;     ...
;   G_LOAD(x, 0);
;   G_STORE(x, 0);
;   G_LOAD(x, 1);
;   G_LOAD(y, (nk > 2) ? 2 : 1);
;   __syncthreads();
; __global__ void __launch_bounds__(256, 2) fwd_megakernel(Params p) {
;     ...
;         if (t < e1) {
;           const int tm = t % (NT / 128), tn = t / (NT / 128), m0 = tm * 128, n0 = tn * 128;
;           gemm_core([=](int m, int k) { return cqn + (long)m * 384 + k; },
;                     [=](int n, int k) { return wuqT + (long)n * 384 + k; }, m0, n0, 384, smem, acc);
.LBB0_565:
	s_mul_hi_i32 s0, s73, 0x38e38e39
	s_lshr_b32 s1, s0, 31
	s_ashr_i32 s0, s0, 5
	s_add_i32 s0, s0, s1
	v_mov_b32_e32 v34, v202
	s_lshl_b32 s1, s0, 7
	s_mulk_i32 s0, 0x4800
	v_ashrrev_i32_e32 v35, 3, v34
	v_subrev_u32_e32 v0, s0, v35
	v_add_u32_e32 v28, s72, v0
	v_add_u32_e32 v0, 0xffffffa0, v28
	v_mov_b64_e32 v[26:27], s[20:21]
	v_mad_i64_i32 v[2:3], s[30:31], v0, s84, v[26:27]
	v_lshlrev_b32_e32 v0, 4, v34
	v_add_u32_e32 v32, s1, v35
	v_mov_b64_e32 v[30:31], s[22:23]
	v_and_b32_e32 v0, 0x70, v0
	v_mad_i64_i32 v[6:7], s[30:31], v32, s84, v[30:31]
	v_subrev_u32_e32 v10, 64, v28
	s_waitcnt vmcnt(4)
	v_lshl_add_u64 v[146:147], v[2:3], 0, v[0:1]
	s_waitcnt vmcnt(3)
	v_lshl_add_u64 v[148:149], v[6:7], 0, v[0:1]
	v_mad_i64_i32 v[10:11], s[30:31], v10, s84, v[26:27]
	v_add_u32_e32 v14, 32, v32
	global_load_dwordx4 v[2:5], v[146:147], off
	global_load_dwordx4 v[6:9], v[148:149], off
	v_lshl_add_u64 v[142:143], v[10:11], 0, v[0:1]
	v_mad_i64_i32 v[14:15], s[30:31], v14, s84, v[30:31]
	v_subrev_u32_e32 v18, 32, v28
	global_load_dwordx4 v[10:13], v[142:143], off
	v_lshl_add_u64 v[144:145], v[14:15], 0, v[0:1]
	v_mad_i64_i32 v[18:19], s[30:31], v18, s84, v[26:27]
	v_add_u32_e32 v22, 64, v32
	global_load_dwordx4 v[14:17], v[144:145], off
	v_lshl_add_u64 v[138:139], v[18:19], 0, v[0:1]
	v_mad_i64_i32 v[22:23], s[30:31], v22, s84, v[30:31]
	global_load_dwordx4 v[18:21], v[138:139], off
	v_lshl_add_u64 v[140:141], v[22:23], 0, v[0:1]
	v_mad_i64_i32 v[26:27], s[30:31], v28, s84, v[26:27]
	v_add_u32_e32 v32, 0x60, v32
	global_load_dwordx4 v[22:25], v[140:141], off
	v_lshl_add_u64 v[134:135], v[26:27], 0, v[0:1]
	v_mad_i64_i32 v[30:31], s[30:31], v32, s84, v[30:31]
	global_load_dwordx4 v[26:29], v[134:135], off
	v_lshl_add_u64 v[136:137], v[30:31], 0, v[0:1]
	global_load_dwordx4 v[30:33], v[136:137], off
	v_mad_u64_u32 v[130:131], s[30:31], v35, s82, v[0:1]
	v_add_u32_e32 v0, 0x9000, v130
	global_load_dwordx4 v[122:125], v[146:147], off offset:128
	global_load_dwordx4 v[126:129], v[148:149], off offset:128
	global_load_dwordx4 v[114:117], v[142:143], off offset:128
	global_load_dwordx4 v[118:121], v[144:145], off offset:128
	global_load_dwordx4 v[106:109], v[138:139], off offset:128
	global_load_dwordx4 v[110:113], v[140:141], off offset:128
	global_load_dwordx4 v[98:101], v[134:135], off offset:128
	global_load_dwordx4 v[102:105], v[136:137], off offset:128
	global_load_dwordx4 v[90:93], v[146:147], off offset:256
	global_load_dwordx4 v[94:97], v[148:149], off offset:256
	global_load_dwordx4 v[82:85], v[142:143], off offset:256
	global_load_dwordx4 v[86:89], v[144:145], off offset:256
	global_load_dwordx4 v[74:77], v[138:139], off offset:256
	global_load_dwordx4 v[78:81], v[140:141], off offset:256
	global_load_dwordx4 v[66:69], v[134:135], off offset:256
	global_load_dwordx4 v[70:73], v[136:137], off offset:256
	s_waitcnt vmcnt(23)
	ds_write_b128 v130, v[2:5]
	s_waitcnt vmcnt(22)
	ds_write_b128 v130, v[6:9] offset:36864
	s_waitcnt vmcnt(21)
	ds_write_b128 v130, v[10:13] offset:4608
	s_waitcnt vmcnt(20)
	ds_write_b128 v130, v[14:17] offset:41472
	s_waitcnt vmcnt(19)
	ds_write_b128 v130, v[18:21] offset:9216
	s_waitcnt vmcnt(18)
	ds_write_b128 v130, v[22:25] offset:46080
	s_waitcnt vmcnt(17)
	ds_write_b128 v130, v[26:29] offset:13824
	s_waitcnt vmcnt(16)
	ds_write_b128 v130, v[30:33] offset:50688
	v_lshrrev_b32_e32 v2, 1, v34
	v_and_b32_e32 v3, 31, v34
	v_and_or_b32 v3, v2, s83, v3
	v_and_b32_e32 v2, 16, v2
	v_mad_u64_u32 v[132:133], s[30:31], v3, s82, v[2:3]
	v_and_b32_e32 v3, 0x5f, v34
	v_mul_u32_u24_e32 v3, 0x48, v3
	s_waitcnt lgkmcnt(0)
	s_barrier
	v_lshl_add_u32 v131, v3, 1, v2
	ds_read_b128 v[2:5], v132 offset:4608
	ds_read_b128 v[6:9], v131 offset:41472
	ds_read_b128 v[10:13], v132
	ds_read_b128 v[150:153], v132 offset:32
	ds_read_b128 v[154:157], v132 offset:4640
	ds_read_b128 v[14:17], v131 offset:36864
	ds_read_b128 v[158:161], v131 offset:36896
	ds_read_b128 v[162:165], v131 offset:41504
	s_waitcnt lgkmcnt(2)
	v_mfma_f32_32x32x16_bf16 v[34:49], v[10:13], v[14:17], 0
	s_waitcnt vmcnt(15)
	ds_write_b128 v130, v[122:125] offset:18432
	s_waitcnt vmcnt(14)
	ds_write_b128 v130, v[126:129] offset:55296
	global_load_dwordx4 v[122:125], v[146:147], off offset:384
	global_load_dwordx4 v[126:129], v[148:149], off offset:384
	v_mfma_f32_32x32x16_bf16 v[50:65], v[10:13], v[6:9], 0
	v_mfma_f32_32x32x16_bf16 v[18:33], v[2:5], v[14:17], 0
	v_mfma_f32_32x32x16_bf16 v[2:17], v[2:5], v[6:9], 0
	s_waitcnt lgkmcnt(3)
	v_mfma_f32_32x32x16_bf16 v[34:49], v[150:153], v[158:161], v[34:49]
	s_waitcnt lgkmcnt(2)
	v_mfma_f32_32x32x16_bf16 v[50:65], v[150:153], v[162:165], v[50:65]
	v_mfma_f32_32x32x16_bf16 v[18:33], v[154:157], v[158:161], v[18:33]
	global_load_dwordx4 v[150:153], v[142:143], off offset:384
	global_load_dwordx4 v[158:161], v[144:145], off offset:384
	ds_read_b128 v[166:169], v132 offset:64
	ds_read_b128 v[170:173], v132 offset:4672
	ds_read_b128 v[174:177], v131 offset:36928
	ds_read_b128 v[178:181], v131 offset:41536
	s_waitcnt vmcnt(17)
	ds_write_b128 v130, v[114:117] offset:23040
	s_waitcnt vmcnt(16)
	ds_write_b128 v130, v[118:121] offset:59904
	v_mfma_f32_32x32x16_bf16 v[2:17], v[154:157], v[162:165], v[2:17]
	global_load_dwordx4 v[114:117], v[138:139], off offset:384
	global_load_dwordx4 v[118:121], v[140:141], off offset:384
	s_waitcnt lgkmcnt(3)
	v_mfma_f32_32x32x16_bf16 v[34:49], v[166:169], v[174:177], v[34:49]
	s_waitcnt lgkmcnt(2)
	v_mfma_f32_32x32x16_bf16 v[50:65], v[166:169], v[178:181], v[50:65]
	v_mfma_f32_32x32x16_bf16 v[18:33], v[170:173], v[174:177], v[18:33]
	ds_read_b128 v[154:157], v132 offset:96
	ds_read_b128 v[162:165], v132 offset:4704
	ds_read_b128 v[166:169], v131 offset:36960
	ds_read_b128 v[174:177], v131 offset:41568
	s_waitcnt vmcnt(17)
	ds_write_b128 v130, v[106:109] offset:27648
	s_waitcnt vmcnt(16)
	ds_write_b128 v130, v[110:113] offset:64512
	v_mfma_f32_32x32x16_bf16 v[2:17], v[170:173], v[178:181], v[2:17]
	global_load_dwordx4 v[106:109], v[134:135], off offset:384
	global_load_dwordx4 v[110:113], v[136:137], off offset:384
	s_waitcnt lgkmcnt(3)
	v_mfma_f32_32x32x16_bf16 v[34:49], v[154:157], v[166:169], v[34:49]
	s_waitcnt vmcnt(17)
	ds_write_b128 v130, v[98:101] offset:32256
	s_waitcnt vmcnt(16)
	ds_write_b128 v0, v[102:105] offset:32256
	s_waitcnt lgkmcnt(4)
	v_mfma_f32_32x32x16_bf16 v[50:65], v[154:157], v[174:177], v[50:65]
	v_mfma_f32_32x32x16_bf16 v[18:33], v[162:165], v[166:169], v[18:33]
	v_mfma_f32_32x32x16_bf16 v[2:17], v[162:165], v[174:177], v[2:17]
	s_waitcnt lgkmcnt(0)
	s_barrier
; #define G_LOAD(S, kt_) do { G_LD1(S##a0, S##b0, 0, kt_); G_LD1(S##a1, S##b1, 1, kt_); G_LD1(S##a2, S##b2, 2, kt_); G_LD1(S##a3, S##b3, 3, kt_); } while (0)
; #define G_STORE(S, buf_) do { G_ST1(S##a0, S##b0, 0, buf_); G_ST1(S##a1, S##b1, 1, buf_); G_ST1(S##a2, S##b2, 2, buf_); G_ST1(S##a3, S##b3, 3, buf_); } while (0)
; template <class AL, class BL>
; DI void gemm_core(AL al, BL bl, int m0, int n0, int K, char* smem, f32x16 (&acc)[2][2]) {
;     ...
;   G_LOAD(x, 0);
;   G_STORE(x, 0);
;   G_LOAD(x, 1);
;   G_LOAD(y, (nk > 2) ? 2 : 1);
;   __syncthreads();
;   for (int kt = 0; kt < nk; kt += 2) {
;     G_TILE(0, x, true, (kt + 3 < nk), kt + 3);
;     __syncthreads();
;     G_TILE(1, y, (kt + 2 < nk), (kt + 4 < nk), kt + 4);
;     __syncthreads();
	ds_read_b128 v[98:101], v132 offset:18432
	ds_read_b128 v[102:105], v131 offset:55296
	ds_read_b128 v[154:157], v132 offset:18464
	ds_read_b128 v[162:165], v131 offset:55328
	ds_read_b128 v[166:169], v131 offset:59904
	ds_read_b128 v[170:173], v131 offset:59936
	s_waitcnt lgkmcnt(4)
	v_mfma_f32_32x32x16_bf16 v[34:49], v[98:101], v[102:105], v[34:49]
	s_waitcnt lgkmcnt(1)
	v_mfma_f32_32x32x16_bf16 v[50:65], v[98:101], v[166:169], v[50:65]
	ds_read_b128 v[98:101], v132 offset:23040
	ds_read_b128 v[174:177], v132 offset:23072
	s_waitcnt lgkmcnt(1)
	v_mfma_f32_32x32x16_bf16 v[18:33], v[98:101], v[102:105], v[18:33]
	global_load_dwordx4 v[102:105], v[146:147], off offset:512
	global_load_dwordx4 v[178:181], v[148:149], off offset:512
	s_waitcnt vmcnt(17)
	ds_write_b128 v130, v[90:93]
	s_waitcnt vmcnt(16)
	ds_write_b128 v130, v[94:97] offset:36864
	v_mfma_f32_32x32x16_bf16 v[2:17], v[98:101], v[166:169], v[2:17]
	global_load_dwordx4 v[90:93], v[142:143], off offset:512
	global_load_dwordx4 v[94:97], v[144:145], off offset:512
	v_mfma_f32_32x32x16_bf16 v[34:49], v[154:157], v[162:165], v[34:49]
	v_mfma_f32_32x32x16_bf16 v[50:65], v[154:157], v[170:173], v[50:65]
	s_waitcnt lgkmcnt(2)
	v_mfma_f32_32x32x16_bf16 v[18:33], v[174:177], v[162:165], v[18:33]
	ds_read_b128 v[98:101], v132 offset:18496
	ds_read_b128 v[154:157], v132 offset:23104
	ds_read_b128 v[162:165], v131 offset:55360
	ds_read_b128 v[166:169], v131 offset:59968
	s_waitcnt vmcnt(17)
	ds_write_b128 v130, v[82:85] offset:4608
	s_waitcnt vmcnt(16)
	ds_write_b128 v130, v[86:89] offset:41472
	v_mfma_f32_32x32x16_bf16 v[2:17], v[174:177], v[170:173], v[2:17]
	global_load_dwordx4 v[82:85], v[138:139], off offset:512
	global_load_dwordx4 v[86:89], v[140:141], off offset:512
	s_waitcnt lgkmcnt(3)
	v_mfma_f32_32x32x16_bf16 v[34:49], v[98:101], v[162:165], v[34:49]
	s_waitcnt lgkmcnt(2)
	v_mfma_f32_32x32x16_bf16 v[50:65], v[98:101], v[166:169], v[50:65]
	v_mfma_f32_32x32x16_bf16 v[18:33], v[154:157], v[162:165], v[18:33]
	ds_read_b128 v[98:101], v132 offset:18528
	ds_read_b128 v[162:165], v132 offset:23136
	ds_read_b128 v[170:173], v131 offset:55392
	ds_read_b128 v[174:177], v131 offset:60000
	s_waitcnt vmcnt(17)
	ds_write_b128 v130, v[74:77] offset:9216
	s_waitcnt vmcnt(16)
	ds_write_b128 v130, v[78:81] offset:46080
	v_mfma_f32_32x32x16_bf16 v[2:17], v[154:157], v[166:169], v[2:17]
	global_load_dwordx4 v[74:77], v[134:135], off offset:512
	global_load_dwordx4 v[78:81], v[136:137], off offset:512
	s_waitcnt lgkmcnt(3)
	v_mfma_f32_32x32x16_bf16 v[34:49], v[98:101], v[170:173], v[34:49]
	s_waitcnt vmcnt(17)
	ds_write_b128 v130, v[66:69] offset:13824
	s_waitcnt vmcnt(16)
	ds_write_b128 v130, v[70:73] offset:50688
	s_waitcnt lgkmcnt(4)
	v_mfma_f32_32x32x16_bf16 v[50:65], v[98:101], v[174:177], v[50:65]
	v_mfma_f32_32x32x16_bf16 v[18:33], v[162:165], v[170:173], v[18:33]
	v_mfma_f32_32x32x16_bf16 v[2:17], v[162:165], v[174:177], v[2:17]
	s_waitcnt lgkmcnt(0)
	s_barrier
	ds_read_b128 v[66:69], v132
	ds_read_b128 v[70:73], v131 offset:36864
	ds_read_b128 v[98:101], v131 offset:41472
	s_waitcnt lgkmcnt(1)
	v_mfma_f32_32x32x16_bf16 v[34:49], v[66:69], v[70:73], v[34:49]
	s_waitcnt lgkmcnt(0)
	v_mfma_f32_32x32x16_bf16 v[50:65], v[66:69], v[98:101], v[50:65]
	ds_read_b128 v[66:69], v132 offset:4608
	s_waitcnt lgkmcnt(0)
	v_mfma_f32_32x32x16_bf16 v[18:33], v[66:69], v[70:73], v[18:33]
	global_load_dwordx4 v[70:73], v[146:147], off offset:640
	s_nop 0
	global_load_dwordx4 v[146:149], v[148:149], off offset:640
	ds_read_b128 v[154:157], v132 offset:32
	ds_read_b128 v[162:165], v131 offset:36896
	ds_read_b128 v[166:169], v131 offset:41504
	ds_read_b128 v[170:173], v132 offset:4640
	s_waitcnt vmcnt(17)
	ds_write_b128 v130, v[122:125] offset:18432
	s_waitcnt vmcnt(16)
	ds_write_b128 v130, v[126:129] offset:55296
	v_mfma_f32_32x32x16_bf16 v[2:17], v[66:69], v[98:101], v[2:17]
	global_load_dwordx4 v[66:69], v[142:143], off offset:640
	global_load_dwordx4 v[98:101], v[144:145], off offset:640
	s_waitcnt lgkmcnt(4)
	v_mfma_f32_32x32x16_bf16 v[34:49], v[154:157], v[162:165], v[34:49]
	s_waitcnt lgkmcnt(3)
	v_mfma_f32_32x32x16_bf16 v[50:65], v[154:157], v[166:169], v[50:65]
	ds_read_b128 v[122:125], v132 offset:64
	ds_read_b128 v[126:129], v132 offset:4672
	ds_read_b128 v[142:145], v131 offset:36928
	ds_read_b128 v[154:157], v131 offset:41536
	s_waitcnt vmcnt(17)
	ds_write_b128 v130, v[150:153] offset:23040
	s_waitcnt vmcnt(16)
	ds_write_b128 v130, v[158:161] offset:59904
	s_waitcnt lgkmcnt(8)
	v_mfma_f32_32x32x16_bf16 v[18:33], v[170:173], v[162:165], v[18:33]
	v_mfma_f32_32x32x16_bf16 v[2:17], v[170:173], v[166:169], v[2:17]
	s_waitcnt lgkmcnt(3)
	v_mfma_f32_32x32x16_bf16 v[34:49], v[122:125], v[142:145], v[34:49]
	s_waitcnt lgkmcnt(2)
	v_mfma_f32_32x32x16_bf16 v[50:65], v[122:125], v[154:157], v[50:65]
	global_load_dwordx4 v[122:125], v[138:139], off offset:640
	s_nop 0
	global_load_dwordx4 v[138:141], v[140:141], off offset:640
	v_mfma_f32_32x32x16_bf16 v[18:33], v[126:129], v[142:145], v[18:33]
	ds_read_b128 v[142:145], v132 offset:96
	ds_read_b128 v[150:153], v132 offset:4704
	ds_read_b128 v[158:161], v131 offset:36960
	ds_read_b128 v[162:165], v131 offset:41568
	s_waitcnt vmcnt(17)
	ds_write_b128 v130, v[114:117] offset:27648
	s_waitcnt vmcnt(16)
	ds_write_b128 v130, v[118:121] offset:64512
	v_mfma_f32_32x32x16_bf16 v[2:17], v[126:129], v[154:157], v[2:17]
	global_load_dwordx4 v[114:117], v[134:135], off offset:640
	global_load_dwordx4 v[118:121], v[136:137], off offset:640
	s_waitcnt lgkmcnt(3)
	v_mfma_f32_32x32x16_bf16 v[34:49], v[142:145], v[158:161], v[34:49]
	s_waitcnt vmcnt(17)
	ds_write_b128 v130, v[106:109] offset:32256
	s_waitcnt vmcnt(16)
	ds_write_b128 v0, v[110:113] offset:32256
	s_waitcnt lgkmcnt(4)
	v_mfma_f32_32x32x16_bf16 v[50:65], v[142:145], v[162:165], v[50:65]
	v_mfma_f32_32x32x16_bf16 v[18:33], v[150:153], v[158:161], v[18:33]
	v_mfma_f32_32x32x16_bf16 v[2:17], v[150:153], v[162:165], v[2:17]
	s_waitcnt lgkmcnt(0)
	s_barrier
; #define G_LOAD(S, kt_) do { G_LD1(S##a0, S##b0, 0, kt_); G_LD1(S##a1, S##b1, 1, kt_); G_LD1(S##a2, S##b2, 2, kt_); G_LD1(S##a3, S##b3, 3, kt_); } while (0)
; #define G_STORE(S, buf_) do { G_ST1(S##a0, S##b0, 0, buf_); G_ST1(S##a1, S##b1, 1, buf_); G_ST1(S##a2, S##b2, 2, buf_); G_ST1(S##a3, S##b3, 3, buf_); } while (0)
; template <class AL, class BL>
; DI void gemm_core(AL al, BL bl, int m0, int n0, int K, char* smem, f32x16 (&acc)[2][2]) {
;     ...
;   G_LOAD(x, 0);
;   G_STORE(x, 0);
;   G_LOAD(x, 1);
;   G_LOAD(y, (nk > 2) ? 2 : 1);
;   __syncthreads();
;   for (int kt = 0; kt < nk; kt += 2) {
;     G_TILE(0, x, true, (kt + 3 < nk), kt + 3);
;     __syncthreads();
;     G_TILE(1, y, (kt + 2 < nk), (kt + 4 < nk), kt + 4);
;     __syncthreads();
	ds_read_b128 v[106:109], v132 offset:18432
	ds_read_b128 v[110:113], v131 offset:55296
	ds_read_b128 v[126:129], v131 offset:59904
	s_waitcnt lgkmcnt(1)
	v_mfma_f32_32x32x16_bf16 v[34:49], v[106:109], v[110:113], v[34:49]
	s_waitcnt lgkmcnt(0)
	v_mfma_f32_32x32x16_bf16 v[50:65], v[106:109], v[126:129], v[50:65]
	ds_read_b128 v[106:109], v132 offset:23040
	s_waitcnt lgkmcnt(0)
	v_mfma_f32_32x32x16_bf16 v[18:33], v[106:109], v[110:113], v[18:33]
	ds_read_b128 v[110:113], v132 offset:18464
	ds_read_b128 v[134:137], v131 offset:55328
	ds_read_b128 v[142:145], v131 offset:59936
	ds_read_b128 v[150:153], v132 offset:23072
	s_waitcnt vmcnt(15)
	ds_write_b128 v130, v[102:105]
	s_waitcnt vmcnt(14)
	ds_write_b128 v130, v[178:181] offset:36864
	v_mfma_f32_32x32x16_bf16 v[2:17], v[106:109], v[126:129], v[2:17]
	s_waitcnt lgkmcnt(4)
	v_mfma_f32_32x32x16_bf16 v[34:49], v[110:113], v[134:137], v[34:49]
	s_waitcnt lgkmcnt(3)
	v_mfma_f32_32x32x16_bf16 v[50:65], v[110:113], v[142:145], v[50:65]
	ds_read_b128 v[102:105], v132 offset:18496
	ds_read_b128 v[106:109], v132 offset:23104
	ds_read_b128 v[110:113], v131 offset:55360
	ds_read_b128 v[126:129], v131 offset:59968
	s_waitcnt vmcnt(13)
	ds_write_b128 v130, v[90:93] offset:4608
	s_waitcnt vmcnt(12)
	ds_write_b128 v130, v[94:97] offset:41472
	s_waitcnt lgkmcnt(8)
	v_mfma_f32_32x32x16_bf16 v[18:33], v[150:153], v[134:137], v[18:33]
	v_mfma_f32_32x32x16_bf16 v[2:17], v[150:153], v[142:145], v[2:17]
	s_waitcnt lgkmcnt(3)
	v_mfma_f32_32x32x16_bf16 v[34:49], v[102:105], v[110:113], v[34:49]
	s_waitcnt lgkmcnt(2)
	v_mfma_f32_32x32x16_bf16 v[50:65], v[102:105], v[126:129], v[50:65]
	v_mfma_f32_32x32x16_bf16 v[18:33], v[106:109], v[110:113], v[18:33]
	ds_read_b128 v[90:93], v132 offset:18528
	ds_read_b128 v[94:97], v132 offset:23136
	ds_read_b128 v[102:105], v131 offset:55392
	ds_read_b128 v[110:113], v131 offset:60000
	s_waitcnt vmcnt(11)
	ds_write_b128 v130, v[82:85] offset:9216
	s_waitcnt vmcnt(10)
	ds_write_b128 v130, v[86:89] offset:46080
	v_mfma_f32_32x32x16_bf16 v[2:17], v[106:109], v[126:129], v[2:17]
	s_waitcnt lgkmcnt(3)
	v_mfma_f32_32x32x16_bf16 v[34:49], v[90:93], v[102:105], v[34:49]
	s_waitcnt vmcnt(9)
	ds_write_b128 v130, v[74:77] offset:13824
	s_waitcnt vmcnt(8)
	ds_write_b128 v130, v[78:81] offset:50688
	s_waitcnt lgkmcnt(4)
	v_mfma_f32_32x32x16_bf16 v[50:65], v[90:93], v[110:113], v[50:65]
	v_mfma_f32_32x32x16_bf16 v[18:33], v[94:97], v[102:105], v[18:33]
	v_mfma_f32_32x32x16_bf16 v[2:17], v[94:97], v[110:113], v[2:17]
	s_waitcnt lgkmcnt(0)
	s_barrier
	ds_read_b128 v[74:77], v132
	ds_read_b128 v[78:81], v131 offset:36864
	ds_read_b128 v[82:85], v131 offset:41472
	s_waitcnt lgkmcnt(1)
	v_mfma_f32_32x32x16_bf16 v[34:49], v[74:77], v[78:81], v[34:49]
	s_waitcnt lgkmcnt(0)
	v_mfma_f32_32x32x16_bf16 v[50:65], v[74:77], v[82:85], v[50:65]
	ds_read_b128 v[74:77], v132 offset:4608
	s_waitcnt lgkmcnt(0)
	v_mfma_f32_32x32x16_bf16 v[18:33], v[74:77], v[78:81], v[18:33]
	ds_read_b128 v[78:81], v132 offset:32
	ds_read_b128 v[86:89], v131 offset:36896
	ds_read_b128 v[90:93], v131 offset:41504
	ds_read_b128 v[94:97], v132 offset:4640
	s_waitcnt vmcnt(7)
	ds_write_b128 v130, v[70:73] offset:18432
	s_waitcnt vmcnt(6)
	ds_write_b128 v130, v[146:149] offset:55296
	v_mfma_f32_32x32x16_bf16 v[2:17], v[74:77], v[82:85], v[2:17]
	s_waitcnt lgkmcnt(4)
	v_mfma_f32_32x32x16_bf16 v[34:49], v[78:81], v[86:89], v[34:49]
	s_waitcnt lgkmcnt(3)
	v_mfma_f32_32x32x16_bf16 v[50:65], v[78:81], v[90:93], v[50:65]
	ds_read_b128 v[70:73], v132 offset:64
	ds_read_b128 v[74:77], v132 offset:4672
	ds_read_b128 v[78:81], v131 offset:36928
	ds_read_b128 v[82:85], v131 offset:41536
	s_waitcnt vmcnt(5)
	ds_write_b128 v130, v[66:69] offset:23040
	s_waitcnt vmcnt(4)
	ds_write_b128 v130, v[98:101] offset:59904
	s_waitcnt lgkmcnt(8)
	v_mfma_f32_32x32x16_bf16 v[18:33], v[94:97], v[86:89], v[18:33]
	v_mfma_f32_32x32x16_bf16 v[2:17], v[94:97], v[90:93], v[2:17]
	s_waitcnt lgkmcnt(3)
	v_mfma_f32_32x32x16_bf16 v[34:49], v[70:73], v[78:81], v[34:49]
	s_waitcnt lgkmcnt(2)
	v_mfma_f32_32x32x16_bf16 v[50:65], v[70:73], v[82:85], v[50:65]
	v_mfma_f32_32x32x16_bf16 v[18:33], v[74:77], v[78:81], v[18:33]
	ds_read_b128 v[66:69], v132 offset:96
	ds_read_b128 v[70:73], v132 offset:4704
	ds_read_b128 v[78:81], v131 offset:36960
	ds_read_b128 v[86:89], v131 offset:41568
	s_waitcnt vmcnt(3)
	ds_write_b128 v130, v[122:125] offset:27648
	s_waitcnt vmcnt(2)
	ds_write_b128 v130, v[138:141] offset:64512
	v_mfma_f32_32x32x16_bf16 v[2:17], v[74:77], v[82:85], v[2:17]
	s_waitcnt lgkmcnt(3)
	v_mfma_f32_32x32x16_bf16 v[34:49], v[66:69], v[78:81], v[34:49]
	s_waitcnt vmcnt(1)
	ds_write_b128 v130, v[114:117] offset:32256
	s_waitcnt vmcnt(0)
	ds_write_b128 v0, v[118:121] offset:32256
	s_waitcnt lgkmcnt(4)
	v_mfma_f32_32x32x16_bf16 v[50:65], v[66:69], v[86:89], v[50:65]
	v_mfma_f32_32x32x16_bf16 v[18:33], v[70:73], v[78:81], v[18:33]
	v_mfma_f32_32x32x16_bf16 v[2:17], v[70:73], v[86:89], v[2:17]
	s_waitcnt lgkmcnt(0)
	s_barrier
; DI u16 f2bf(float x) { return (u16)(pack2(x, 0.f) & 0xffffu); }
; DI int opaque_tid() { int t = threadIdx.x; asm volatile("" : "+v"(t)); return t; }
; DI int crow(int i, int h) { return (i & 3) + 8 * (i >> 2) + 4 * h; }
; template <class AL, class BL>
; DI void gemm_core(AL al, BL bl, int m0, int n0, int K, char* smem, f32x16 (&acc)[2][2]) {
;     ...
;   for (int kt = 0; kt < nk; kt += 2) {
;     G_TILE(0, x, true, (kt + 3 < nk), kt + 3);
;     __syncthreads();
;     G_TILE(1, y, (kt + 2 < nk), (kt + 4 < nk), kt + 4);
;     __syncthreads();
;   }
; __global__ void __launch_bounds__(256, 2) fwd_megakernel(Params p) {
;     ...
;           const int tid = opaque_tid(), lane = tid & 63, wv = tid >> 6;
;           const int wm = wv >> 1, wn = wv & 1, h = lane >> 5, r = lane & 31;
;           const int nw0 = n0 + wn * 64;
;           const bool is_rope = (nw0 % 192) == 128;
;           if (is_rope) {
; #pragma unroll
;             for (int mt = 0; mt < 2; mt++)
; #pragma unroll
;               for (int i = 0; i < 16; i++) {
;                 const int m = m0 + wm * 64 + mt * 32 + crow(i, h);
;                 const float v0 = acc[mt][0][i], v1 = acc[mt][1][i];
;                 const int pos = tok_pos(m);
;                 const float c = ct[pos * 32 + r], s = st[pos * 32 + r];
;                 Q[(long)m * 1536 + nw0 + r] = f2bf((v0 * c - v1 * s) * QSCALE);
;                 Q[(long)m * 1536 + nw0 + 32 + r] = f2bf((v1 * c + v0 * s) * QSCALE);
;               }
;           } else {
; #pragma unroll
;             for (int mt = 0; mt < 2; mt++)
; #pragma unroll
;               for (int i = 0; i < 16; i++) {
;                 const int m = m0 + wm * 64 + mt * 32 + crow(i, h);
;                 Q[(long)m * 1536 + nw0 + r] = f2bf(acc[mt][0][i] * QSCALE);
;                 Q[(long)m * 1536 + nw0 + 32 + r] = f2bf(acc[mt][1][i] * QSCALE);
;               }
	ds_read_b128 v[66:69], v132 offset:18432
	ds_read_b128 v[70:73], v131 offset:55296
	ds_read_b128 v[74:77], v131 offset:59904
	s_waitcnt lgkmcnt(1)
	v_mfma_f32_32x32x16_bf16 v[34:49], v[66:69], v[70:73], v[34:49]
	s_waitcnt lgkmcnt(0)
	v_mfma_f32_32x32x16_bf16 v[50:65], v[66:69], v[74:77], v[50:65]
	ds_read_b128 v[66:69], v132 offset:23040
	s_waitcnt lgkmcnt(0)
	v_mfma_f32_32x32x16_bf16 v[18:33], v[66:69], v[70:73], v[18:33]
	ds_read_b128 v[70:73], v132 offset:18464
	ds_read_b128 v[78:81], v131 offset:55328
	ds_read_b128 v[82:85], v131 offset:59936
	ds_read_b128 v[86:89], v132 offset:23072
	v_mfma_f32_32x32x16_bf16 v[2:17], v[66:69], v[74:77], v[2:17]
	s_waitcnt lgkmcnt(2)
	v_mfma_f32_32x32x16_bf16 v[34:49], v[70:73], v[78:81], v[34:49]
	s_waitcnt lgkmcnt(1)
	v_mfma_f32_32x32x16_bf16 v[50:65], v[70:73], v[82:85], v[50:65]
	s_waitcnt lgkmcnt(0)
	v_mfma_f32_32x32x16_bf16 v[18:33], v[86:89], v[78:81], v[18:33]
	ds_read_b128 v[66:69], v132 offset:18496
	ds_read_b128 v[70:73], v132 offset:23104
	ds_read_b128 v[74:77], v131 offset:55360
	ds_read_b128 v[78:81], v131 offset:59968
	v_mfma_f32_32x32x16_bf16 v[2:17], v[86:89], v[82:85], v[2:17]
	s_waitcnt lgkmcnt(1)
	v_mfma_f32_32x32x16_bf16 v[34:49], v[66:69], v[74:77], v[34:49]
	s_waitcnt lgkmcnt(0)
	v_mfma_f32_32x32x16_bf16 v[50:65], v[66:69], v[78:81], v[50:65]
	v_mfma_f32_32x32x16_bf16 v[18:33], v[70:73], v[74:77], v[18:33]
	ds_read_b128 v[66:69], v132 offset:18528
	ds_read_b128 v[74:77], v132 offset:23136
	ds_read_b128 v[82:85], v131 offset:55392
	ds_read_b128 v[86:89], v131 offset:60000
	v_mfma_f32_32x32x16_bf16 v[2:17], v[70:73], v[78:81], v[2:17]
	s_waitcnt lgkmcnt(1)
	v_mfma_f32_32x32x16_bf16 v[34:49], v[66:69], v[82:85], v[34:49]
	s_waitcnt lgkmcnt(0)
	v_mfma_f32_32x32x16_bf16 v[50:65], v[66:69], v[86:89], v[50:65]
	v_mfma_f32_32x32x16_bf16 v[18:33], v[74:77], v[82:85], v[18:33]
	v_mfma_f32_32x32x16_bf16 v[2:17], v[74:77], v[86:89], v[2:17]
	v_mov_b32_e32 v0, v202
	s_barrier
	s_nop 0
	v_and_or_b32 v66, v0, 64, s1
	s_mov_b32 s1, 0x2aaaaaab
	v_mul_hi_i32 v67, v66, s1
	v_lshrrev_b32_e32 v68, 31, v67
	v_lshrrev_b32_e32 v67, 5, v67
	v_add_u32_e32 v67, v67, v68
	s_movk_i32 s1, 0xc0
	v_mul_lo_u32 v67, v67, s1
	v_sub_u32_e32 v67, v66, v67
	v_and_b32_e32 v69, 31, v0
	v_cmp_ne_u32_e32 vcc, s16, v67
	v_ashrrev_i32_e32 v67, 1, v0
	v_lshrrev_b32_e32 v0, 3, v0
	v_and_b32_e32 v100, 4, v0
	s_movk_i32 s1, 0xffc0
	v_and_or_b32 v0, v67, s1, v100
	v_subrev_u32_e32 v0, s0, v0
	v_ashrrev_i32_e32 v67, 31, v66
	v_add_u32_e32 v101, s72, v0
	v_lshl_add_u64 v[66:67], v[66:67], 1, s[38:39]
	v_lshlrev_b32_e32 v0, 1, v69
	v_add_u32_e32 v99, 0xffffffa0, v101
	v_lshl_add_u64 v[66:67], v[66:67], 0, v[0:1]
	v_add_u32_e32 v98, 0xffffffa1, v101
	v_add_u32_e32 v97, 0xffffffa2, v101
	v_add_u32_e32 v96, 0xffffffa3, v101
	v_add_u32_e32 v95, 0xffffffa8, v101
	v_add_u32_e32 v94, 0xffffffa9, v101
	v_add_u32_e32 v93, 0xffffffaa, v101
	v_add_u32_e32 v92, 0xffffffab, v101
	v_add_u32_e32 v91, 0xffffffb0, v101
	v_add_u32_e32 v90, 0xffffffb1, v101
	v_add_u32_e32 v89, 0xffffffb2, v101
	v_add_u32_e32 v88, 0xffffffb3, v101
	v_add_u32_e32 v87, 0xffffffb8, v101
	v_add_u32_e32 v86, 0xffffffb9, v101
	v_add_u32_e32 v85, 0xffffffba, v101
	v_add_u32_e32 v84, 0xffffffbb, v101
	v_subrev_u32_e32 v83, 64, v101
	v_subrev_u32_e32 v79, 56, v101
	v_subrev_u32_e32 v75, 48, v101
	v_subrev_u32_e32 v71, 40, v101
	v_subrev_u32_e32 v82, 63, v101
	v_subrev_u32_e32 v81, 62, v101
	v_subrev_u32_e32 v80, 61, v101
	v_subrev_u32_e32 v78, 55, v101
	v_subrev_u32_e32 v77, 54, v101
	v_subrev_u32_e32 v76, 53, v101
	v_subrev_u32_e32 v74, 47, v101
	v_subrev_u32_e32 v73, 46, v101
	v_subrev_u32_e32 v72, 45, v101
	v_subrev_u32_e32 v70, 39, v101
	v_subrev_u32_e32 v68, 38, v101
	v_subrev_u32_e32 v0, 37, v101
	s_and_saveexec_b64 s[0:1], vcc
	s_xor_b64 s[0:1], exec, s[0:1]
	s_cbranch_execz .LBB0_567
	v_mul_f32_e32 v34, 0x3dd53b94, v34
	v_cvt_pk_bf16_f32 v34, v34, s0
	v_mad_i64_i32 v[100:101], s[30:31], v99, s85, v[66:67]
	global_store_short v[100:101], v34, off
	v_mul_f32_e32 v34, 0x3dd53b94, v50
	v_cvt_pk_bf16_f32 v34, v34, s0
	global_store_short v[100:101], v34, off offset:64
	v_mul_f32_e32 v34, 0x3dd53b94, v35
	v_cvt_pk_bf16_f32 v50, v34, s0
	v_mad_i64_i32 v[34:35], s[30:31], v98, s85, v[66:67]
	global_store_short v[34:35], v50, off
	v_mul_f32_e32 v50, 0x3dd53b94, v51
	v_cvt_pk_bf16_f32 v50, v50, s0
	global_store_short v[34:35], v50, off offset:64
	v_mul_f32_e32 v34, 0x3dd53b94, v36
	v_cvt_pk_bf16_f32 v36, v34, s0
	v_mad_i64_i32 v[34:35], s[30:31], v97, s85, v[66:67]
	global_store_short v[34:35], v36, off
	v_mul_f32_e32 v36, 0x3dd53b94, v52
	v_cvt_pk_bf16_f32 v36, v36, s0
	global_store_short v[34:35], v36, off offset:64
	v_mul_f32_e32 v34, 0x3dd53b94, v37
	v_cvt_pk_bf16_f32 v36, v34, s0
	v_mad_i64_i32 v[34:35], s[30:31], v96, s85, v[66:67]
	global_store_short v[34:35], v36, off
	v_mul_f32_e32 v36, 0x3dd53b94, v53
	v_cvt_pk_bf16_f32 v36, v36, s0
	global_store_short v[34:35], v36, off offset:64
	v_mul_f32_e32 v34, 0x3dd53b94, v38
	v_cvt_pk_bf16_f32 v36, v34, s0
	v_mad_i64_i32 v[34:35], s[30:31], v95, s85, v[66:67]
	global_store_short v[34:35], v36, off
	v_mul_f32_e32 v36, 0x3dd53b94, v54
	v_cvt_pk_bf16_f32 v36, v36, s0
	global_store_short v[34:35], v36, off offset:64
	v_mul_f32_e32 v34, 0x3dd53b94, v39
	v_cvt_pk_bf16_f32 v36, v34, s0
	v_mad_i64_i32 v[34:35], s[30:31], v94, s85, v[66:67]
	global_store_short v[34:35], v36, off
	v_mul_f32_e32 v36, 0x3dd53b94, v55
	v_cvt_pk_bf16_f32 v36, v36, s0
	global_store_short v[34:35], v36, off offset:64
	v_mul_f32_e32 v34, 0x3dd53b94, v40
	v_cvt_pk_bf16_f32 v36, v34, s0
	v_mad_i64_i32 v[34:35], s[30:31], v93, s85, v[66:67]
; DI u16 f2bf(float x) { return (u16)(pack2(x, 0.f) & 0xffffu); }
; DI int crow(int i, int h) { return (i & 3) + 8 * (i >> 2) + 4 * h; }
; __global__ void __launch_bounds__(256, 2) fwd_megakernel(Params p) {
;     ...
;           } else {
; #pragma unroll
;             for (int mt = 0; mt < 2; mt++)
; #pragma unroll
;               for (int i = 0; i < 16; i++) {
;                 const int m = m0 + wm * 64 + mt * 32 + crow(i, h);
;                 Q[(long)m * 1536 + nw0 + r] = f2bf(acc[mt][0][i] * QSCALE);
;                 Q[(long)m * 1536 + nw0 + 32 + r] = f2bf(acc[mt][1][i] * QSCALE);
;               }
	global_store_short v[34:35], v36, off
	v_mul_f32_e32 v36, 0x3dd53b94, v56
	v_cvt_pk_bf16_f32 v36, v36, s0
	global_store_short v[34:35], v36, off offset:64
	v_mul_f32_e32 v34, 0x3dd53b94, v41
	v_cvt_pk_bf16_f32 v36, v34, s0
	v_mad_i64_i32 v[34:35], s[30:31], v92, s85, v[66:67]
	global_store_short v[34:35], v36, off
	v_mul_f32_e32 v36, 0x3dd53b94, v57
	v_cvt_pk_bf16_f32 v36, v36, s0
	global_store_short v[34:35], v36, off offset:64
	v_mul_f32_e32 v34, 0x3dd53b94, v42
	v_cvt_pk_bf16_f32 v36, v34, s0
	v_mad_i64_i32 v[34:35], s[30:31], v91, s85, v[66:67]
	global_store_short v[34:35], v36, off
	v_mul_f32_e32 v36, 0x3dd53b94, v58
	v_cvt_pk_bf16_f32 v36, v36, s0
	global_store_short v[34:35], v36, off offset:64
	v_mul_f32_e32 v34, 0x3dd53b94, v43
	v_cvt_pk_bf16_f32 v36, v34, s0
	v_mad_i64_i32 v[34:35], s[30:31], v90, s85, v[66:67]
	global_store_short v[34:35], v36, off
	v_mul_f32_e32 v36, 0x3dd53b94, v59
	v_cvt_pk_bf16_f32 v36, v36, s0
	global_store_short v[34:35], v36, off offset:64
	v_mul_f32_e32 v34, 0x3dd53b94, v44
	v_cvt_pk_bf16_f32 v36, v34, s0
	v_mad_i64_i32 v[34:35], s[30:31], v89, s85, v[66:67]
	global_store_short v[34:35], v36, off
	v_mul_f32_e32 v36, 0x3dd53b94, v60
	v_cvt_pk_bf16_f32 v36, v36, s0
	global_store_short v[34:35], v36, off offset:64
	v_mul_f32_e32 v34, 0x3dd53b94, v45
	v_cvt_pk_bf16_f32 v36, v34, s0
	v_mad_i64_i32 v[34:35], s[30:31], v88, s85, v[66:67]
	global_store_short v[34:35], v36, off
	v_mul_f32_e32 v36, 0x3dd53b94, v61
	v_cvt_pk_bf16_f32 v36, v36, s0
	global_store_short v[34:35], v36, off offset:64
	v_mul_f32_e32 v34, 0x3dd53b94, v46
	v_cvt_pk_bf16_f32 v36, v34, s0
	v_mad_i64_i32 v[34:35], s[30:31], v87, s85, v[66:67]
	global_store_short v[34:35], v36, off
	v_mul_f32_e32 v36, 0x3dd53b94, v62
	v_cvt_pk_bf16_f32 v36, v36, s0
	global_store_short v[34:35], v36, off offset:64
	v_mul_f32_e32 v34, 0x3dd53b94, v47
	v_cvt_pk_bf16_f32 v36, v34, s0
	v_mad_i64_i32 v[34:35], s[30:31], v86, s85, v[66:67]
	global_store_short v[34:35], v36, off
	v_mul_f32_e32 v36, 0x3dd53b94, v63
	v_cvt_pk_bf16_f32 v36, v36, s0
	global_store_short v[34:35], v36, off offset:64
	v_mul_f32_e32 v34, 0x3dd53b94, v48
	v_cvt_pk_bf16_f32 v36, v34, s0
	v_mad_i64_i32 v[34:35], s[30:31], v85, s85, v[66:67]
	global_store_short v[34:35], v36, off
	v_mul_f32_e32 v36, 0x3dd53b94, v64
	v_cvt_pk_bf16_f32 v36, v36, s0
	global_store_short v[34:35], v36, off offset:64
	v_mul_f32_e32 v34, 0x3dd53b94, v49
	v_cvt_pk_bf16_f32 v36, v34, s0
	v_mad_i64_i32 v[34:35], s[30:31], v84, s85, v[66:67]
	global_store_short v[34:35], v36, off
	v_mul_f32_e32 v36, 0x3dd53b94, v65
	v_cvt_pk_bf16_f32 v36, v36, s0
	v_mul_f32_e32 v2, 0x3dd53b94, v2
	global_store_short v[34:35], v36, off offset:64
	v_mul_f32_e32 v18, 0x3dd53b94, v18
	v_mad_i64_i32 v[34:35], s[30:31], v83, s85, v[66:67]
	v_cvt_pk_bf16_f32 v2, v2, s0
	v_cvt_pk_bf16_f32 v18, v18, s0
	global_store_short v[34:35], v2, off offset:64
	v_mul_f32_e32 v2, 0x3dd53b94, v19
	global_store_short v[34:35], v18, off
	v_cvt_pk_bf16_f32 v2, v2, s0
	v_mad_i64_i32 v[18:19], s[30:31], v82, s85, v[66:67]
	global_store_short v[18:19], v2, off
	v_mul_f32_e32 v2, 0x3dd53b94, v3
	v_cvt_pk_bf16_f32 v2, v2, s0
	global_store_short v[18:19], v2, off offset:64
	v_mul_f32_e32 v2, 0x3dd53b94, v20
	v_mul_f32_e32 v4, 0x3dd53b94, v4
	v_cvt_pk_bf16_f32 v18, v2, s0
	v_mad_i64_i32 v[2:3], s[30:31], v81, s85, v[66:67]
	v_cvt_pk_bf16_f32 v4, v4, s0
	global_store_short v[2:3], v18, off
	global_store_short v[2:3], v4, off offset:64
	v_mul_f32_e32 v2, 0x3dd53b94, v21
	v_cvt_pk_bf16_f32 v4, v2, s0
	v_mad_i64_i32 v[2:3], s[30:31], v80, s85, v[66:67]
	global_store_short v[2:3], v4, off
	v_mul_f32_e32 v4, 0x3dd53b94, v5
	v_cvt_pk_bf16_f32 v4, v4, s0
	global_store_short v[2:3], v4, off offset:64
	v_mul_f32_e32 v2, 0x3dd53b94, v22
	v_cvt_pk_bf16_f32 v4, v2, s0
	v_mad_i64_i32 v[2:3], s[30:31], v79, s85, v[66:67]
	global_store_short v[2:3], v4, off
	v_mul_f32_e32 v4, 0x3dd53b94, v6
	v_cvt_pk_bf16_f32 v4, v4, s0
	global_store_short v[2:3], v4, off offset:64
	v_mul_f32_e32 v2, 0x3dd53b94, v23
	v_cvt_pk_bf16_f32 v4, v2, s0
	v_mad_i64_i32 v[2:3], s[30:31], v78, s85, v[66:67]
	global_store_short v[2:3], v4, off
	v_mul_f32_e32 v4, 0x3dd53b94, v7
	v_cvt_pk_bf16_f32 v4, v4, s0
	global_store_short v[2:3], v4, off offset:64
	v_mul_f32_e32 v2, 0x3dd53b94, v24
	v_cvt_pk_bf16_f32 v4, v2, s0
	v_mad_i64_i32 v[2:3], s[30:31], v77, s85, v[66:67]
	global_store_short v[2:3], v4, off
	v_mul_f32_e32 v4, 0x3dd53b94, v8
	v_cvt_pk_bf16_f32 v4, v4, s0
	global_store_short v[2:3], v4, off offset:64
	v_mul_f32_e32 v2, 0x3dd53b94, v25
	v_cvt_pk_bf16_f32 v4, v2, s0
	v_mad_i64_i32 v[2:3], s[30:31], v76, s85, v[66:67]
	global_store_short v[2:3], v4, off
	v_mul_f32_e32 v4, 0x3dd53b94, v9
	v_cvt_pk_bf16_f32 v4, v4, s0
	global_store_short v[2:3], v4, off offset:64
	v_mul_f32_e32 v2, 0x3dd53b94, v26
	v_cvt_pk_bf16_f32 v4, v2, s0
	v_mad_i64_i32 v[2:3], s[30:31], v75, s85, v[66:67]
	global_store_short v[2:3], v4, off
	v_mul_f32_e32 v4, 0x3dd53b94, v10
	v_cvt_pk_bf16_f32 v4, v4, s0
	global_store_short v[2:3], v4, off offset:64
	v_mul_f32_e32 v2, 0x3dd53b94, v27
	v_cvt_pk_bf16_f32 v4, v2, s0
	v_mad_i64_i32 v[2:3], s[30:31], v74, s85, v[66:67]
	global_store_short v[2:3], v4, off
	v_mul_f32_e32 v4, 0x3dd53b94, v11
	v_cvt_pk_bf16_f32 v4, v4, s0
	global_store_short v[2:3], v4, off offset:64
	v_mul_f32_e32 v2, 0x3dd53b94, v28
	v_cvt_pk_bf16_f32 v4, v2, s0
	v_mad_i64_i32 v[2:3], s[30:31], v73, s85, v[66:67]
	global_store_short v[2:3], v4, off
	v_mul_f32_e32 v4, 0x3dd53b94, v12
	v_cvt_pk_bf16_f32 v4, v4, s0
	global_store_short v[2:3], v4, off offset:64
	v_mul_f32_e32 v2, 0x3dd53b94, v29
	v_cvt_pk_bf16_f32 v4, v2, s0
	v_mad_i64_i32 v[2:3], s[30:31], v72, s85, v[66:67]
	global_store_short v[2:3], v4, off
	v_mul_f32_e32 v4, 0x3dd53b94, v13
	v_cvt_pk_bf16_f32 v4, v4, s0
	global_store_short v[2:3], v4, off offset:64
	v_mul_f32_e32 v2, 0x3dd53b94, v30
	v_cvt_pk_bf16_f32 v4, v2, s0
	v_mad_i64_i32 v[2:3], s[30:31], v71, s85, v[66:67]
	global_store_short v[2:3], v4, off
	v_mul_f32_e32 v4, 0x3dd53b94, v14
	v_cvt_pk_bf16_f32 v4, v4, s0
	global_store_short v[2:3], v4, off offset:64
	v_mul_f32_e32 v2, 0x3dd53b94, v31
	v_cvt_pk_bf16_f32 v4, v2, s0
	v_mad_i64_i32 v[2:3], s[30:31], v70, s85, v[66:67]
	global_store_short v[2:3], v4, off
	v_mul_f32_e32 v4, 0x3dd53b94, v15
	v_cvt_pk_bf16_f32 v4, v4, s0
	global_store_short v[2:3], v4, off offset:64
	v_mul_f32_e32 v2, 0x3dd53b94, v32
	v_cvt_pk_bf16_f32 v4, v2, s0
	v_mad_i64_i32 v[2:3], s[30:31], v68, s85, v[66:67]
	global_store_short v[2:3], v4, off
	v_mul_f32_e32 v4, 0x3dd53b94, v16
	v_cvt_pk_bf16_f32 v4, v4, s0
	global_store_short v[2:3], v4, off offset:64
	v_mul_f32_e32 v2, 0x3dd53b94, v33
	v_cvt_pk_bf16_f32 v4, v2, s0
	v_mad_i64_i32 v[2:3], s[30:31], v0, s85, v[66:67]
	v_mul_f32_e32 v0, 0x3dd53b94, v17
	v_cvt_pk_bf16_f32 v0, v0, s0
	global_store_short v[2:3], v4, off
	global_store_short v[2:3], v0, off offset:64
